# v23 plus all GEMM K-loops: duplicated no-op lgkmcnt(0) after s_setprio 1 at the head of each MFMA block removed (47 sites)
# speedup vs baseline: 1.0151x; 1.0057x over previous
; #define PG8_STAGE(bufoff, gbase, voff) do { _Pragma("unroll") for (int _i = 0; _i < 2; ++_i) \
;         __builtin_amdgcn_global_load_lds((const unsigned*)((const char*)(gbase) + (voff)[_i]), (LAS unsigned*)(lds + (bufoff) + ldsw + _i * 8192), 16, 0, 0); } while (0)
; #define STG_A(bufoff, kb, h, usen) do { if constexpr (GATHER) { unsigned o_[2] = {(usen) ? noff[h][0] : coff[h][0], (usen) ? noff[h][1] : coff[h][1]}; PG8_STAGE(bufoff, (const char*)A + (kb), o_); } \
;         else { PG8_STAGE(bufoff, ((usen) ? nA : cA) + (kb) + (size_t)(h) * hstep, voffA); } } while (0)
; #define PG8_LDA(dst, b, h) do { _Pragma("unroll") for (int m = 0; m < 4; ++m) _Pragma("unroll") for (int k = 0; k < 2; ++k) dst[m][k] = *(const LAS bf16x8*)(lds + PG8_SA(b, h) + aoff + m * 2048 + k * 1024); } while (0)
; #define PG8_LDB(dst, b, h) do { _Pragma("unroll") for (int n = 0; n < 2; ++n) _Pragma("unroll") for (int k = 0; k < 2; ++k) dst[n][k] = *(const LAS bf16x8*)(lds + PG8_SB(b, h) + boff + n * 2048 + k * 1024); } while (0)
; #define PG8_MMA(ai, bj, At, Bt_) do { __builtin_amdgcn_s_setprio(1); _Pragma("unroll") for (int m = 0; m < 4; ++m) _Pragma("unroll") for (int n = 0; n < 2; ++n) _Pragma("unroll") for (int k = 0; k < 2; ++k) \
;         acc[ai][bj][m][n] = __builtin_amdgcn_mfma_f32_16x16x32_bf16(Bt_[n][k], At[m][k], acc[ai][bj][m][n], 0, 0, 0); __builtin_amdgcn_s_setprio(0); } while (0)
; #define PG8_WAIT_L(n) asm volatile("s_waitcnt lgkmcnt(" #n ")" ::: "memory")
; #define PG8_BAR __builtin_amdgcn_s_barrier()
; #define PG8_SCHED __builtin_amdgcn_sched_barrier(0)
; template <class Epi, bool GATHER = false>
; __device__ __forceinline__ void gemm_phase(LAS unsigned char* lds, const bf16_t* A, const bf16_t* Bt, const int K_, const Sched& S, const Epi& E, const int* gidx = nullptr) {
;     ...
;             PG8_LDB(B0, 0, 0); PG8_SCHED; PG8_LDA(At, 0, 0); STG_A(PG8_SA(1, 1), k1, 1, false);
;             PG8_WAIT_L(8); PG8_BAR; PG8_WAIT_L(0); PG8_MMA(0, 0, At, B0); PG8_BAR; PG8_SCHED;
;             PG8_LDB(B1, 0, 1); PG8_STAGE(PG8_SB(0, 0), b2, voffA);
;             PG8_BAR; PG8_WAIT_L(0); PG8_MMA(0, 1, At, B1); PG8_BAR;
;             PG8_LDA(At, 0, 1); STG_A(PG8_SA(0, 0), k2, 0, last);
;             PG8_BAR; PG8_WAIT_L(0); PG8_MMA(1, 0, At, B0); PG8_BAR; PG8_SCHED;
.LBB0_255:
	s_add_i32 s65, s40, 2
	s_add_u32 s38, s6, 0x100
	ds_read_b128 v[6:9], v205
	ds_read_b128 v[10:13], v205 offset:1024
	ds_read_b128 v[112:115], v205 offset:2048
	ds_read_b128 v[116:119], v205 offset:3072
	s_addc_u32 s39, s7, 0
	s_add_u32 s66, s63, s6
	s_addc_u32 s41, s64, s7
	s_add_i32 s69, s54, s42
	s_add_i32 m0, s43, 0xc000
	s_add_i32 s67, s43, 0xe000
	s_add_i32 s70, s69, 0x2000
	s_cmp_eq_u32 s52, s40
	s_cselect_b32 s40, s0, s66
	s_cselect_b32 s41, s1, s41
	s_cselect_b32 s66, 0, s39
	s_cselect_b32 s71, 0, s38
	v_lshl_add_u64 v[14:15], v[2:3], 0, s[6:7]
	ds_read_b128 v[120:123], v206
	ds_read_b128 v[158:161], v206 offset:1024
	ds_read_b128 v[162:165], v206 offset:2048
	ds_read_b128 v[166:169], v206 offset:3072
	ds_read_b128 v[170:173], v206 offset:4096
	ds_read_b128 v[194:197], v206 offset:5120
	ds_read_b128 v[198:201], v206 offset:6144
	ds_read_b128 v[212:215], v206 offset:7168
	global_load_lds_dwordx4 v[14:15], off
	v_lshl_add_u64 v[14:15], v[4:5], 0, s[6:7]
	s_mov_b32 m0, s67
	s_nop 0
	global_load_lds_dwordx4 v[14:15], off
	s_waitcnt lgkmcnt(8)
	s_barrier
	s_waitcnt lgkmcnt(0)
	s_setprio 1
	v_mfma_f32_16x16x32_bf16 v[44:47], v[6:9], v[120:123], v[44:47]
	v_mfma_f32_16x16x32_bf16 v[40:43], v[112:115], v[120:123], v[40:43]
	v_mfma_f32_16x16x32_bf16 v[28:31], v[6:9], v[162:165], v[28:31]
	v_mfma_f32_16x16x32_bf16 v[24:27], v[112:115], v[162:165], v[24:27]
	v_mfma_f32_16x16x32_bf16 v[154:157], v[6:9], v[170:173], v[154:157]
	v_mfma_f32_16x16x32_bf16 v[150:153], v[112:115], v[170:173], v[150:153]
	v_mfma_f32_16x16x32_bf16 v[138:141], v[6:9], v[198:201], v[138:141]
	v_mfma_f32_16x16x32_bf16 v[134:137], v[112:115], v[198:201], v[134:137]
	v_mfma_f32_16x16x32_bf16 v[44:47], v[10:13], v[158:161], v[44:47]
	v_mfma_f32_16x16x32_bf16 v[40:43], v[116:119], v[158:161], v[40:43]
	v_mfma_f32_16x16x32_bf16 v[28:31], v[10:13], v[166:169], v[28:31]
	v_mfma_f32_16x16x32_bf16 v[24:27], v[116:119], v[166:169], v[24:27]
	v_mfma_f32_16x16x32_bf16 v[154:157], v[10:13], v[194:197], v[154:157]
	v_mfma_f32_16x16x32_bf16 v[150:153], v[116:119], v[194:197], v[150:153]
	v_mfma_f32_16x16x32_bf16 v[138:141], v[10:13], v[212:215], v[138:141]
	v_mfma_f32_16x16x32_bf16 v[134:137], v[116:119], v[212:215], v[134:137]
	s_setprio 0
	s_barrier
	s_mov_b32 m0, s69
	v_lshl_add_u64 v[202:203], s[40:41], 0, v[174:175]
	ds_read_b128 v[216:219], v207
	ds_read_b128 v[220:223], v207 offset:1024
	ds_read_b128 v[224:227], v207 offset:2048
	ds_read_b128 v[228:231], v207 offset:3072
	global_load_lds_dwordx4 v[202:203], off
	v_lshl_add_u64 v[232:233], s[40:41], 0, v[176:177]
	s_mov_b32 m0, s70
	s_nop 0
	global_load_lds_dwordx4 v[232:233], off
	s_barrier
	s_waitcnt lgkmcnt(0)
	s_setprio 1
	v_mfma_f32_16x16x32_bf16 v[36:39], v[216:219], v[120:123], v[36:39]
	v_mfma_f32_16x16x32_bf16 v[32:35], v[224:227], v[120:123], v[32:35]
	v_mfma_f32_16x16x32_bf16 v[20:23], v[216:219], v[162:165], v[20:23]
	v_mfma_f32_16x16x32_bf16 v[14:17], v[224:227], v[162:165], v[16:19]
	v_mfma_f32_16x16x32_bf16 v[142:145], v[224:227], v[170:173], v[142:145]
	v_mfma_f32_16x16x32_bf16 v[130:133], v[216:219], v[198:201], v[130:133]
	v_mfma_f32_16x16x32_bf16 v[124:127], v[224:227], v[198:201], v[126:129]
	v_mfma_f32_16x16x32_bf16 v[36:39], v[220:223], v[158:161], v[36:39]
	v_mfma_f32_16x16x32_bf16 v[32:35], v[228:231], v[158:161], v[32:35]
	v_mfma_f32_16x16x32_bf16 v[20:23], v[220:223], v[166:169], v[20:23]
	v_mfma_f32_16x16x32_bf16 v[14:17], v[228:231], v[166:169], v[14:17]
	v_mfma_f32_16x16x32_bf16 v[120:123], v[216:219], v[170:173], v[146:149]
	v_mfma_f32_16x16x32_bf16 v[142:145], v[228:231], v[194:197], v[142:145]
	v_mfma_f32_16x16x32_bf16 v[130:133], v[220:223], v[212:215], v[130:133]
	v_mfma_f32_16x16x32_bf16 v[124:127], v[228:231], v[212:215], v[124:127]
	v_mfma_f32_16x16x32_bf16 v[120:123], v[220:223], v[194:197], v[120:123]
	s_setprio 0
	s_cselect_b32 s6, s36, s4
	s_cselect_b32 s7, s37, s5
	s_add_u32 s6, s6, s71
	s_addc_u32 s7, s7, s66
	s_mov_b32 m0, s43
	v_lshl_add_u64 v[234:235], s[6:7], 0, v[174:175]
	s_barrier
	ds_read_b128 v[146:149], v206 offset:16384
	ds_read_b128 v[158:161], v206 offset:17408
	ds_read_b128 v[162:165], v206 offset:18432
	ds_read_b128 v[166:169], v206 offset:19456
	ds_read_b128 v[170:173], v206 offset:20480
	ds_read_b128 v[194:197], v206 offset:21504
	ds_read_b128 v[198:201], v206 offset:22528
	ds_read_b128 v[212:215], v206 offset:23552
	global_load_lds_dwordx4 v[234:235], off
	v_lshl_add_u64 v[236:237], s[6:7], 0, v[176:177]
	s_mov_b32 m0, s44
	s_nop 0
	global_load_lds_dwordx4 v[236:237], off
	s_barrier
	s_waitcnt lgkmcnt(0)
	s_setprio 1
	v_mfma_f32_16x16x32_bf16 v[108:111], v[6:9], v[146:149], v[108:111]
	v_mfma_f32_16x16x32_bf16 v[104:107], v[112:115], v[146:149], v[104:107]
	v_mfma_f32_16x16x32_bf16 v[92:95], v[6:9], v[162:165], v[92:95]
	v_mfma_f32_16x16x32_bf16 v[88:91], v[112:115], v[162:165], v[88:91]
	v_mfma_f32_16x16x32_bf16 v[76:79], v[6:9], v[170:173], v[76:79]
	v_mfma_f32_16x16x32_bf16 v[72:75], v[112:115], v[170:173], v[72:75]
	v_mfma_f32_16x16x32_bf16 v[6:9], v[6:9], v[198:201], v[60:63]
	v_mfma_f32_16x16x32_bf16 v[108:111], v[10:13], v[158:161], v[108:111]
	v_mfma_f32_16x16x32_bf16 v[104:107], v[116:119], v[158:161], v[104:107]
	v_mfma_f32_16x16x32_bf16 v[92:95], v[10:13], v[166:169], v[92:95]
	v_mfma_f32_16x16x32_bf16 v[88:91], v[116:119], v[166:169], v[88:91]
	v_mfma_f32_16x16x32_bf16 v[76:79], v[10:13], v[194:197], v[76:79]
	v_mfma_f32_16x16x32_bf16 v[72:75], v[116:119], v[194:197], v[72:75]
	v_mfma_f32_16x16x32_bf16 v[6:9], v[10:13], v[212:215], v[6:9]
	v_mfma_f32_16x16x32_bf16 v[10:13], v[112:115], v[198:201], v[56:59]
	v_mfma_f32_16x16x32_bf16 v[10:13], v[116:119], v[212:215], v[10:13]
	s_setprio 0
	s_barrier
; #define PG8_STAGE(bufoff, gbase, voff) do { _Pragma("unroll") for (int _i = 0; _i < 2; ++_i) \
;         __builtin_amdgcn_global_load_lds((const unsigned*)((const char*)(gbase) + (voff)[_i]), (LAS unsigned*)(lds + (bufoff) + ldsw + _i * 8192), 16, 0, 0); } while (0)
; #define STG_A(bufoff, kb, h, usen) do { if constexpr (GATHER) { unsigned o_[2] = {(usen) ? noff[h][0] : coff[h][0], (usen) ? noff[h][1] : coff[h][1]}; PG8_STAGE(bufoff, (const char*)A + (kb), o_); } \
;         else { PG8_STAGE(bufoff, ((usen) ? nA : cA) + (kb) + (size_t)(h) * hstep, voffA); } } while (0)
; #define PG8_LDA(dst, b, h) do { _Pragma("unroll") for (int m = 0; m < 4; ++m) _Pragma("unroll") for (int k = 0; k < 2; ++k) dst[m][k] = *(const LAS bf16x8*)(lds + PG8_SA(b, h) + aoff + m * 2048 + k * 1024); } while (0)
; #define PG8_LDB(dst, b, h) do { _Pragma("unroll") for (int n = 0; n < 2; ++n) _Pragma("unroll") for (int k = 0; k < 2; ++k) dst[n][k] = *(const LAS bf16x8*)(lds + PG8_SB(b, h) + boff + n * 2048 + k * 1024); } while (0)
; #define PG8_MMA(ai, bj, At, Bt_) do { __builtin_amdgcn_s_setprio(1); _Pragma("unroll") for (int m = 0; m < 4; ++m) _Pragma("unroll") for (int n = 0; n < 2; ++n) _Pragma("unroll") for (int k = 0; k < 2; ++k) \
;         acc[ai][bj][m][n] = __builtin_amdgcn_mfma_f32_16x16x32_bf16(Bt_[n][k], At[m][k], acc[ai][bj][m][n], 0, 0, 0); __builtin_amdgcn_s_setprio(0); } while (0)
; #define PG8_WAIT_V(n) asm volatile("s_waitcnt vmcnt(" #n ")" ::: "memory")
; #define PG8_WAIT_L(n) asm volatile("s_waitcnt lgkmcnt(" #n ")" ::: "memory")
; #define PG8_BAR __builtin_amdgcn_s_barrier()
; #define PG8_SCHED __builtin_amdgcn_sched_barrier(0)
; template <class Epi, bool GATHER = false>
; __device__ __forceinline__ void gemm_phase(LAS unsigned char* lds, const bf16_t* A, const bf16_t* Bt, const int K_, const Sched& S, const Epi& E, const int* gidx = nullptr) {
;     ...
;             PG8_STAGE(PG8_SB(0, 1), b2 + hstep, voffA);
;             PG8_WAIT_V(6); PG8_BAR; PG8_MMA(1, 1, At, B1); PG8_BAR;
;             PG8_LDB(B0, 1, 0); PG8_SCHED; PG8_LDA(At, 1, 0); STG_A(PG8_SA(0, 1), k2, 1, last);
;             PG8_WAIT_L(8); PG8_BAR; PG8_WAIT_L(0); PG8_MMA(0, 0, At, B0); PG8_BAR; PG8_SCHED;
;             PG8_LDB(B1, 1, 1); PG8_STAGE(PG8_SB(1, 0), b3, voffA);
;             PG8_BAR; PG8_WAIT_L(0); PG8_MMA(0, 1, At, B1); PG8_BAR;
	s_add_u32 s40, s40, s10
	s_addc_u32 s41, s41, s11
	s_add_i32 s66, s55, s42
	v_lshl_add_u64 v[238:239], s[40:41], 0, v[174:175]
	s_mov_b32 m0, s66
	v_lshl_add_u64 v[240:241], s[40:41], 0, v[176:177]
	global_load_lds_dwordx4 v[238:239], off
	s_add_i32 m0, s66, 0x2000
	s_nop 0
	global_load_lds_dwordx4 v[240:241], off
	s_waitcnt vmcnt(6)
	s_barrier
	s_setprio 1
	v_mfma_f32_16x16x32_bf16 v[56:59], v[216:219], v[146:149], v[100:103]
	v_mfma_f32_16x16x32_bf16 v[100:103], v[220:223], v[158:161], v[56:59]
	v_mfma_f32_16x16x32_bf16 v[56:59], v[224:227], v[146:149], v[96:99]
	v_mfma_f32_16x16x32_bf16 v[96:99], v[228:231], v[158:161], v[56:59]
	v_mfma_f32_16x16x32_bf16 v[56:59], v[216:219], v[162:165], v[84:87]
	v_mfma_f32_16x16x32_bf16 v[84:87], v[220:223], v[166:169], v[56:59]
	v_mfma_f32_16x16x32_bf16 v[56:59], v[224:227], v[162:165], v[80:83]
	v_mfma_f32_16x16x32_bf16 v[80:83], v[228:231], v[166:169], v[56:59]
	v_mfma_f32_16x16x32_bf16 v[56:59], v[216:219], v[170:173], v[68:71]
	v_mfma_f32_16x16x32_bf16 v[68:71], v[220:223], v[194:197], v[56:59]
	v_mfma_f32_16x16x32_bf16 v[56:59], v[224:227], v[170:173], v[64:67]
	v_mfma_f32_16x16x32_bf16 v[52:55], v[216:219], v[198:201], v[52:55]
	v_mfma_f32_16x16x32_bf16 v[48:51], v[224:227], v[198:201], v[48:51]
	v_mfma_f32_16x16x32_bf16 v[64:67], v[228:231], v[194:197], v[56:59]
	v_mfma_f32_16x16x32_bf16 v[52:55], v[220:223], v[212:215], v[52:55]
	v_mfma_f32_16x16x32_bf16 v[48:51], v[228:231], v[212:215], v[48:51]
	s_setprio 0
	s_add_i32 s40, 0, 0x18000
	v_add_u32_e32 v18, s40, v204
	s_barrier
	ds_read_b128 v[56:59], v18
	ds_read_b128 v[60:63], v18 offset:1024
	ds_read_b128 v[112:115], v18 offset:2048
	ds_read_b128 v[116:119], v18 offset:3072
	s_add_u32 s6, s6, s10
	s_addc_u32 s7, s7, s11
	s_mov_b32 m0, s45
	v_lshl_add_u64 v[18:19], s[6:7], 0, v[174:175]
	ds_read_b128 v[146:149], v206 offset:32768
	ds_read_b128 v[158:161], v206 offset:33792
	ds_read_b128 v[162:165], v206 offset:34816
	ds_read_b128 v[166:169], v206 offset:35840
	ds_read_b128 v[170:173], v206 offset:36864
	ds_read_b128 v[194:197], v206 offset:37888
	ds_read_b128 v[198:201], v206 offset:38912
	ds_read_b128 v[212:215], v206 offset:39936
	global_load_lds_dwordx4 v[18:19], off
	v_lshl_add_u64 v[18:19], s[6:7], 0, v[176:177]
	s_mov_b32 m0, s46
	s_nop 0
	global_load_lds_dwordx4 v[18:19], off
	s_waitcnt lgkmcnt(8)
	s_barrier
	s_waitcnt lgkmcnt(0)
	s_setprio 1
	v_mfma_f32_16x16x32_bf16 v[44:47], v[56:59], v[146:149], v[44:47]
	v_mfma_f32_16x16x32_bf16 v[40:43], v[112:115], v[146:149], v[40:43]
	v_mfma_f32_16x16x32_bf16 v[28:31], v[56:59], v[162:165], v[28:31]
	v_mfma_f32_16x16x32_bf16 v[24:27], v[112:115], v[162:165], v[24:27]
	v_mfma_f32_16x16x32_bf16 v[154:157], v[56:59], v[170:173], v[154:157]
	v_mfma_f32_16x16x32_bf16 v[150:153], v[112:115], v[170:173], v[150:153]
	v_mfma_f32_16x16x32_bf16 v[138:141], v[56:59], v[198:201], v[138:141]
	v_mfma_f32_16x16x32_bf16 v[134:137], v[112:115], v[198:201], v[134:137]
	v_mfma_f32_16x16x32_bf16 v[44:47], v[60:63], v[158:161], v[44:47]
	v_mfma_f32_16x16x32_bf16 v[40:43], v[116:119], v[158:161], v[40:43]
	v_mfma_f32_16x16x32_bf16 v[28:31], v[60:63], v[166:169], v[28:31]
	v_mfma_f32_16x16x32_bf16 v[24:27], v[116:119], v[166:169], v[24:27]
	v_mfma_f32_16x16x32_bf16 v[154:157], v[60:63], v[194:197], v[154:157]
	v_mfma_f32_16x16x32_bf16 v[150:153], v[116:119], v[194:197], v[150:153]
	v_mfma_f32_16x16x32_bf16 v[138:141], v[60:63], v[212:215], v[138:141]
	v_mfma_f32_16x16x32_bf16 v[134:137], v[116:119], v[212:215], v[134:137]
	s_setprio 0
	s_barrier
	s_add_i32 s6, 0, 0x1c000
	v_add_u32_e32 v18, s6, v204
	s_add_i32 s7, s40, s42
	ds_read_b128 v[216:219], v18
	ds_read_b128 v[220:223], v18 offset:1024
	ds_read_b128 v[224:227], v18 offset:2048
	ds_read_b128 v[228:231], v18 offset:3072
	v_lshl_add_u64 v[18:19], v[202:203], 0, s[20:21]
	s_mov_b32 m0, s7
	s_nop 0
	global_load_lds_dwordx4 v[18:19], off
	v_lshl_add_u64 v[18:19], v[232:233], 0, s[20:21]
	s_add_i32 m0, s7, 0x2000
	s_nop 0
	global_load_lds_dwordx4 v[18:19], off
	s_barrier
	s_waitcnt lgkmcnt(0)
	s_setprio 1
	v_mfma_f32_16x16x32_bf16 v[120:123], v[216:219], v[170:173], v[120:123]
	v_mfma_f32_16x16x32_bf16 v[36:39], v[216:219], v[146:149], v[36:39]
	v_mfma_f32_16x16x32_bf16 v[32:35], v[224:227], v[146:149], v[32:35]
	v_mfma_f32_16x16x32_bf16 v[146:149], v[220:223], v[194:197], v[120:123]
	v_mfma_f32_16x16x32_bf16 v[120:123], v[224:227], v[170:173], v[142:145]
	v_mfma_f32_16x16x32_bf16 v[142:145], v[228:231], v[194:197], v[120:123]
	v_mfma_f32_16x16x32_bf16 v[120:123], v[216:219], v[198:201], v[130:133]
	v_mfma_f32_16x16x32_bf16 v[18:21], v[216:219], v[162:165], v[20:23]
	v_mfma_f32_16x16x32_bf16 v[14:17], v[224:227], v[162:165], v[14:17]
	v_mfma_f32_16x16x32_bf16 v[130:133], v[220:223], v[212:215], v[120:123]
	v_mfma_f32_16x16x32_bf16 v[120:123], v[224:227], v[198:201], v[124:127]
	v_mfma_f32_16x16x32_bf16 v[36:39], v[220:223], v[158:161], v[36:39]
	v_mfma_f32_16x16x32_bf16 v[32:35], v[228:231], v[158:161], v[32:35]
	v_mfma_f32_16x16x32_bf16 v[20:23], v[220:223], v[166:169], v[18:21]
	v_mfma_f32_16x16x32_bf16 v[16:19], v[228:231], v[166:169], v[14:17]
	v_mfma_f32_16x16x32_bf16 v[126:129], v[228:231], v[212:215], v[120:123]
	s_setprio 0
	s_mov_b32 m0, s50
	v_lshl_add_u64 v[14:15], v[234:235], 0, s[20:21]
	s_barrier
; #define PG8_STAGE(bufoff, gbase, voff) do { _Pragma("unroll") for (int _i = 0; _i < 2; ++_i) \
;         __builtin_amdgcn_global_load_lds((const unsigned*)((const char*)(gbase) + (voff)[_i]), (LAS unsigned*)(lds + (bufoff) + ldsw + _i * 8192), 16, 0, 0); } while (0)
; #define STG_A(bufoff, kb, h, usen) do { if constexpr (GATHER) { unsigned o_[2] = {(usen) ? noff[h][0] : coff[h][0], (usen) ? noff[h][1] : coff[h][1]}; PG8_STAGE(bufoff, (const char*)A + (kb), o_); } \
;         else { PG8_STAGE(bufoff, ((usen) ? nA : cA) + (kb) + (size_t)(h) * hstep, voffA); } } while (0)
; #define PG8_LDA(dst, b, h) do { _Pragma("unroll") for (int m = 0; m < 4; ++m) _Pragma("unroll") for (int k = 0; k < 2; ++k) dst[m][k] = *(const LAS bf16x8*)(lds + PG8_SA(b, h) + aoff + m * 2048 + k * 1024); } while (0)
; #define PG8_MMA(ai, bj, At, Bt_) do { __builtin_amdgcn_s_setprio(1); _Pragma("unroll") for (int m = 0; m < 4; ++m) _Pragma("unroll") for (int n = 0; n < 2; ++n) _Pragma("unroll") for (int k = 0; k < 2; ++k) \
;         acc[ai][bj][m][n] = __builtin_amdgcn_mfma_f32_16x16x32_bf16(Bt_[n][k], At[m][k], acc[ai][bj][m][n], 0, 0, 0); __builtin_amdgcn_s_setprio(0); } while (0)
; #define PG8_WAIT_V(n) asm volatile("s_waitcnt vmcnt(" #n ")" ::: "memory")
; #define PG8_WAIT_L(n) asm volatile("s_waitcnt lgkmcnt(" #n ")" ::: "memory")
; #define PG8_BAR __builtin_amdgcn_s_barrier()
; #define PG8_SCHED __builtin_amdgcn_sched_barrier(0)
; template <class Epi, bool GATHER = false>
; __device__ __forceinline__ void gemm_phase(LAS unsigned char* lds, const bf16_t* A, const bf16_t* Bt, const int K_, const Sched& S, const Epi& E, const int* gidx = nullptr) {
;     ...
;             PG8_LDA(At, 1, 1); STG_A(PG8_SA(1, 0), k3, 0, last);
;             PG8_BAR; PG8_WAIT_L(0); PG8_MMA(1, 0, At, B0); PG8_BAR; PG8_SCHED;
;             PG8_STAGE(PG8_SB(1, 1), b3 + hstep, voffA);
;             PG8_WAIT_V(6); PG8_BAR; PG8_MMA(1, 1, At, B1); PG8_BAR;
;         }
;         E(acc, cur, wr, wc, fr, fq);
	ds_read_b128 v[120:123], v206 offset:49152
	ds_read_b128 v[158:161], v206 offset:50176
	ds_read_b128 v[162:165], v206 offset:51200
	ds_read_b128 v[166:169], v206 offset:52224
	ds_read_b128 v[170:173], v206 offset:53248
	ds_read_b128 v[194:197], v206 offset:54272
	ds_read_b128 v[198:201], v206 offset:55296
	ds_read_b128 v[212:215], v206 offset:56320
	global_load_lds_dwordx4 v[14:15], off
	v_lshl_add_u64 v[14:15], v[236:237], 0, s[20:21]
	s_mov_b32 m0, s51
	s_nop 0
	global_load_lds_dwordx4 v[14:15], off
	s_barrier
	s_waitcnt lgkmcnt(0)
	s_setprio 1
	v_mfma_f32_16x16x32_bf16 v[108:111], v[56:59], v[120:123], v[108:111]
	v_mfma_f32_16x16x32_bf16 v[92:95], v[56:59], v[162:165], v[92:95]
	v_mfma_f32_16x16x32_bf16 v[76:79], v[56:59], v[170:173], v[76:79]
	v_mfma_f32_16x16x32_bf16 v[6:9], v[56:59], v[198:201], v[6:9]
	v_mfma_f32_16x16x32_bf16 v[108:111], v[60:63], v[158:161], v[108:111]
	v_mfma_f32_16x16x32_bf16 v[104:107], v[112:115], v[120:123], v[104:107]
	v_mfma_f32_16x16x32_bf16 v[92:95], v[60:63], v[166:169], v[92:95]
	v_mfma_f32_16x16x32_bf16 v[88:91], v[112:115], v[162:165], v[88:91]
	v_mfma_f32_16x16x32_bf16 v[76:79], v[60:63], v[194:197], v[76:79]
	v_mfma_f32_16x16x32_bf16 v[72:75], v[112:115], v[170:173], v[72:75]
	v_mfma_f32_16x16x32_bf16 v[60:63], v[60:63], v[212:215], v[6:9]
	v_mfma_f32_16x16x32_bf16 v[6:9], v[112:115], v[198:201], v[10:13]
	v_mfma_f32_16x16x32_bf16 v[104:107], v[116:119], v[158:161], v[104:107]
	v_mfma_f32_16x16x32_bf16 v[88:91], v[116:119], v[166:169], v[88:91]
	v_mfma_f32_16x16x32_bf16 v[72:75], v[116:119], v[194:197], v[72:75]
	v_mfma_f32_16x16x32_bf16 v[56:59], v[116:119], v[212:215], v[6:9]
	s_setprio 0
	s_barrier
	s_add_i32 s6, s6, s42
	s_nop 0
	v_lshl_add_u64 v[6:7], v[238:239], 0, s[20:21]
	s_mov_b32 m0, s6
	s_nop 0
	global_load_lds_dwordx4 v[6:7], off
	v_lshl_add_u64 v[6:7], v[240:241], 0, s[20:21]
	s_add_i32 m0, s6, 0x2000
	s_nop 0
	global_load_lds_dwordx4 v[6:7], off
	s_waitcnt vmcnt(6)
	s_barrier
	s_setprio 1
	v_mfma_f32_16x16x32_bf16 v[6:9], v[216:219], v[120:123], v[100:103]
	v_mfma_f32_16x16x32_bf16 v[100:103], v[220:223], v[158:161], v[6:9]
	v_mfma_f32_16x16x32_bf16 v[6:9], v[224:227], v[120:123], v[96:99]
	v_mfma_f32_16x16x32_bf16 v[96:99], v[228:231], v[158:161], v[6:9]
	v_mfma_f32_16x16x32_bf16 v[6:9], v[216:219], v[162:165], v[84:87]
	v_mfma_f32_16x16x32_bf16 v[84:87], v[220:223], v[166:169], v[6:9]
	v_mfma_f32_16x16x32_bf16 v[6:9], v[224:227], v[162:165], v[80:83]
	v_mfma_f32_16x16x32_bf16 v[80:83], v[228:231], v[166:169], v[6:9]
	v_mfma_f32_16x16x32_bf16 v[6:9], v[216:219], v[170:173], v[68:71]
	v_mfma_f32_16x16x32_bf16 v[68:71], v[220:223], v[194:197], v[6:9]
	v_mfma_f32_16x16x32_bf16 v[6:9], v[224:227], v[170:173], v[64:67]
	v_mfma_f32_16x16x32_bf16 v[64:67], v[228:231], v[194:197], v[6:9]
	v_mfma_f32_16x16x32_bf16 v[6:9], v[216:219], v[198:201], v[52:55]
	v_mfma_f32_16x16x32_bf16 v[52:55], v[220:223], v[212:215], v[6:9]
	v_mfma_f32_16x16x32_bf16 v[6:9], v[224:227], v[198:201], v[48:51]
	v_mfma_f32_16x16x32_bf16 v[48:51], v[228:231], v[212:215], v[6:9]
	s_setprio 0
	s_cmp_ge_i32 s65, s49
	s_mov_b64 s[6:7], s[38:39]
	s_mov_b32 s40, s65
	s_barrier
	s_cbranch_scc0 .LBB0_255
	v_mov_b32_e32 v203, v46
	v_mov_b32_e32 v46, v45
	v_mov_b32_e32 v202, v44
	v_mov_b32_e32 v45, v42
	v_mov_b32_e32 v42, v41
	v_mov_b32_e32 v44, v40
	v_mov_b32_e32 v201, v30
	v_mov_b32_e32 v30, v29
	v_mov_b32_e32 v200, v28
	v_mov_b32_e32 v29, v26
	v_mov_b32_e32 v26, v25
	v_mov_b32_e32 v28, v24
	v_mov_b32_e32 v195, v156
	v_mov_b32_e32 v156, v155
	v_mov_b32_e32 v194, v154
	v_mov_b32_e32 v155, v152
	v_mov_b32_e32 v152, v151
	v_mov_b32_e32 v154, v150
	v_mov_b32_e32 v151, v140
	v_mov_b32_e32 v140, v139
	v_mov_b32_e32 v150, v138
	v_mov_b32_e32 v139, v136
	v_mov_b32_e32 v136, v135
	v_mov_b32_e32 v138, v134
	v_mov_b32_e32 v41, v38
	v_mov_b32_e32 v38, v37
	v_mov_b32_e32 v40, v36
	v_mov_b32_e32 v37, v34
	v_mov_b32_e32 v34, v33
	v_mov_b32_e32 v36, v32
	v_mov_b32_e32 v25, v22
	v_mov_b32_e32 v22, v21
	v_mov_b32_e32 v24, v20
	v_mov_b32_e32 v21, v18
	v_mov_b32_e32 v18, v17
	v_mov_b32_e32 v20, v16
	v_mov_b32_e32 v197, v148
	v_mov_b32_e32 v148, v147
	v_mov_b32_e32 v196, v146
	v_mov_b32_e32 v199, v144
	v_mov_b32_e32 v144, v143
	v_mov_b32_e32 v198, v142
	v_mov_b32_e32 v143, v132
	v_mov_b32_e32 v132, v131
	v_mov_b32_e32 v142, v130
	v_mov_b32_e32 v147, v128
	v_mov_b32_e32 v128, v127
	v_mov_b32_e32 v146, v126
	v_mov_b32_e32 v131, v110
	v_mov_b32_e32 v110, v109
	v_mov_b32_e32 v130, v108
	v_mov_b32_e32 v109, v106
	v_mov_b32_e32 v106, v105
	v_mov_b32_e32 v108, v104
	v_mov_b32_e32 v105, v94
	v_mov_b32_e32 v94, v93
	v_mov_b32_e32 v104, v92
	v_mov_b32_e32 v93, v90
	v_mov_b32_e32 v90, v89
	v_mov_b32_e32 v92, v88
	v_mov_b32_e32 v89, v78
	v_mov_b32_e32 v78, v77
	v_mov_b32_e32 v88, v76
	v_mov_b32_e32 v77, v74
	v_mov_b32_e32 v74, v73
	v_mov_b32_e32 v76, v72
	v_mov_b32_e32 v73, v62
	v_mov_b32_e32 v62, v61
	v_mov_b32_e32 v72, v60
	v_mov_b32_e32 v61, v58
	v_mov_b32_e32 v58, v57
	v_mov_b32_e32 v60, v56
	v_mov_b32_e32 v135, v102
	v_mov_b32_e32 v102, v101
	v_mov_b32_e32 v134, v100
	v_mov_b32_e32 v101, v98
	v_mov_b32_e32 v98, v97
	v_mov_b32_e32 v100, v96
	v_mov_b32_e32 v97, v86
	v_mov_b32_e32 v86, v85
	v_mov_b32_e32 v96, v84
	v_mov_b32_e32 v85, v82
	v_mov_b32_e32 v82, v81
	v_mov_b32_e32 v84, v80
	v_mov_b32_e32 v81, v70
	v_mov_b32_e32 v70, v69
	v_mov_b32_e32 v80, v68
	v_mov_b32_e32 v69, v66
	v_mov_b32_e32 v66, v65
	v_mov_b32_e32 v68, v64
	v_mov_b32_e32 v57, v54
	v_mov_b32_e32 v54, v53
	v_mov_b32_e32 v56, v52
	v_mov_b32_e32 v53, v50
	v_mov_b32_e32 v50, v49
	v_mov_b32_e32 v52, v48

; #define PG8_STAGE(bufoff, gbase, voff) do { _Pragma("unroll") for (int _i = 0; _i < 2; ++_i) \
;         __builtin_amdgcn_global_load_lds((const unsigned*)((const char*)(gbase) + (voff)[_i]), (LAS unsigned*)(lds + (bufoff) + ldsw + _i * 8192), 16, 0, 0); } while (0)
; #define STG_A(bufoff, kb, h, usen) do { if constexpr (GATHER) { unsigned o_[2] = {(usen) ? noff[h][0] : coff[h][0], (usen) ? noff[h][1] : coff[h][1]}; PG8_STAGE(bufoff, (const char*)A + (kb), o_); } \
;         else { PG8_STAGE(bufoff, ((usen) ? nA : cA) + (kb) + (size_t)(h) * hstep, voffA); } } while (0)
; #define PG8_LDA(dst, b, h) do { _Pragma("unroll") for (int m = 0; m < 4; ++m) _Pragma("unroll") for (int k = 0; k < 2; ++k) dst[m][k] = *(const LAS bf16x8*)(lds + PG8_SA(b, h) + aoff + m * 2048 + k * 1024); } while (0)
; #define PG8_LDB(dst, b, h) do { _Pragma("unroll") for (int n = 0; n < 2; ++n) _Pragma("unroll") for (int k = 0; k < 2; ++k) dst[n][k] = *(const LAS bf16x8*)(lds + PG8_SB(b, h) + boff + n * 2048 + k * 1024); } while (0)
; #define PG8_MMA(ai, bj, At, Bt_) do { __builtin_amdgcn_s_setprio(1); _Pragma("unroll") for (int m = 0; m < 4; ++m) _Pragma("unroll") for (int n = 0; n < 2; ++n) _Pragma("unroll") for (int k = 0; k < 2; ++k) \
;         acc[ai][bj][m][n] = __builtin_amdgcn_mfma_f32_16x16x32_bf16(Bt_[n][k], At[m][k], acc[ai][bj][m][n], 0, 0, 0); __builtin_amdgcn_s_setprio(0); } while (0)
; #define PG8_WAIT_L(n) asm volatile("s_waitcnt lgkmcnt(" #n ")" ::: "memory")
; #define PG8_BAR __builtin_amdgcn_s_barrier()
; #define PG8_SCHED __builtin_amdgcn_sched_barrier(0)
; template <class Epi, bool GATHER = false>
; __device__ __forceinline__ void gemm_phase(LAS unsigned char* lds, const bf16_t* A, const bf16_t* Bt, const int K_, const Sched& S, const Epi& E, const int* gidx = nullptr) {
;     ...
;             PG8_LDB(B0, 0, 0); PG8_SCHED; PG8_LDA(At, 0, 0); STG_A(PG8_SA(1, 1), k1, 1, false);
;             PG8_WAIT_L(8); PG8_BAR; PG8_WAIT_L(0); PG8_MMA(0, 0, At, B0); PG8_BAR; PG8_SCHED;
;             PG8_LDB(B1, 0, 1); PG8_STAGE(PG8_SB(0, 0), b2, voffA);
;             PG8_BAR; PG8_WAIT_L(0); PG8_MMA(0, 1, At, B1); PG8_BAR;
;             PG8_LDA(At, 0, 1); STG_A(PG8_SA(0, 0), k2, 0, last);
;             PG8_BAR; PG8_WAIT_L(0); PG8_MMA(1, 0, At, B0); PG8_BAR; PG8_SCHED;
.LBB0_607:
	s_add_i32 s82, s50, 2
	s_add_u32 s48, s46, 0x100
	ds_read_b128 v[148:151], v144
	ds_read_b128 v[152:155], v144 offset:1024
	ds_read_b128 v[156:159], v144 offset:2048
	ds_read_b128 v[160:163], v144 offset:3072
	s_addc_u32 s49, s47, 0
	s_add_u32 s83, s80, s46
	s_addc_u32 s51, s81, s47
	s_add_i32 s85, s66, s55
	s_add_i32 m0, s56, 0xc000
	s_add_i32 s84, s56, 0xe000
	s_add_i32 s86, s85, 0x2000
	s_cmp_eq_u32 s65, s50
	s_cselect_b32 s50, s0, s83
	s_cselect_b32 s51, s1, s51
	s_cselect_b32 s83, 0, s49
	s_cselect_b32 s87, 0, s48
	v_lshl_add_u64 v[198:199], v[138:139], 0, s[46:47]
	ds_read_b128 v[164:167], v145
	ds_read_b128 v[168:171], v145 offset:1024
	ds_read_b128 v[172:175], v145 offset:2048
	ds_read_b128 v[176:179], v145 offset:3072
	ds_read_b128 v[182:185], v145 offset:4096
	ds_read_b128 v[186:189], v145 offset:5120
	ds_read_b128 v[190:193], v145 offset:6144
	ds_read_b128 v[194:197], v145 offset:7168
	global_load_lds_dwordx4 v[198:199], off
	v_lshl_add_u64 v[198:199], v[140:141], 0, s[46:47]
	s_mov_b32 m0, s84
	s_nop 0
	global_load_lds_dwordx4 v[198:199], off
	s_waitcnt lgkmcnt(8)
	s_barrier
	s_waitcnt lgkmcnt(0)
	s_setprio 1
	v_mfma_f32_16x16x32_bf16 v[122:125], v[148:151], v[164:167], v[122:125]
	v_mfma_f32_16x16x32_bf16 v[118:121], v[156:159], v[164:167], v[118:121]
	v_mfma_f32_16x16x32_bf16 v[110:113], v[148:151], v[172:175], v[110:113]
	v_mfma_f32_16x16x32_bf16 v[102:105], v[156:159], v[172:175], v[102:105]
	v_mfma_f32_16x16x32_bf16 v[94:97], v[148:151], v[182:185], v[94:97]
	v_mfma_f32_16x16x32_bf16 v[86:89], v[156:159], v[182:185], v[86:89]
	v_mfma_f32_16x16x32_bf16 v[78:81], v[148:151], v[190:193], v[78:81]
	v_mfma_f32_16x16x32_bf16 v[70:73], v[156:159], v[190:193], v[70:73]
	v_mfma_f32_16x16x32_bf16 v[122:125], v[152:155], v[168:171], v[122:125]
	v_mfma_f32_16x16x32_bf16 v[118:121], v[160:163], v[168:171], v[118:121]
	v_mfma_f32_16x16x32_bf16 v[110:113], v[152:155], v[176:179], v[110:113]
	v_mfma_f32_16x16x32_bf16 v[102:105], v[160:163], v[176:179], v[102:105]
	v_mfma_f32_16x16x32_bf16 v[94:97], v[152:155], v[186:189], v[94:97]
	v_mfma_f32_16x16x32_bf16 v[86:89], v[160:163], v[186:189], v[86:89]
	v_mfma_f32_16x16x32_bf16 v[78:81], v[152:155], v[194:197], v[78:81]
	v_mfma_f32_16x16x32_bf16 v[70:73], v[160:163], v[194:197], v[70:73]
	s_setprio 0
	s_barrier
	s_mov_b32 m0, s85
	v_lshl_add_u64 v[214:215], s[50:51], 0, v[132:133]
	ds_read_b128 v[198:201], v146
	ds_read_b128 v[202:205], v146 offset:1024
	ds_read_b128 v[206:209], v146 offset:2048
	ds_read_b128 v[210:213], v146 offset:3072
	global_load_lds_dwordx4 v[214:215], off
	v_lshl_add_u64 v[216:217], s[50:51], 0, v[130:131]
	s_mov_b32 m0, s86
	s_nop 0
	global_load_lds_dwordx4 v[216:217], off
	s_barrier
	s_waitcnt lgkmcnt(0)
	s_setprio 1
	v_mfma_f32_16x16x32_bf16 v[126:129], v[198:201], v[164:167], v[126:129]
	v_mfma_f32_16x16x32_bf16 v[114:117], v[206:209], v[164:167], v[114:117]
	v_mfma_f32_16x16x32_bf16 v[106:109], v[198:201], v[172:175], v[106:109]
	v_mfma_f32_16x16x32_bf16 v[98:101], v[206:209], v[172:175], v[98:101]
	v_mfma_f32_16x16x32_bf16 v[90:93], v[198:201], v[182:185], v[90:93]
	v_mfma_f32_16x16x32_bf16 v[82:85], v[206:209], v[182:185], v[82:85]
	v_mfma_f32_16x16x32_bf16 v[74:77], v[198:201], v[190:193], v[74:77]
	v_mfma_f32_16x16x32_bf16 v[66:69], v[206:209], v[190:193], v[66:69]
	v_mfma_f32_16x16x32_bf16 v[126:129], v[202:205], v[168:171], v[126:129]
	v_mfma_f32_16x16x32_bf16 v[114:117], v[210:213], v[168:171], v[114:117]
	v_mfma_f32_16x16x32_bf16 v[106:109], v[202:205], v[176:179], v[106:109]
	v_mfma_f32_16x16x32_bf16 v[98:101], v[210:213], v[176:179], v[98:101]
	v_mfma_f32_16x16x32_bf16 v[90:93], v[202:205], v[186:189], v[90:93]
	v_mfma_f32_16x16x32_bf16 v[82:85], v[210:213], v[186:189], v[82:85]
	v_mfma_f32_16x16x32_bf16 v[74:77], v[202:205], v[194:197], v[74:77]
	v_mfma_f32_16x16x32_bf16 v[66:69], v[210:213], v[194:197], v[66:69]
	s_setprio 0
	s_cselect_b32 s46, s42, s44
	s_cselect_b32 s47, s43, s45
	s_add_u32 s46, s46, s87
	s_addc_u32 s47, s47, s83
	s_mov_b32 m0, s56
	v_lshl_add_u64 v[218:219], s[46:47], 0, v[132:133]
	s_barrier
	ds_read_b128 v[164:167], v145 offset:16384
	ds_read_b128 v[168:171], v145 offset:17408
	ds_read_b128 v[172:175], v145 offset:18432
	ds_read_b128 v[176:179], v145 offset:19456
	ds_read_b128 v[182:185], v145 offset:20480
	ds_read_b128 v[186:189], v145 offset:21504
	ds_read_b128 v[190:193], v145 offset:22528
	ds_read_b128 v[194:197], v145 offset:23552
	global_load_lds_dwordx4 v[218:219], off
	v_lshl_add_u64 v[220:221], s[46:47], 0, v[130:131]
	s_mov_b32 m0, s57
	s_nop 0
	global_load_lds_dwordx4 v[220:221], off
	s_barrier
	s_waitcnt lgkmcnt(0)
	s_setprio 1
	v_mfma_f32_16x16x32_bf16 v[62:65], v[148:151], v[164:167], v[62:65]
	v_mfma_f32_16x16x32_bf16 v[58:61], v[156:159], v[164:167], v[58:61]
	v_mfma_f32_16x16x32_bf16 v[46:49], v[148:151], v[172:175], v[46:49]
	v_mfma_f32_16x16x32_bf16 v[42:45], v[156:159], v[172:175], v[42:45]
	v_mfma_f32_16x16x32_bf16 v[30:33], v[148:151], v[182:185], v[30:33]
	v_mfma_f32_16x16x32_bf16 v[26:29], v[156:159], v[182:185], v[26:29]
	v_mfma_f32_16x16x32_bf16 v[14:17], v[148:151], v[190:193], v[14:17]
	v_mfma_f32_16x16x32_bf16 v[10:13], v[156:159], v[190:193], v[10:13]
	v_mfma_f32_16x16x32_bf16 v[62:65], v[152:155], v[168:171], v[62:65]
	v_mfma_f32_16x16x32_bf16 v[58:61], v[160:163], v[168:171], v[58:61]
	v_mfma_f32_16x16x32_bf16 v[46:49], v[152:155], v[176:179], v[46:49]
	v_mfma_f32_16x16x32_bf16 v[42:45], v[160:163], v[176:179], v[42:45]
	v_mfma_f32_16x16x32_bf16 v[30:33], v[152:155], v[186:189], v[30:33]
	v_mfma_f32_16x16x32_bf16 v[26:29], v[160:163], v[186:189], v[26:29]
	v_mfma_f32_16x16x32_bf16 v[14:17], v[152:155], v[194:197], v[14:17]
	v_mfma_f32_16x16x32_bf16 v[10:13], v[160:163], v[194:197], v[10:13]
	s_setprio 0
	s_barrier
; #define PG8_STAGE(bufoff, gbase, voff) do { _Pragma("unroll") for (int _i = 0; _i < 2; ++_i) \
;         __builtin_amdgcn_global_load_lds((const unsigned*)((const char*)(gbase) + (voff)[_i]), (LAS unsigned*)(lds + (bufoff) + ldsw + _i * 8192), 16, 0, 0); } while (0)
; #define STG_A(bufoff, kb, h, usen) do { if constexpr (GATHER) { unsigned o_[2] = {(usen) ? noff[h][0] : coff[h][0], (usen) ? noff[h][1] : coff[h][1]}; PG8_STAGE(bufoff, (const char*)A + (kb), o_); } \
;         else { PG8_STAGE(bufoff, ((usen) ? nA : cA) + (kb) + (size_t)(h) * hstep, voffA); } } while (0)
; #define PG8_LDA(dst, b, h) do { _Pragma("unroll") for (int m = 0; m < 4; ++m) _Pragma("unroll") for (int k = 0; k < 2; ++k) dst[m][k] = *(const LAS bf16x8*)(lds + PG8_SA(b, h) + aoff + m * 2048 + k * 1024); } while (0)
; #define PG8_LDB(dst, b, h) do { _Pragma("unroll") for (int n = 0; n < 2; ++n) _Pragma("unroll") for (int k = 0; k < 2; ++k) dst[n][k] = *(const LAS bf16x8*)(lds + PG8_SB(b, h) + boff + n * 2048 + k * 1024); } while (0)
; #define PG8_MMA(ai, bj, At, Bt_) do { __builtin_amdgcn_s_setprio(1); _Pragma("unroll") for (int m = 0; m < 4; ++m) _Pragma("unroll") for (int n = 0; n < 2; ++n) _Pragma("unroll") for (int k = 0; k < 2; ++k) \
;         acc[ai][bj][m][n] = __builtin_amdgcn_mfma_f32_16x16x32_bf16(Bt_[n][k], At[m][k], acc[ai][bj][m][n], 0, 0, 0); __builtin_amdgcn_s_setprio(0); } while (0)
; #define PG8_WAIT_V(n) asm volatile("s_waitcnt vmcnt(" #n ")" ::: "memory")
; #define PG8_WAIT_L(n) asm volatile("s_waitcnt lgkmcnt(" #n ")" ::: "memory")
; #define PG8_BAR __builtin_amdgcn_s_barrier()
; #define PG8_SCHED __builtin_amdgcn_sched_barrier(0)
; template <class Epi, bool GATHER = false>
; __device__ __forceinline__ void gemm_phase(LAS unsigned char* lds, const bf16_t* A, const bf16_t* Bt, const int K_, const Sched& S, const Epi& E, const int* gidx = nullptr) {
;     ...
;             PG8_STAGE(PG8_SB(0, 1), b2 + hstep, voffA);
;             PG8_WAIT_V(6); PG8_BAR; PG8_MMA(1, 1, At, B1); PG8_BAR;
;             PG8_LDB(B0, 1, 0); PG8_SCHED; PG8_LDA(At, 1, 0); STG_A(PG8_SA(0, 1), k2, 1, last);
;             PG8_WAIT_L(8); PG8_BAR; PG8_WAIT_L(0); PG8_MMA(0, 0, At, B0); PG8_BAR; PG8_SCHED;
;             PG8_LDB(B1, 1, 1); PG8_STAGE(PG8_SB(1, 0), b3, voffA);
	s_add_u32 s50, s50, s8
	s_addc_u32 s51, s51, s9
	s_add_i32 s83, s67, s55
	v_lshl_add_u64 v[222:223], s[50:51], 0, v[132:133]
	s_mov_b32 m0, s83
	v_lshl_add_u64 v[224:225], s[50:51], 0, v[130:131]
	global_load_lds_dwordx4 v[222:223], off
	s_add_i32 m0, s83, 0x2000
	s_nop 0
	global_load_lds_dwordx4 v[224:225], off
	s_waitcnt vmcnt(6)
	s_barrier
	s_setprio 1
	v_mfma_f32_16x16x32_bf16 v[54:57], v[198:201], v[164:167], v[54:57]
	v_mfma_f32_16x16x32_bf16 v[50:53], v[206:209], v[164:167], v[50:53]
	v_mfma_f32_16x16x32_bf16 v[38:41], v[198:201], v[172:175], v[38:41]
	v_mfma_f32_16x16x32_bf16 v[34:37], v[206:209], v[172:175], v[34:37]
	v_mfma_f32_16x16x32_bf16 v[22:25], v[198:201], v[182:185], v[22:25]
	v_mfma_f32_16x16x32_bf16 v[18:21], v[206:209], v[182:185], v[18:21]
	v_mfma_f32_16x16x32_bf16 v[6:9], v[198:201], v[190:193], v[6:9]
	v_mfma_f32_16x16x32_bf16 v[2:5], v[206:209], v[190:193], v[2:5]
	v_mfma_f32_16x16x32_bf16 v[54:57], v[202:205], v[168:171], v[54:57]
	v_mfma_f32_16x16x32_bf16 v[50:53], v[210:213], v[168:171], v[50:53]
	v_mfma_f32_16x16x32_bf16 v[38:41], v[202:205], v[176:179], v[38:41]
	v_mfma_f32_16x16x32_bf16 v[34:37], v[210:213], v[176:179], v[34:37]
	v_mfma_f32_16x16x32_bf16 v[22:25], v[202:205], v[186:189], v[22:25]
	v_mfma_f32_16x16x32_bf16 v[18:21], v[210:213], v[186:189], v[18:21]
	v_mfma_f32_16x16x32_bf16 v[6:9], v[202:205], v[194:197], v[6:9]
	v_mfma_f32_16x16x32_bf16 v[2:5], v[210:213], v[194:197], v[2:5]
	s_setprio 0
	s_add_i32 s50, 0, 0x18000
	v_add_u32_e32 v147, s50, v142
	s_barrier
	ds_read_b128 v[148:151], v147
	ds_read_b128 v[152:155], v147 offset:1024
	ds_read_b128 v[156:159], v147 offset:2048
	ds_read_b128 v[160:163], v147 offset:3072
	s_add_u32 s46, s46, s8
	s_addc_u32 s47, s47, s9
	s_mov_b32 m0, s58
	v_lshl_add_u64 v[198:199], s[46:47], 0, v[132:133]
	ds_read_b128 v[164:167], v145 offset:32768
	ds_read_b128 v[168:171], v145 offset:33792
	ds_read_b128 v[172:175], v145 offset:34816
	ds_read_b128 v[176:179], v145 offset:35840
	ds_read_b128 v[182:185], v145 offset:36864
	ds_read_b128 v[186:189], v145 offset:37888
	ds_read_b128 v[190:193], v145 offset:38912
	ds_read_b128 v[194:197], v145 offset:39936
	global_load_lds_dwordx4 v[198:199], off
	v_lshl_add_u64 v[198:199], s[46:47], 0, v[130:131]
	s_mov_b32 m0, s59
	s_nop 0
	global_load_lds_dwordx4 v[198:199], off
	s_waitcnt lgkmcnt(8)
	s_barrier
	s_waitcnt lgkmcnt(0)
	s_setprio 1
	v_mfma_f32_16x16x32_bf16 v[122:125], v[148:151], v[164:167], v[122:125]
	v_mfma_f32_16x16x32_bf16 v[118:121], v[156:159], v[164:167], v[118:121]
	v_mfma_f32_16x16x32_bf16 v[110:113], v[148:151], v[172:175], v[110:113]
	v_mfma_f32_16x16x32_bf16 v[102:105], v[156:159], v[172:175], v[102:105]
	v_mfma_f32_16x16x32_bf16 v[94:97], v[148:151], v[182:185], v[94:97]
	v_mfma_f32_16x16x32_bf16 v[86:89], v[156:159], v[182:185], v[86:89]
	v_mfma_f32_16x16x32_bf16 v[78:81], v[148:151], v[190:193], v[78:81]
	v_mfma_f32_16x16x32_bf16 v[70:73], v[156:159], v[190:193], v[70:73]
	v_mfma_f32_16x16x32_bf16 v[122:125], v[152:155], v[168:171], v[122:125]
	v_mfma_f32_16x16x32_bf16 v[118:121], v[160:163], v[168:171], v[118:121]
	v_mfma_f32_16x16x32_bf16 v[110:113], v[152:155], v[176:179], v[110:113]
	v_mfma_f32_16x16x32_bf16 v[102:105], v[160:163], v[176:179], v[102:105]
	v_mfma_f32_16x16x32_bf16 v[94:97], v[152:155], v[186:189], v[94:97]
	v_mfma_f32_16x16x32_bf16 v[86:89], v[160:163], v[186:189], v[86:89]
	v_mfma_f32_16x16x32_bf16 v[78:81], v[152:155], v[194:197], v[78:81]
	v_mfma_f32_16x16x32_bf16 v[70:73], v[160:163], v[194:197], v[70:73]
	s_setprio 0
	s_barrier
	s_add_i32 s46, 0, 0x1c000
	s_add_i32 s47, s50, s55
	v_add_u32_e32 v147, s46, v142
	v_lshl_add_u64 v[214:215], v[214:215], 0, s[12:13]
	s_mov_b32 m0, s47
	ds_read_b128 v[198:201], v147
	ds_read_b128 v[202:205], v147 offset:1024
	ds_read_b128 v[206:209], v147 offset:2048
	ds_read_b128 v[210:213], v147 offset:3072
	global_load_lds_dwordx4 v[214:215], off
	v_lshl_add_u64 v[214:215], v[216:217], 0, s[12:13]
	s_add_i32 m0, s47, 0x2000
	s_nop 0
	global_load_lds_dwordx4 v[214:215], off
	s_barrier
; #define PG8_STAGE(bufoff, gbase, voff) do { _Pragma("unroll") for (int _i = 0; _i < 2; ++_i) \
;         __builtin_amdgcn_global_load_lds((const unsigned*)((const char*)(gbase) + (voff)[_i]), (LAS unsigned*)(lds + (bufoff) + ldsw + _i * 8192), 16, 0, 0); } while (0)
; #define STG_A(bufoff, kb, h, usen) do { if constexpr (GATHER) { unsigned o_[2] = {(usen) ? noff[h][0] : coff[h][0], (usen) ? noff[h][1] : coff[h][1]}; PG8_STAGE(bufoff, (const char*)A + (kb), o_); } \
;         else { PG8_STAGE(bufoff, ((usen) ? nA : cA) + (kb) + (size_t)(h) * hstep, voffA); } } while (0)
; #define PG8_LDA(dst, b, h) do { _Pragma("unroll") for (int m = 0; m < 4; ++m) _Pragma("unroll") for (int k = 0; k < 2; ++k) dst[m][k] = *(const LAS bf16x8*)(lds + PG8_SA(b, h) + aoff + m * 2048 + k * 1024); } while (0)
; #define PG8_MMA(ai, bj, At, Bt_) do { __builtin_amdgcn_s_setprio(1); _Pragma("unroll") for (int m = 0; m < 4; ++m) _Pragma("unroll") for (int n = 0; n < 2; ++n) _Pragma("unroll") for (int k = 0; k < 2; ++k) \
;         acc[ai][bj][m][n] = __builtin_amdgcn_mfma_f32_16x16x32_bf16(Bt_[n][k], At[m][k], acc[ai][bj][m][n], 0, 0, 0); __builtin_amdgcn_s_setprio(0); } while (0)
; #define PG8_WAIT_V(n) asm volatile("s_waitcnt vmcnt(" #n ")" ::: "memory")
; #define PG8_WAIT_L(n) asm volatile("s_waitcnt lgkmcnt(" #n ")" ::: "memory")
; #define PG8_BAR __builtin_amdgcn_s_barrier()
; #define PG8_SCHED __builtin_amdgcn_sched_barrier(0)
; template <class Epi, bool GATHER = false>
; __device__ __forceinline__ void gemm_phase(LAS unsigned char* lds, const bf16_t* A, const bf16_t* Bt, const int K_, const Sched& S, const Epi& E, const int* gidx = nullptr) {
;     ...
;             PG8_BAR; PG8_WAIT_L(0); PG8_MMA(0, 1, At, B1); PG8_BAR;
;             PG8_LDA(At, 1, 1); STG_A(PG8_SA(1, 0), k3, 0, last);
;             PG8_BAR; PG8_WAIT_L(0); PG8_MMA(1, 0, At, B0); PG8_BAR; PG8_SCHED;
;             PG8_STAGE(PG8_SB(1, 1), b3 + hstep, voffA);
;             PG8_WAIT_V(6); PG8_BAR; PG8_MMA(1, 1, At, B1); PG8_BAR;
;         }
	s_waitcnt lgkmcnt(0)
	s_setprio 1
	v_mfma_f32_16x16x32_bf16 v[126:129], v[198:201], v[164:167], v[126:129]
	v_mfma_f32_16x16x32_bf16 v[114:117], v[206:209], v[164:167], v[114:117]
	v_mfma_f32_16x16x32_bf16 v[106:109], v[198:201], v[172:175], v[106:109]
	v_mfma_f32_16x16x32_bf16 v[98:101], v[206:209], v[172:175], v[98:101]
	v_mfma_f32_16x16x32_bf16 v[90:93], v[198:201], v[182:185], v[90:93]
	v_mfma_f32_16x16x32_bf16 v[82:85], v[206:209], v[182:185], v[82:85]
	v_mfma_f32_16x16x32_bf16 v[74:77], v[198:201], v[190:193], v[74:77]
	v_mfma_f32_16x16x32_bf16 v[66:69], v[206:209], v[190:193], v[66:69]
	v_mfma_f32_16x16x32_bf16 v[126:129], v[202:205], v[168:171], v[126:129]
	v_mfma_f32_16x16x32_bf16 v[114:117], v[210:213], v[168:171], v[114:117]
	v_mfma_f32_16x16x32_bf16 v[106:109], v[202:205], v[176:179], v[106:109]
	v_mfma_f32_16x16x32_bf16 v[98:101], v[210:213], v[176:179], v[98:101]
	v_mfma_f32_16x16x32_bf16 v[90:93], v[202:205], v[186:189], v[90:93]
	v_mfma_f32_16x16x32_bf16 v[82:85], v[210:213], v[186:189], v[82:85]
	v_mfma_f32_16x16x32_bf16 v[74:77], v[202:205], v[194:197], v[74:77]
	v_mfma_f32_16x16x32_bf16 v[66:69], v[210:213], v[194:197], v[66:69]
	s_setprio 0
	s_mov_b32 m0, s62
	v_lshl_add_u64 v[214:215], v[218:219], 0, s[12:13]
	s_barrier
	ds_read_b128 v[164:167], v145 offset:49152
	ds_read_b128 v[168:171], v145 offset:50176
	ds_read_b128 v[172:175], v145 offset:51200
	ds_read_b128 v[176:179], v145 offset:52224
	ds_read_b128 v[182:185], v145 offset:53248
	ds_read_b128 v[186:189], v145 offset:54272
	ds_read_b128 v[190:193], v145 offset:55296
	ds_read_b128 v[194:197], v145 offset:56320
	global_load_lds_dwordx4 v[214:215], off
	v_lshl_add_u64 v[214:215], v[220:221], 0, s[12:13]
	s_mov_b32 m0, s63
	s_nop 0
	global_load_lds_dwordx4 v[214:215], off
	s_barrier
	s_waitcnt lgkmcnt(0)
	s_setprio 1
	v_mfma_f32_16x16x32_bf16 v[62:65], v[148:151], v[164:167], v[62:65]
	v_mfma_f32_16x16x32_bf16 v[58:61], v[156:159], v[164:167], v[58:61]
	v_mfma_f32_16x16x32_bf16 v[46:49], v[148:151], v[172:175], v[46:49]
	v_mfma_f32_16x16x32_bf16 v[42:45], v[156:159], v[172:175], v[42:45]
	v_mfma_f32_16x16x32_bf16 v[30:33], v[148:151], v[182:185], v[30:33]
	v_mfma_f32_16x16x32_bf16 v[26:29], v[156:159], v[182:185], v[26:29]
	v_mfma_f32_16x16x32_bf16 v[14:17], v[148:151], v[190:193], v[14:17]
	v_mfma_f32_16x16x32_bf16 v[10:13], v[156:159], v[190:193], v[10:13]
	v_mfma_f32_16x16x32_bf16 v[62:65], v[152:155], v[168:171], v[62:65]
	v_mfma_f32_16x16x32_bf16 v[58:61], v[160:163], v[168:171], v[58:61]
	v_mfma_f32_16x16x32_bf16 v[46:49], v[152:155], v[176:179], v[46:49]
	v_mfma_f32_16x16x32_bf16 v[42:45], v[160:163], v[176:179], v[42:45]
	v_mfma_f32_16x16x32_bf16 v[30:33], v[152:155], v[186:189], v[30:33]
	v_mfma_f32_16x16x32_bf16 v[26:29], v[160:163], v[186:189], v[26:29]
	v_mfma_f32_16x16x32_bf16 v[14:17], v[152:155], v[194:197], v[14:17]
	v_mfma_f32_16x16x32_bf16 v[10:13], v[160:163], v[194:197], v[10:13]
	s_setprio 0
	s_barrier
	s_add_i32 s46, s46, s55
	v_lshl_add_u64 v[148:149], v[222:223], 0, s[12:13]
	s_mov_b32 m0, s46
	s_nop 0
	global_load_lds_dwordx4 v[148:149], off
	v_lshl_add_u64 v[148:149], v[224:225], 0, s[12:13]
	s_add_i32 m0, s46, 0x2000
	s_nop 0
	global_load_lds_dwordx4 v[148:149], off
	s_waitcnt vmcnt(6)
	s_barrier
	s_setprio 1
	v_mfma_f32_16x16x32_bf16 v[54:57], v[198:201], v[164:167], v[54:57]
	v_mfma_f32_16x16x32_bf16 v[50:53], v[206:209], v[164:167], v[50:53]
	v_mfma_f32_16x16x32_bf16 v[38:41], v[198:201], v[172:175], v[38:41]
	v_mfma_f32_16x16x32_bf16 v[34:37], v[206:209], v[172:175], v[34:37]
	v_mfma_f32_16x16x32_bf16 v[22:25], v[198:201], v[182:185], v[22:25]
	v_mfma_f32_16x16x32_bf16 v[18:21], v[206:209], v[182:185], v[18:21]
	v_mfma_f32_16x16x32_bf16 v[6:9], v[198:201], v[190:193], v[6:9]
	v_mfma_f32_16x16x32_bf16 v[2:5], v[206:209], v[190:193], v[2:5]
	v_mfma_f32_16x16x32_bf16 v[54:57], v[202:205], v[168:171], v[54:57]
	v_mfma_f32_16x16x32_bf16 v[50:53], v[210:213], v[168:171], v[50:53]
	v_mfma_f32_16x16x32_bf16 v[38:41], v[202:205], v[176:179], v[38:41]
	v_mfma_f32_16x16x32_bf16 v[34:37], v[210:213], v[176:179], v[34:37]
	v_mfma_f32_16x16x32_bf16 v[22:25], v[202:205], v[186:189], v[22:25]
	v_mfma_f32_16x16x32_bf16 v[18:21], v[210:213], v[186:189], v[18:21]
	v_mfma_f32_16x16x32_bf16 v[6:9], v[202:205], v[194:197], v[6:9]
	v_mfma_f32_16x16x32_bf16 v[2:5], v[210:213], v[194:197], v[2:5]
	s_setprio 0
	s_cmp_ge_i32 s82, s64
	s_mov_b64 s[46:47], s[48:49]
	s_mov_b32 s50, s82
	s_barrier
	s_cbranch_scc0 .LBB0_607
	s_branch .LBB0_594

; #define PG8_STAGE(bufoff, gbase, voff) do { _Pragma("unroll") for (int _i = 0; _i < 2; ++_i) \
;         __builtin_amdgcn_global_load_lds((const unsigned*)((const char*)(gbase) + (voff)[_i]), (LAS unsigned*)(lds + (bufoff) + ldsw + _i * 8192), 16, 0, 0); } while (0)
; #define STG_A(bufoff, kb, h, usen) do { if constexpr (GATHER) { unsigned o_[2] = {(usen) ? noff[h][0] : coff[h][0], (usen) ? noff[h][1] : coff[h][1]}; PG8_STAGE(bufoff, (const char*)A + (kb), o_); } \
;         else { PG8_STAGE(bufoff, ((usen) ? nA : cA) + (kb) + (size_t)(h) * hstep, voffA); } } while (0)
; #define PG8_LDA(dst, b, h) do { _Pragma("unroll") for (int m = 0; m < 4; ++m) _Pragma("unroll") for (int k = 0; k < 2; ++k) dst[m][k] = *(const LAS bf16x8*)(lds + PG8_SA(b, h) + aoff + m * 2048 + k * 1024); } while (0)
; #define PG8_LDB(dst, b, h) do { _Pragma("unroll") for (int n = 0; n < 2; ++n) _Pragma("unroll") for (int k = 0; k < 2; ++k) dst[n][k] = *(const LAS bf16x8*)(lds + PG8_SB(b, h) + boff + n * 2048 + k * 1024); } while (0)
; #define PG8_MMA(ai, bj, At, Bt_) do { __builtin_amdgcn_s_setprio(1); _Pragma("unroll") for (int m = 0; m < 4; ++m) _Pragma("unroll") for (int n = 0; n < 2; ++n) _Pragma("unroll") for (int k = 0; k < 2; ++k) \
;         acc[ai][bj][m][n] = __builtin_amdgcn_mfma_f32_16x16x32_bf16(Bt_[n][k], At[m][k], acc[ai][bj][m][n], 0, 0, 0); __builtin_amdgcn_s_setprio(0); } while (0)
; #define PG8_WAIT_L(n) asm volatile("s_waitcnt lgkmcnt(" #n ")" ::: "memory")
; #define PG8_BAR __builtin_amdgcn_s_barrier()
; #define PG8_SCHED __builtin_amdgcn_sched_barrier(0)
; template <class Epi, bool GATHER = false>
; __device__ __forceinline__ void gemm_phase(LAS unsigned char* lds, const bf16_t* A, const bf16_t* Bt, const int K_, const Sched& S, const Epi& E, const int* gidx = nullptr) {
;     ...
;             PG8_LDB(B0, 0, 0); PG8_SCHED; PG8_LDA(At, 0, 0); STG_A(PG8_SA(1, 1), k1, 1, false);
;             PG8_WAIT_L(8); PG8_BAR; PG8_WAIT_L(0); PG8_MMA(0, 0, At, B0); PG8_BAR; PG8_SCHED;
;             PG8_LDB(B1, 0, 1); PG8_STAGE(PG8_SB(0, 0), b2, voffA);
;             PG8_BAR; PG8_WAIT_L(0); PG8_MMA(0, 1, At, B1); PG8_BAR;
;             PG8_LDA(At, 0, 1); STG_A(PG8_SA(0, 0), k2, 0, last);
;             PG8_BAR; PG8_WAIT_L(0); PG8_MMA(1, 0, At, B0); PG8_BAR; PG8_SCHED;
.LBB0_700:
	s_add_i32 s31, s22, 2
	s_add_u32 s20, s18, 0x100
	s_addc_u32 s21, s19, 0
	s_add_u32 s33, s51, s18
	s_addc_u32 s23, s52, s19
	s_add_i32 s53, 0, 0x10000
	v_add_u32_e32 v156, s53, v141
	ds_read_b128 v[144:147], v156
	ds_read_b128 v[148:151], v156 offset:1024
	ds_read_b128 v[152:155], v156 offset:2048
	ds_read_b128 v[156:159], v156 offset:3072
	s_add_i32 s56, s53, s35
	s_add_i32 m0, s37, 0xc000
	s_add_i32 s54, s37, 0xe000
	s_add_i32 s55, 0, 0x14000
	s_add_i32 s57, s56, 0x2000
	s_cmp_eq_u32 s44, s22
	s_cselect_b32 s22, s4, s33
	s_cselect_b32 s23, s5, s23
	s_cselect_b32 s33, 0, s21
	s_cselect_b32 s53, 0, s20
	v_lshl_add_u64 v[168:169], v[136:137], 0, s[18:19]
	ds_read_b128 v[160:163], v143
	ds_read_b128 v[164:167], v143 offset:1024
	ds_read_b128 v[188:191], v143 offset:2048
	ds_read_b128 v[192:195], v143 offset:3072
	ds_read_b128 v[196:199], v143 offset:4096
	ds_read_b128 v[200:203], v143 offset:5120
	ds_read_b128 v[204:207], v143 offset:6144
	ds_read_b128 v[208:211], v143 offset:7168
	global_load_lds_dwordx4 v[168:169], off
	v_lshl_add_u64 v[168:169], v[138:139], 0, s[18:19]
	s_mov_b32 m0, s54
	s_nop 0
	global_load_lds_dwordx4 v[168:169], off
	s_waitcnt lgkmcnt(8)
	s_barrier
	s_waitcnt lgkmcnt(0)
	s_setprio 1
	v_mfma_f32_16x16x32_bf16 v[126:129], v[144:147], v[160:163], v[126:129]
	v_mfma_f32_16x16x32_bf16 v[122:125], v[152:155], v[160:163], v[122:125]
	v_mfma_f32_16x16x32_bf16 v[108:111], v[144:147], v[188:191], v[108:111]
	v_mfma_f32_16x16x32_bf16 v[104:107], v[152:155], v[188:191], v[104:107]
	v_mfma_f32_16x16x32_bf16 v[92:95], v[144:147], v[196:199], v[92:95]
	v_mfma_f32_16x16x32_bf16 v[88:91], v[152:155], v[196:199], v[88:91]
	v_mfma_f32_16x16x32_bf16 v[76:79], v[144:147], v[204:207], v[76:79]
	v_mfma_f32_16x16x32_bf16 v[72:75], v[152:155], v[204:207], v[72:75]
	v_mfma_f32_16x16x32_bf16 v[126:129], v[148:151], v[164:167], v[126:129]
	v_mfma_f32_16x16x32_bf16 v[122:125], v[156:159], v[164:167], v[122:125]
	v_mfma_f32_16x16x32_bf16 v[108:111], v[148:151], v[192:195], v[108:111]
	v_mfma_f32_16x16x32_bf16 v[104:107], v[156:159], v[192:195], v[104:107]
	v_mfma_f32_16x16x32_bf16 v[92:95], v[148:151], v[200:203], v[92:95]
	v_mfma_f32_16x16x32_bf16 v[88:91], v[156:159], v[200:203], v[88:91]
	v_mfma_f32_16x16x32_bf16 v[76:79], v[148:151], v[208:211], v[76:79]
	v_mfma_f32_16x16x32_bf16 v[72:75], v[156:159], v[208:211], v[72:75]
	s_setprio 0
	s_barrier
	v_add_u32_e32 v168, s55, v141
	s_mov_b32 m0, s56
	ds_read_b128 v[212:215], v168
	ds_read_b128 v[216:219], v168 offset:1024
	ds_read_b128 v[220:223], v168 offset:2048
	ds_read_b128 v[224:227], v168 offset:3072
	v_lshl_add_u64 v[168:169], s[22:23], 0, v[112:113]
	global_load_lds_dwordx4 v[168:169], off
	v_lshl_add_u64 v[228:229], s[22:23], 0, v[130:131]
	s_mov_b32 m0, s57
	s_nop 0
	global_load_lds_dwordx4 v[228:229], off
	s_barrier
	s_waitcnt lgkmcnt(0)
	s_setprio 1
	v_mfma_f32_16x16x32_bf16 v[118:121], v[212:215], v[160:163], v[118:121]
	v_mfma_f32_16x16x32_bf16 v[114:117], v[220:223], v[160:163], v[114:117]
	v_mfma_f32_16x16x32_bf16 v[100:103], v[212:215], v[188:191], v[100:103]
	v_mfma_f32_16x16x32_bf16 v[96:99], v[220:223], v[188:191], v[96:99]
	v_mfma_f32_16x16x32_bf16 v[84:87], v[212:215], v[196:199], v[84:87]
	v_mfma_f32_16x16x32_bf16 v[80:83], v[220:223], v[196:199], v[80:83]
	v_mfma_f32_16x16x32_bf16 v[68:71], v[212:215], v[204:207], v[68:71]
	v_mfma_f32_16x16x32_bf16 v[64:67], v[220:223], v[204:207], v[64:67]
	v_mfma_f32_16x16x32_bf16 v[118:121], v[216:219], v[164:167], v[118:121]
	v_mfma_f32_16x16x32_bf16 v[114:117], v[224:227], v[164:167], v[114:117]
	v_mfma_f32_16x16x32_bf16 v[100:103], v[216:219], v[192:195], v[100:103]
	v_mfma_f32_16x16x32_bf16 v[96:99], v[224:227], v[192:195], v[96:99]
	v_mfma_f32_16x16x32_bf16 v[84:87], v[216:219], v[200:203], v[84:87]
	v_mfma_f32_16x16x32_bf16 v[80:83], v[224:227], v[200:203], v[80:83]
	v_mfma_f32_16x16x32_bf16 v[68:71], v[216:219], v[208:211], v[68:71]
	v_mfma_f32_16x16x32_bf16 v[64:67], v[224:227], v[208:211], v[64:67]
	s_setprio 0
	s_cselect_b32 s18, s14, s16
	s_cselect_b32 s19, s15, s17
	s_add_u32 s18, s18, s53
	s_addc_u32 s19, s19, s33
	s_mov_b32 m0, s37
	v_lshl_add_u64 v[230:231], s[18:19], 0, v[112:113]
	s_barrier
	ds_read_b128 v[160:163], v143 offset:16384
	ds_read_b128 v[164:167], v143 offset:17408
	ds_read_b128 v[188:191], v143 offset:18432
	ds_read_b128 v[192:195], v143 offset:19456
	ds_read_b128 v[196:199], v143 offset:20480
	ds_read_b128 v[200:203], v143 offset:21504
	ds_read_b128 v[204:207], v143 offset:22528
	ds_read_b128 v[208:211], v143 offset:23552
	global_load_lds_dwordx4 v[230:231], off
	v_lshl_add_u64 v[232:233], s[18:19], 0, v[130:131]
	s_mov_b32 m0, s38
	s_nop 0
	global_load_lds_dwordx4 v[232:233], off
	s_barrier
	s_waitcnt lgkmcnt(0)
	s_setprio 1
	v_mfma_f32_16x16x32_bf16 v[60:63], v[144:147], v[160:163], v[60:63]
	v_mfma_f32_16x16x32_bf16 v[56:59], v[152:155], v[160:163], v[56:59]
	v_mfma_f32_16x16x32_bf16 v[44:47], v[144:147], v[188:191], v[44:47]
	v_mfma_f32_16x16x32_bf16 v[40:43], v[152:155], v[188:191], v[40:43]
	v_mfma_f32_16x16x32_bf16 v[28:31], v[144:147], v[196:199], v[28:31]
	v_mfma_f32_16x16x32_bf16 v[24:27], v[152:155], v[196:199], v[24:27]
	v_mfma_f32_16x16x32_bf16 v[12:15], v[144:147], v[204:207], v[12:15]
	v_mfma_f32_16x16x32_bf16 v[8:11], v[152:155], v[204:207], v[8:11]
	v_mfma_f32_16x16x32_bf16 v[60:63], v[148:151], v[164:167], v[60:63]
	v_mfma_f32_16x16x32_bf16 v[56:59], v[156:159], v[164:167], v[56:59]
	v_mfma_f32_16x16x32_bf16 v[44:47], v[148:151], v[192:195], v[44:47]
	v_mfma_f32_16x16x32_bf16 v[40:43], v[156:159], v[192:195], v[40:43]
	v_mfma_f32_16x16x32_bf16 v[28:31], v[148:151], v[200:203], v[28:31]
	v_mfma_f32_16x16x32_bf16 v[24:27], v[156:159], v[200:203], v[24:27]
	v_mfma_f32_16x16x32_bf16 v[12:15], v[148:151], v[208:211], v[12:15]
	v_mfma_f32_16x16x32_bf16 v[8:11], v[156:159], v[208:211], v[8:11]
	s_setprio 0
	s_barrier
; #define PG8_STAGE(bufoff, gbase, voff) do { _Pragma("unroll") for (int _i = 0; _i < 2; ++_i) \
;         __builtin_amdgcn_global_load_lds((const unsigned*)((const char*)(gbase) + (voff)[_i]), (LAS unsigned*)(lds + (bufoff) + ldsw + _i * 8192), 16, 0, 0); } while (0)
; #define STG_A(bufoff, kb, h, usen) do { if constexpr (GATHER) { unsigned o_[2] = {(usen) ? noff[h][0] : coff[h][0], (usen) ? noff[h][1] : coff[h][1]}; PG8_STAGE(bufoff, (const char*)A + (kb), o_); } \
;         else { PG8_STAGE(bufoff, ((usen) ? nA : cA) + (kb) + (size_t)(h) * hstep, voffA); } } while (0)
; #define PG8_LDA(dst, b, h) do { _Pragma("unroll") for (int m = 0; m < 4; ++m) _Pragma("unroll") for (int k = 0; k < 2; ++k) dst[m][k] = *(const LAS bf16x8*)(lds + PG8_SA(b, h) + aoff + m * 2048 + k * 1024); } while (0)
; #define PG8_LDB(dst, b, h) do { _Pragma("unroll") for (int n = 0; n < 2; ++n) _Pragma("unroll") for (int k = 0; k < 2; ++k) dst[n][k] = *(const LAS bf16x8*)(lds + PG8_SB(b, h) + boff + n * 2048 + k * 1024); } while (0)
; #define PG8_MMA(ai, bj, At, Bt_) do { __builtin_amdgcn_s_setprio(1); _Pragma("unroll") for (int m = 0; m < 4; ++m) _Pragma("unroll") for (int n = 0; n < 2; ++n) _Pragma("unroll") for (int k = 0; k < 2; ++k) \
;         acc[ai][bj][m][n] = __builtin_amdgcn_mfma_f32_16x16x32_bf16(Bt_[n][k], At[m][k], acc[ai][bj][m][n], 0, 0, 0); __builtin_amdgcn_s_setprio(0); } while (0)
; #define PG8_WAIT_V(n) asm volatile("s_waitcnt vmcnt(" #n ")" ::: "memory")
; #define PG8_WAIT_L(n) asm volatile("s_waitcnt lgkmcnt(" #n ")" ::: "memory")
; #define PG8_BAR __builtin_amdgcn_s_barrier()
; #define PG8_SCHED __builtin_amdgcn_sched_barrier(0)
; template <class Epi, bool GATHER = false>
; __device__ __forceinline__ void gemm_phase(LAS unsigned char* lds, const bf16_t* A, const bf16_t* Bt, const int K_, const Sched& S, const Epi& E, const int* gidx = nullptr) {
;     ...
;             PG8_STAGE(PG8_SB(0, 1), b2 + hstep, voffA);
;             PG8_WAIT_V(6); PG8_BAR; PG8_MMA(1, 1, At, B1); PG8_BAR;
;             PG8_LDB(B0, 1, 0); PG8_SCHED; PG8_LDA(At, 1, 0); STG_A(PG8_SA(0, 1), k2, 1, last);
;             PG8_WAIT_L(8); PG8_BAR; PG8_WAIT_L(0); PG8_MMA(0, 0, At, B0); PG8_BAR; PG8_SCHED;
;             PG8_LDB(B1, 1, 1); PG8_STAGE(PG8_SB(1, 0), b3, voffA);
	s_add_u32 s22, s22, s6
	s_addc_u32 s23, s23, s7
	s_add_i32 s33, s55, s35
	v_lshl_add_u64 v[234:235], s[22:23], 0, v[112:113]
	s_mov_b32 m0, s33
	v_lshl_add_u64 v[236:237], s[22:23], 0, v[130:131]
	global_load_lds_dwordx4 v[234:235], off
	s_add_i32 m0, s33, 0x2000
	s_nop 0
	global_load_lds_dwordx4 v[236:237], off
	s_waitcnt vmcnt(6)
	s_barrier
	s_setprio 1
	v_mfma_f32_16x16x32_bf16 v[52:55], v[212:215], v[160:163], v[52:55]
	v_mfma_f32_16x16x32_bf16 v[48:51], v[220:223], v[160:163], v[48:51]
	v_mfma_f32_16x16x32_bf16 v[36:39], v[212:215], v[188:191], v[36:39]
	v_mfma_f32_16x16x32_bf16 v[32:35], v[220:223], v[188:191], v[32:35]
	v_mfma_f32_16x16x32_bf16 v[20:23], v[212:215], v[196:199], v[20:23]
	v_mfma_f32_16x16x32_bf16 v[16:19], v[220:223], v[196:199], v[16:19]
	v_mfma_f32_16x16x32_bf16 v[4:7], v[212:215], v[204:207], v[4:7]
	v_mfma_f32_16x16x32_bf16 v[0:3], v[220:223], v[204:207], v[0:3]
	v_mfma_f32_16x16x32_bf16 v[52:55], v[216:219], v[164:167], v[52:55]
	v_mfma_f32_16x16x32_bf16 v[48:51], v[224:227], v[164:167], v[48:51]
	v_mfma_f32_16x16x32_bf16 v[36:39], v[216:219], v[192:195], v[36:39]
	v_mfma_f32_16x16x32_bf16 v[32:35], v[224:227], v[192:195], v[32:35]
	v_mfma_f32_16x16x32_bf16 v[20:23], v[216:219], v[200:203], v[20:23]
	v_mfma_f32_16x16x32_bf16 v[16:19], v[224:227], v[200:203], v[16:19]
	v_mfma_f32_16x16x32_bf16 v[4:7], v[216:219], v[208:211], v[4:7]
	v_mfma_f32_16x16x32_bf16 v[0:3], v[224:227], v[208:211], v[0:3]
	s_setprio 0
	s_add_i32 s22, 0, 0x18000
	v_add_u32_e32 v156, s22, v141
	s_barrier
	ds_read_b128 v[144:147], v156
	ds_read_b128 v[148:151], v156 offset:1024
	ds_read_b128 v[152:155], v156 offset:2048
	ds_read_b128 v[156:159], v156 offset:3072
	s_add_u32 s18, s18, s6
	s_addc_u32 s19, s19, s7
	s_mov_b32 m0, s39
	v_lshl_add_u64 v[212:213], s[18:19], 0, v[112:113]
	ds_read_b128 v[160:163], v143 offset:32768
	ds_read_b128 v[164:167], v143 offset:33792
	ds_read_b128 v[188:191], v143 offset:34816
	ds_read_b128 v[192:195], v143 offset:35840
	ds_read_b128 v[196:199], v143 offset:36864
	ds_read_b128 v[200:203], v143 offset:37888
	ds_read_b128 v[204:207], v143 offset:38912
	ds_read_b128 v[208:211], v143 offset:39936
	global_load_lds_dwordx4 v[212:213], off
	v_lshl_add_u64 v[212:213], s[18:19], 0, v[130:131]
	s_mov_b32 m0, s40
	s_nop 0
	global_load_lds_dwordx4 v[212:213], off
	s_waitcnt lgkmcnt(8)
	s_barrier
	s_waitcnt lgkmcnt(0)
	s_setprio 1
	v_mfma_f32_16x16x32_bf16 v[126:129], v[144:147], v[160:163], v[126:129]
	v_mfma_f32_16x16x32_bf16 v[122:125], v[152:155], v[160:163], v[122:125]
	v_mfma_f32_16x16x32_bf16 v[108:111], v[144:147], v[188:191], v[108:111]
	v_mfma_f32_16x16x32_bf16 v[104:107], v[152:155], v[188:191], v[104:107]
	v_mfma_f32_16x16x32_bf16 v[92:95], v[144:147], v[196:199], v[92:95]
	v_mfma_f32_16x16x32_bf16 v[88:91], v[152:155], v[196:199], v[88:91]
	v_mfma_f32_16x16x32_bf16 v[76:79], v[144:147], v[204:207], v[76:79]
	v_mfma_f32_16x16x32_bf16 v[72:75], v[152:155], v[204:207], v[72:75]
	v_mfma_f32_16x16x32_bf16 v[126:129], v[148:151], v[164:167], v[126:129]
	v_mfma_f32_16x16x32_bf16 v[122:125], v[156:159], v[164:167], v[122:125]
	v_mfma_f32_16x16x32_bf16 v[108:111], v[148:151], v[192:195], v[108:111]
	v_mfma_f32_16x16x32_bf16 v[104:107], v[156:159], v[192:195], v[104:107]
	v_mfma_f32_16x16x32_bf16 v[92:95], v[148:151], v[200:203], v[92:95]
	v_mfma_f32_16x16x32_bf16 v[88:91], v[156:159], v[200:203], v[88:91]
	v_mfma_f32_16x16x32_bf16 v[76:79], v[148:151], v[208:211], v[76:79]
	v_mfma_f32_16x16x32_bf16 v[72:75], v[156:159], v[208:211], v[72:75]
	s_setprio 0
	s_barrier
	s_add_i32 s18, 0, 0x1c000
	s_add_i32 s19, s22, s35
	v_add_u32_e32 v187, s18, v141
	v_lshl_add_u64 v[168:169], v[168:169], 0, s[2:3]
	s_mov_b32 m0, s19
	ds_read_b128 v[212:215], v187
	ds_read_b128 v[216:219], v187 offset:1024
	ds_read_b128 v[220:223], v187 offset:2048
	ds_read_b128 v[224:227], v187 offset:3072
	global_load_lds_dwordx4 v[168:169], off
	v_lshl_add_u64 v[168:169], v[228:229], 0, s[2:3]
	s_add_i32 m0, s19, 0x2000
	s_nop 0
	global_load_lds_dwordx4 v[168:169], off
	s_barrier
; #define PG8_STAGE(bufoff, gbase, voff) do { _Pragma("unroll") for (int _i = 0; _i < 2; ++_i) \
;         __builtin_amdgcn_global_load_lds((const unsigned*)((const char*)(gbase) + (voff)[_i]), (LAS unsigned*)(lds + (bufoff) + ldsw + _i * 8192), 16, 0, 0); } while (0)
; #define STG_A(bufoff, kb, h, usen) do { if constexpr (GATHER) { unsigned o_[2] = {(usen) ? noff[h][0] : coff[h][0], (usen) ? noff[h][1] : coff[h][1]}; PG8_STAGE(bufoff, (const char*)A + (kb), o_); } \
;         else { PG8_STAGE(bufoff, ((usen) ? nA : cA) + (kb) + (size_t)(h) * hstep, voffA); } } while (0)
; #define PG8_LDA(dst, b, h) do { _Pragma("unroll") for (int m = 0; m < 4; ++m) _Pragma("unroll") for (int k = 0; k < 2; ++k) dst[m][k] = *(const LAS bf16x8*)(lds + PG8_SA(b, h) + aoff + m * 2048 + k * 1024); } while (0)
; #define PG8_MMA(ai, bj, At, Bt_) do { __builtin_amdgcn_s_setprio(1); _Pragma("unroll") for (int m = 0; m < 4; ++m) _Pragma("unroll") for (int n = 0; n < 2; ++n) _Pragma("unroll") for (int k = 0; k < 2; ++k) \
;         acc[ai][bj][m][n] = __builtin_amdgcn_mfma_f32_16x16x32_bf16(Bt_[n][k], At[m][k], acc[ai][bj][m][n], 0, 0, 0); __builtin_amdgcn_s_setprio(0); } while (0)
; #define PG8_WAIT_V(n) asm volatile("s_waitcnt vmcnt(" #n ")" ::: "memory")
; #define PG8_WAIT_L(n) asm volatile("s_waitcnt lgkmcnt(" #n ")" ::: "memory")
; #define PG8_BAR __builtin_amdgcn_s_barrier()
; #define PG8_SCHED __builtin_amdgcn_sched_barrier(0)
; template <class Epi, bool GATHER = false>
; __device__ __forceinline__ void gemm_phase(LAS unsigned char* lds, const bf16_t* A, const bf16_t* Bt, const int K_, const Sched& S, const Epi& E, const int* gidx = nullptr) {
;     ...
;             PG8_BAR; PG8_WAIT_L(0); PG8_MMA(0, 1, At, B1); PG8_BAR;
;             PG8_LDA(At, 1, 1); STG_A(PG8_SA(1, 0), k3, 0, last);
;             PG8_BAR; PG8_WAIT_L(0); PG8_MMA(1, 0, At, B0); PG8_BAR; PG8_SCHED;
;             PG8_STAGE(PG8_SB(1, 1), b3 + hstep, voffA);
;             PG8_WAIT_V(6); PG8_BAR; PG8_MMA(1, 1, At, B1); PG8_BAR;
;         }
	s_waitcnt lgkmcnt(0)
	s_setprio 1
	v_mfma_f32_16x16x32_bf16 v[118:121], v[212:215], v[160:163], v[118:121]
	v_mfma_f32_16x16x32_bf16 v[114:117], v[220:223], v[160:163], v[114:117]
	v_mfma_f32_16x16x32_bf16 v[100:103], v[212:215], v[188:191], v[100:103]
	v_mfma_f32_16x16x32_bf16 v[96:99], v[220:223], v[188:191], v[96:99]
	v_mfma_f32_16x16x32_bf16 v[84:87], v[212:215], v[196:199], v[84:87]
	v_mfma_f32_16x16x32_bf16 v[80:83], v[220:223], v[196:199], v[80:83]
	v_mfma_f32_16x16x32_bf16 v[68:71], v[212:215], v[204:207], v[68:71]
	v_mfma_f32_16x16x32_bf16 v[64:67], v[220:223], v[204:207], v[64:67]
	v_mfma_f32_16x16x32_bf16 v[118:121], v[216:219], v[164:167], v[118:121]
	v_mfma_f32_16x16x32_bf16 v[114:117], v[224:227], v[164:167], v[114:117]
	v_mfma_f32_16x16x32_bf16 v[100:103], v[216:219], v[192:195], v[100:103]
	v_mfma_f32_16x16x32_bf16 v[96:99], v[224:227], v[192:195], v[96:99]
	v_mfma_f32_16x16x32_bf16 v[84:87], v[216:219], v[200:203], v[84:87]
	v_mfma_f32_16x16x32_bf16 v[80:83], v[224:227], v[200:203], v[80:83]
	v_mfma_f32_16x16x32_bf16 v[68:71], v[216:219], v[208:211], v[68:71]
	v_mfma_f32_16x16x32_bf16 v[64:67], v[224:227], v[208:211], v[64:67]
	s_setprio 0
	s_mov_b32 m0, s42
	v_lshl_add_u64 v[168:169], v[230:231], 0, s[2:3]
	s_barrier
	ds_read_b128 v[160:163], v143 offset:49152
	ds_read_b128 v[164:167], v143 offset:50176
	ds_read_b128 v[188:191], v143 offset:51200
	ds_read_b128 v[192:195], v143 offset:52224
	ds_read_b128 v[196:199], v143 offset:53248
	ds_read_b128 v[200:203], v143 offset:54272
	ds_read_b128 v[204:207], v143 offset:55296
	ds_read_b128 v[208:211], v143 offset:56320
	global_load_lds_dwordx4 v[168:169], off
	v_lshl_add_u64 v[168:169], v[232:233], 0, s[2:3]
	s_mov_b32 m0, s43
	s_nop 0
	global_load_lds_dwordx4 v[168:169], off
	s_barrier
	s_waitcnt lgkmcnt(0)
	s_setprio 1
	v_mfma_f32_16x16x32_bf16 v[60:63], v[144:147], v[160:163], v[60:63]
	v_mfma_f32_16x16x32_bf16 v[56:59], v[152:155], v[160:163], v[56:59]
	v_mfma_f32_16x16x32_bf16 v[44:47], v[144:147], v[188:191], v[44:47]
	v_mfma_f32_16x16x32_bf16 v[40:43], v[152:155], v[188:191], v[40:43]
	v_mfma_f32_16x16x32_bf16 v[28:31], v[144:147], v[196:199], v[28:31]
	v_mfma_f32_16x16x32_bf16 v[24:27], v[152:155], v[196:199], v[24:27]
	v_mfma_f32_16x16x32_bf16 v[12:15], v[144:147], v[204:207], v[12:15]
	v_mfma_f32_16x16x32_bf16 v[8:11], v[152:155], v[204:207], v[8:11]
	v_mfma_f32_16x16x32_bf16 v[60:63], v[148:151], v[164:167], v[60:63]
	v_mfma_f32_16x16x32_bf16 v[56:59], v[156:159], v[164:167], v[56:59]
	v_mfma_f32_16x16x32_bf16 v[44:47], v[148:151], v[192:195], v[44:47]
	v_mfma_f32_16x16x32_bf16 v[40:43], v[156:159], v[192:195], v[40:43]
	v_mfma_f32_16x16x32_bf16 v[28:31], v[148:151], v[200:203], v[28:31]
	v_mfma_f32_16x16x32_bf16 v[24:27], v[156:159], v[200:203], v[24:27]
	v_mfma_f32_16x16x32_bf16 v[12:15], v[148:151], v[208:211], v[12:15]
	v_mfma_f32_16x16x32_bf16 v[8:11], v[156:159], v[208:211], v[8:11]
	s_setprio 0
	s_barrier
	s_add_i32 s18, s18, s35
	v_lshl_add_u64 v[144:145], v[234:235], 0, s[2:3]
	s_mov_b32 m0, s18
	s_nop 0
	global_load_lds_dwordx4 v[144:145], off
	v_lshl_add_u64 v[144:145], v[236:237], 0, s[2:3]
	s_add_i32 m0, s18, 0x2000
	s_nop 0
	global_load_lds_dwordx4 v[144:145], off
	s_waitcnt vmcnt(6)
	s_barrier
	s_setprio 1
	v_mfma_f32_16x16x32_bf16 v[52:55], v[212:215], v[160:163], v[52:55]
	v_mfma_f32_16x16x32_bf16 v[48:51], v[220:223], v[160:163], v[48:51]
	v_mfma_f32_16x16x32_bf16 v[36:39], v[212:215], v[188:191], v[36:39]
	v_mfma_f32_16x16x32_bf16 v[32:35], v[220:223], v[188:191], v[32:35]
	v_mfma_f32_16x16x32_bf16 v[20:23], v[212:215], v[196:199], v[20:23]
	v_mfma_f32_16x16x32_bf16 v[16:19], v[220:223], v[196:199], v[16:19]
	v_mfma_f32_16x16x32_bf16 v[4:7], v[212:215], v[204:207], v[4:7]
	v_mfma_f32_16x16x32_bf16 v[0:3], v[220:223], v[204:207], v[0:3]
	v_mfma_f32_16x16x32_bf16 v[52:55], v[216:219], v[164:167], v[52:55]
	v_mfma_f32_16x16x32_bf16 v[48:51], v[224:227], v[164:167], v[48:51]
	v_mfma_f32_16x16x32_bf16 v[36:39], v[216:219], v[192:195], v[36:39]
	v_mfma_f32_16x16x32_bf16 v[32:35], v[224:227], v[192:195], v[32:35]
	v_mfma_f32_16x16x32_bf16 v[20:23], v[216:219], v[200:203], v[20:23]
	v_mfma_f32_16x16x32_bf16 v[16:19], v[224:227], v[200:203], v[16:19]
	v_mfma_f32_16x16x32_bf16 v[4:7], v[216:219], v[208:211], v[4:7]
	v_mfma_f32_16x16x32_bf16 v[0:3], v[224:227], v[208:211], v[0:3]
	s_setprio 0
	s_cmp_ge_i32 s31, s41
	s_mov_b64 s[18:19], s[20:21]
	s_mov_b32 s22, s31
	s_barrier
	s_cbranch_scc0 .LBB0_700
	v_readlane_b32 s52, v255, 34
	v_readlane_b32 s53, v255, 35
	s_branch .LBB0_687

; #define PG8_STAGE(bufoff, gbase, voff) do { _Pragma("unroll") for (int _i = 0; _i < 2; ++_i) \
;         __builtin_amdgcn_global_load_lds((const unsigned*)((const char*)(gbase) + (voff)[_i]), (LAS unsigned*)(lds + (bufoff) + ldsw + _i * 8192), 16, 0, 0); } while (0)
; #define STG_A(bufoff, kb, h, usen) do { if constexpr (GATHER) { unsigned o_[2] = {(usen) ? noff[h][0] : coff[h][0], (usen) ? noff[h][1] : coff[h][1]}; PG8_STAGE(bufoff, (const char*)A + (kb), o_); } \
;         else { PG8_STAGE(bufoff, ((usen) ? nA : cA) + (kb) + (size_t)(h) * hstep, voffA); } } while (0)
; #define PG8_LDA(dst, b, h) do { _Pragma("unroll") for (int m = 0; m < 4; ++m) _Pragma("unroll") for (int k = 0; k < 2; ++k) dst[m][k] = *(const LAS bf16x8*)(lds + PG8_SA(b, h) + aoff + m * 2048 + k * 1024); } while (0)
; #define PG8_LDB(dst, b, h) do { _Pragma("unroll") for (int n = 0; n < 2; ++n) _Pragma("unroll") for (int k = 0; k < 2; ++k) dst[n][k] = *(const LAS bf16x8*)(lds + PG8_SB(b, h) + boff + n * 2048 + k * 1024); } while (0)
; #define PG8_MMA(ai, bj, At, Bt_) do { __builtin_amdgcn_s_setprio(1); _Pragma("unroll") for (int m = 0; m < 4; ++m) _Pragma("unroll") for (int n = 0; n < 2; ++n) _Pragma("unroll") for (int k = 0; k < 2; ++k) \
;         acc[ai][bj][m][n] = __builtin_amdgcn_mfma_f32_16x16x32_bf16(Bt_[n][k], At[m][k], acc[ai][bj][m][n], 0, 0, 0); __builtin_amdgcn_s_setprio(0); } while (0)
; #define PG8_WAIT_L(n) asm volatile("s_waitcnt lgkmcnt(" #n ")" ::: "memory")
; #define PG8_BAR __builtin_amdgcn_s_barrier()
; #define PG8_SCHED __builtin_amdgcn_sched_barrier(0)
; template <class Epi, bool GATHER = false>
; __device__ __forceinline__ void gemm_phase(LAS unsigned char* lds, const bf16_t* A, const bf16_t* Bt, const int K_, const Sched& S, const Epi& E, const int* gidx = nullptr) {
;     ...
;             PG8_LDB(B0, 0, 0); PG8_SCHED; PG8_LDA(At, 0, 0); STG_A(PG8_SA(1, 1), k1, 1, false);
;             PG8_WAIT_L(8); PG8_BAR; PG8_WAIT_L(0); PG8_MMA(0, 0, At, B0); PG8_BAR; PG8_SCHED;
;             PG8_LDB(B1, 0, 1); PG8_STAGE(PG8_SB(0, 0), b2, voffA);
;             PG8_BAR; PG8_WAIT_L(0); PG8_MMA(0, 1, At, B1); PG8_BAR;
;             PG8_LDA(At, 0, 1); STG_A(PG8_SA(0, 0), k2, 0, last);
;             PG8_BAR; PG8_WAIT_L(0); PG8_MMA(1, 0, At, B0); PG8_BAR; PG8_SCHED;
.LBB0_857:
	s_add_i32 s31, s20, 2
	s_add_u32 s18, s16, 0x100
	s_addc_u32 s19, s17, 0
	s_add_u32 s33, s41, s16
	s_addc_u32 s21, s43, s17
	s_add_i32 s44, 0, 0x10000
	v_add_u32_e32 v112, s44, v162
	ds_read_b128 v[134:137], v112
	ds_read_b128 v[138:141], v112 offset:1024
	ds_read_b128 v[142:145], v112 offset:2048
	ds_read_b128 v[164:167], v112 offset:3072
	s_add_i32 s56, s44, s23
	s_add_i32 m0, s34, 0xc000
	s_add_i32 s45, s34, 0xe000
	s_add_i32 s55, 0, 0x14000
	s_add_i32 s57, s56, 0x2000
	s_cmp_eq_u32 s50, s20
	s_cselect_b32 s20, s4, s33
	s_cselect_b32 s21, s5, s21
	s_cselect_b32 s33, 0, s19
	s_cselect_b32 s44, 0, s18
	v_lshl_add_u64 v[146:147], v[114:115], 0, s[16:17]
	ds_read_b128 v[188:191], v163
	ds_read_b128 v[192:195], v163 offset:1024
	ds_read_b128 v[196:199], v163 offset:2048
	ds_read_b128 v[200:203], v163 offset:3072
	ds_read_b128 v[204:207], v163 offset:4096
	ds_read_b128 v[208:211], v163 offset:5120
	ds_read_b128 v[212:215], v163 offset:6144
	ds_read_b128 v[216:219], v163 offset:7168
	global_load_lds_dwordx4 v[146:147], off
	v_lshl_add_u64 v[146:147], v[132:133], 0, s[16:17]
	s_mov_b32 m0, s45
	s_nop 0
	global_load_lds_dwordx4 v[146:147], off
	s_waitcnt lgkmcnt(8)
	s_barrier
	s_waitcnt lgkmcnt(0)
	s_setprio 1
	v_mfma_f32_16x16x32_bf16 v[128:131], v[134:137], v[188:191], v[128:131]
	v_mfma_f32_16x16x32_bf16 v[124:127], v[142:145], v[188:191], v[124:127]
	v_mfma_f32_16x16x32_bf16 v[108:111], v[134:137], v[196:199], v[108:111]
	v_mfma_f32_16x16x32_bf16 v[104:107], v[142:145], v[196:199], v[104:107]
	v_mfma_f32_16x16x32_bf16 v[92:95], v[134:137], v[204:207], v[92:95]
	v_mfma_f32_16x16x32_bf16 v[88:91], v[142:145], v[204:207], v[88:91]
	v_mfma_f32_16x16x32_bf16 v[76:79], v[134:137], v[212:215], v[76:79]
	v_mfma_f32_16x16x32_bf16 v[72:75], v[142:145], v[212:215], v[72:75]
	v_mfma_f32_16x16x32_bf16 v[128:131], v[138:141], v[192:195], v[128:131]
	v_mfma_f32_16x16x32_bf16 v[124:127], v[164:167], v[192:195], v[124:127]
	v_mfma_f32_16x16x32_bf16 v[108:111], v[138:141], v[200:203], v[108:111]
	v_mfma_f32_16x16x32_bf16 v[104:107], v[164:167], v[200:203], v[104:107]
	v_mfma_f32_16x16x32_bf16 v[92:95], v[138:141], v[208:211], v[92:95]
	v_mfma_f32_16x16x32_bf16 v[88:91], v[164:167], v[208:211], v[88:91]
	v_mfma_f32_16x16x32_bf16 v[76:79], v[138:141], v[216:219], v[76:79]
	v_mfma_f32_16x16x32_bf16 v[72:75], v[164:167], v[216:219], v[72:75]
	s_setprio 0
	s_barrier
	s_mov_b32 m0, s56
	v_add_u32_e32 v112, s55, v162
	v_lshl_add_u64 v[146:147], s[20:21], 0, v[150:151]
	ds_read_b128 v[220:223], v112
	ds_read_b128 v[224:227], v112 offset:1024
	ds_read_b128 v[228:231], v112 offset:2048
	ds_read_b128 v[232:235], v112 offset:3072
	global_load_lds_dwordx4 v[146:147], off
	v_lshl_add_u64 v[168:169], s[20:21], 0, v[148:149]
	s_mov_b32 m0, s57
	s_nop 0
	global_load_lds_dwordx4 v[168:169], off
	s_barrier
	s_waitcnt lgkmcnt(0)
	s_setprio 1
	v_mfma_f32_16x16x32_bf16 v[120:123], v[220:223], v[188:191], v[120:123]
	v_mfma_f32_16x16x32_bf16 v[116:119], v[228:231], v[188:191], v[116:119]
	v_mfma_f32_16x16x32_bf16 v[100:103], v[220:223], v[196:199], v[100:103]
	v_mfma_f32_16x16x32_bf16 v[96:99], v[228:231], v[196:199], v[96:99]
	v_mfma_f32_16x16x32_bf16 v[84:87], v[220:223], v[204:207], v[84:87]
	v_mfma_f32_16x16x32_bf16 v[80:83], v[228:231], v[204:207], v[80:83]
	v_mfma_f32_16x16x32_bf16 v[68:71], v[220:223], v[212:215], v[68:71]
	v_mfma_f32_16x16x32_bf16 v[64:67], v[228:231], v[212:215], v[64:67]
	v_mfma_f32_16x16x32_bf16 v[120:123], v[224:227], v[192:195], v[120:123]
	v_mfma_f32_16x16x32_bf16 v[116:119], v[232:235], v[192:195], v[116:119]
	v_mfma_f32_16x16x32_bf16 v[100:103], v[224:227], v[200:203], v[100:103]
	v_mfma_f32_16x16x32_bf16 v[96:99], v[232:235], v[200:203], v[96:99]
	v_mfma_f32_16x16x32_bf16 v[84:87], v[224:227], v[208:211], v[84:87]
	v_mfma_f32_16x16x32_bf16 v[80:83], v[232:235], v[208:211], v[80:83]
	v_mfma_f32_16x16x32_bf16 v[68:71], v[224:227], v[216:219], v[68:71]
	v_mfma_f32_16x16x32_bf16 v[64:67], v[232:235], v[216:219], v[64:67]
	s_setprio 0
	s_cselect_b32 s16, s12, s14
	s_cselect_b32 s17, s13, s15
	s_add_u32 s16, s16, s44
	s_addc_u32 s17, s17, s33
	s_mov_b32 m0, s34
	v_lshl_add_u64 v[236:237], s[16:17], 0, v[150:151]
	s_barrier
	ds_read_b128 v[188:191], v163 offset:16384
	ds_read_b128 v[192:195], v163 offset:17408
	ds_read_b128 v[196:199], v163 offset:18432
	ds_read_b128 v[200:203], v163 offset:19456
	ds_read_b128 v[204:207], v163 offset:20480
	ds_read_b128 v[208:211], v163 offset:21504
	ds_read_b128 v[212:215], v163 offset:22528
	ds_read_b128 v[216:219], v163 offset:23552
	global_load_lds_dwordx4 v[236:237], off
	v_lshl_add_u64 v[238:239], s[16:17], 0, v[148:149]
	s_mov_b32 m0, s35
	s_nop 0
	global_load_lds_dwordx4 v[238:239], off
	s_barrier
	s_waitcnt lgkmcnt(0)
	s_setprio 1
	v_mfma_f32_16x16x32_bf16 v[60:63], v[134:137], v[188:191], v[60:63]
	v_mfma_f32_16x16x32_bf16 v[56:59], v[142:145], v[188:191], v[56:59]
	v_mfma_f32_16x16x32_bf16 v[44:47], v[134:137], v[196:199], v[44:47]
	v_mfma_f32_16x16x32_bf16 v[40:43], v[142:145], v[196:199], v[40:43]
	v_mfma_f32_16x16x32_bf16 v[28:31], v[134:137], v[204:207], v[28:31]
	v_mfma_f32_16x16x32_bf16 v[24:27], v[142:145], v[204:207], v[24:27]
	v_mfma_f32_16x16x32_bf16 v[12:15], v[134:137], v[212:215], v[12:15]
	v_mfma_f32_16x16x32_bf16 v[8:11], v[142:145], v[212:215], v[8:11]
	v_mfma_f32_16x16x32_bf16 v[60:63], v[138:141], v[192:195], v[60:63]
	v_mfma_f32_16x16x32_bf16 v[56:59], v[164:167], v[192:195], v[56:59]
	v_mfma_f32_16x16x32_bf16 v[44:47], v[138:141], v[200:203], v[44:47]
	v_mfma_f32_16x16x32_bf16 v[40:43], v[164:167], v[200:203], v[40:43]
	v_mfma_f32_16x16x32_bf16 v[28:31], v[138:141], v[208:211], v[28:31]
	v_mfma_f32_16x16x32_bf16 v[24:27], v[164:167], v[208:211], v[24:27]
	v_mfma_f32_16x16x32_bf16 v[12:15], v[138:141], v[216:219], v[12:15]
	v_mfma_f32_16x16x32_bf16 v[8:11], v[164:167], v[216:219], v[8:11]
	s_setprio 0
	s_barrier
; #define PG8_STAGE(bufoff, gbase, voff) do { _Pragma("unroll") for (int _i = 0; _i < 2; ++_i) \
;         __builtin_amdgcn_global_load_lds((const unsigned*)((const char*)(gbase) + (voff)[_i]), (LAS unsigned*)(lds + (bufoff) + ldsw + _i * 8192), 16, 0, 0); } while (0)
; #define STG_A(bufoff, kb, h, usen) do { if constexpr (GATHER) { unsigned o_[2] = {(usen) ? noff[h][0] : coff[h][0], (usen) ? noff[h][1] : coff[h][1]}; PG8_STAGE(bufoff, (const char*)A + (kb), o_); } \
;         else { PG8_STAGE(bufoff, ((usen) ? nA : cA) + (kb) + (size_t)(h) * hstep, voffA); } } while (0)
; #define PG8_LDA(dst, b, h) do { _Pragma("unroll") for (int m = 0; m < 4; ++m) _Pragma("unroll") for (int k = 0; k < 2; ++k) dst[m][k] = *(const LAS bf16x8*)(lds + PG8_SA(b, h) + aoff + m * 2048 + k * 1024); } while (0)
; #define PG8_LDB(dst, b, h) do { _Pragma("unroll") for (int n = 0; n < 2; ++n) _Pragma("unroll") for (int k = 0; k < 2; ++k) dst[n][k] = *(const LAS bf16x8*)(lds + PG8_SB(b, h) + boff + n * 2048 + k * 1024); } while (0)
; #define PG8_MMA(ai, bj, At, Bt_) do { __builtin_amdgcn_s_setprio(1); _Pragma("unroll") for (int m = 0; m < 4; ++m) _Pragma("unroll") for (int n = 0; n < 2; ++n) _Pragma("unroll") for (int k = 0; k < 2; ++k) \
;         acc[ai][bj][m][n] = __builtin_amdgcn_mfma_f32_16x16x32_bf16(Bt_[n][k], At[m][k], acc[ai][bj][m][n], 0, 0, 0); __builtin_amdgcn_s_setprio(0); } while (0)
; #define PG8_WAIT_V(n) asm volatile("s_waitcnt vmcnt(" #n ")" ::: "memory")
; #define PG8_WAIT_L(n) asm volatile("s_waitcnt lgkmcnt(" #n ")" ::: "memory")
; #define PG8_BAR __builtin_amdgcn_s_barrier()
; #define PG8_SCHED __builtin_amdgcn_sched_barrier(0)
; template <class Epi, bool GATHER = false>
; __device__ __forceinline__ void gemm_phase(LAS unsigned char* lds, const bf16_t* A, const bf16_t* Bt, const int K_, const Sched& S, const Epi& E, const int* gidx = nullptr) {
;     ...
;             PG8_STAGE(PG8_SB(0, 1), b2 + hstep, voffA);
;             PG8_WAIT_V(6); PG8_BAR; PG8_MMA(1, 1, At, B1); PG8_BAR;
;             PG8_LDB(B0, 1, 0); PG8_SCHED; PG8_LDA(At, 1, 0); STG_A(PG8_SA(0, 1), k2, 1, last);
;             PG8_WAIT_L(8); PG8_BAR; PG8_WAIT_L(0); PG8_MMA(0, 0, At, B0); PG8_BAR; PG8_SCHED;
;             PG8_LDB(B1, 1, 1); PG8_STAGE(PG8_SB(1, 0), b3, voffA);
	s_add_u32 s20, s20, s0
	s_addc_u32 s21, s21, s1
	s_add_i32 s33, s55, s23
	v_lshl_add_u64 v[240:241], s[20:21], 0, v[150:151]
	s_mov_b32 m0, s33
	v_lshl_add_u64 v[242:243], s[20:21], 0, v[148:149]
	global_load_lds_dwordx4 v[240:241], off
	s_add_i32 m0, s33, 0x2000
	s_nop 0
	global_load_lds_dwordx4 v[242:243], off
	s_waitcnt vmcnt(6)
	s_barrier
	s_setprio 1
	v_mfma_f32_16x16x32_bf16 v[52:55], v[220:223], v[188:191], v[52:55]
	v_mfma_f32_16x16x32_bf16 v[48:51], v[228:231], v[188:191], v[48:51]
	v_mfma_f32_16x16x32_bf16 v[36:39], v[220:223], v[196:199], v[36:39]
	v_mfma_f32_16x16x32_bf16 v[32:35], v[228:231], v[196:199], v[32:35]
	v_mfma_f32_16x16x32_bf16 v[20:23], v[220:223], v[204:207], v[20:23]
	v_mfma_f32_16x16x32_bf16 v[16:19], v[228:231], v[204:207], v[16:19]
	v_mfma_f32_16x16x32_bf16 v[4:7], v[220:223], v[212:215], v[4:7]
	v_mfma_f32_16x16x32_bf16 v[0:3], v[228:231], v[212:215], v[0:3]
	v_mfma_f32_16x16x32_bf16 v[52:55], v[224:227], v[192:195], v[52:55]
	v_mfma_f32_16x16x32_bf16 v[48:51], v[232:235], v[192:195], v[48:51]
	v_mfma_f32_16x16x32_bf16 v[36:39], v[224:227], v[200:203], v[36:39]
	v_mfma_f32_16x16x32_bf16 v[32:35], v[232:235], v[200:203], v[32:35]
	v_mfma_f32_16x16x32_bf16 v[20:23], v[224:227], v[208:211], v[20:23]
	v_mfma_f32_16x16x32_bf16 v[16:19], v[232:235], v[208:211], v[16:19]
	v_mfma_f32_16x16x32_bf16 v[4:7], v[224:227], v[216:219], v[4:7]
	v_mfma_f32_16x16x32_bf16 v[0:3], v[232:235], v[216:219], v[0:3]
	s_setprio 0
	s_add_i32 s20, 0, 0x18000
	v_add_u32_e32 v112, s20, v162
	s_barrier
	ds_read_b128 v[134:137], v112
	ds_read_b128 v[138:141], v112 offset:1024
	ds_read_b128 v[142:145], v112 offset:2048
	ds_read_b128 v[164:167], v112 offset:3072
	s_add_u32 s16, s16, s0
	s_addc_u32 s17, s17, s1
	s_mov_b32 m0, s37
	v_lshl_add_u64 v[220:221], s[16:17], 0, v[150:151]
	ds_read_b128 v[188:191], v163 offset:32768
	ds_read_b128 v[192:195], v163 offset:33792
	ds_read_b128 v[196:199], v163 offset:34816
	ds_read_b128 v[200:203], v163 offset:35840
	ds_read_b128 v[204:207], v163 offset:36864
	ds_read_b128 v[208:211], v163 offset:37888
	ds_read_b128 v[212:215], v163 offset:38912
	ds_read_b128 v[216:219], v163 offset:39936
	global_load_lds_dwordx4 v[220:221], off
	v_lshl_add_u64 v[220:221], s[16:17], 0, v[148:149]
	s_mov_b32 m0, s38
	s_nop 0
	global_load_lds_dwordx4 v[220:221], off
	s_waitcnt lgkmcnt(8)
	s_barrier
	s_waitcnt lgkmcnt(0)
	s_setprio 1
	v_mfma_f32_16x16x32_bf16 v[128:131], v[134:137], v[188:191], v[128:131]
	v_mfma_f32_16x16x32_bf16 v[124:127], v[142:145], v[188:191], v[124:127]
	v_mfma_f32_16x16x32_bf16 v[108:111], v[134:137], v[196:199], v[108:111]
	v_mfma_f32_16x16x32_bf16 v[104:107], v[142:145], v[196:199], v[104:107]
	v_mfma_f32_16x16x32_bf16 v[92:95], v[134:137], v[204:207], v[92:95]
	v_mfma_f32_16x16x32_bf16 v[88:91], v[142:145], v[204:207], v[88:91]
	v_mfma_f32_16x16x32_bf16 v[76:79], v[134:137], v[212:215], v[76:79]
	v_mfma_f32_16x16x32_bf16 v[72:75], v[142:145], v[212:215], v[72:75]
	v_mfma_f32_16x16x32_bf16 v[128:131], v[138:141], v[192:195], v[128:131]
	v_mfma_f32_16x16x32_bf16 v[124:127], v[164:167], v[192:195], v[124:127]
	v_mfma_f32_16x16x32_bf16 v[108:111], v[138:141], v[200:203], v[108:111]
	v_mfma_f32_16x16x32_bf16 v[104:107], v[164:167], v[200:203], v[104:107]
	v_mfma_f32_16x16x32_bf16 v[92:95], v[138:141], v[208:211], v[92:95]
	v_mfma_f32_16x16x32_bf16 v[88:91], v[164:167], v[208:211], v[88:91]
	v_mfma_f32_16x16x32_bf16 v[76:79], v[138:141], v[216:219], v[76:79]
	v_mfma_f32_16x16x32_bf16 v[72:75], v[164:167], v[216:219], v[72:75]
	s_setprio 0
	s_barrier
	s_add_i32 s16, 0, 0x1c000
	s_add_i32 s17, s20, s23
	v_add_u32_e32 v112, s16, v162
	v_lshl_add_u64 v[146:147], v[146:147], 0, s[2:3]
	s_mov_b32 m0, s17
	ds_read_b128 v[220:223], v112
	ds_read_b128 v[224:227], v112 offset:1024
	ds_read_b128 v[228:231], v112 offset:2048
	ds_read_b128 v[232:235], v112 offset:3072
	global_load_lds_dwordx4 v[146:147], off
	v_lshl_add_u64 v[146:147], v[168:169], 0, s[2:3]
	s_add_i32 m0, s17, 0x2000
	s_nop 0
	global_load_lds_dwordx4 v[146:147], off
	s_barrier
; #define PG8_STAGE(bufoff, gbase, voff) do { _Pragma("unroll") for (int _i = 0; _i < 2; ++_i) \
;         __builtin_amdgcn_global_load_lds((const unsigned*)((const char*)(gbase) + (voff)[_i]), (LAS unsigned*)(lds + (bufoff) + ldsw + _i * 8192), 16, 0, 0); } while (0)
; #define STG_A(bufoff, kb, h, usen) do { if constexpr (GATHER) { unsigned o_[2] = {(usen) ? noff[h][0] : coff[h][0], (usen) ? noff[h][1] : coff[h][1]}; PG8_STAGE(bufoff, (const char*)A + (kb), o_); } \
;         else { PG8_STAGE(bufoff, ((usen) ? nA : cA) + (kb) + (size_t)(h) * hstep, voffA); } } while (0)
; #define PG8_LDA(dst, b, h) do { _Pragma("unroll") for (int m = 0; m < 4; ++m) _Pragma("unroll") for (int k = 0; k < 2; ++k) dst[m][k] = *(const LAS bf16x8*)(lds + PG8_SA(b, h) + aoff + m * 2048 + k * 1024); } while (0)
; #define PG8_MMA(ai, bj, At, Bt_) do { __builtin_amdgcn_s_setprio(1); _Pragma("unroll") for (int m = 0; m < 4; ++m) _Pragma("unroll") for (int n = 0; n < 2; ++n) _Pragma("unroll") for (int k = 0; k < 2; ++k) \
;         acc[ai][bj][m][n] = __builtin_amdgcn_mfma_f32_16x16x32_bf16(Bt_[n][k], At[m][k], acc[ai][bj][m][n], 0, 0, 0); __builtin_amdgcn_s_setprio(0); } while (0)
; #define PG8_WAIT_V(n) asm volatile("s_waitcnt vmcnt(" #n ")" ::: "memory")
; #define PG8_WAIT_L(n) asm volatile("s_waitcnt lgkmcnt(" #n ")" ::: "memory")
; #define PG8_BAR __builtin_amdgcn_s_barrier()
; #define PG8_SCHED __builtin_amdgcn_sched_barrier(0)
; template <class Epi, bool GATHER = false>
; __device__ __forceinline__ void gemm_phase(LAS unsigned char* lds, const bf16_t* A, const bf16_t* Bt, const int K_, const Sched& S, const Epi& E, const int* gidx = nullptr) {
;     ...
;             PG8_BAR; PG8_WAIT_L(0); PG8_MMA(0, 1, At, B1); PG8_BAR;
;             PG8_LDA(At, 1, 1); STG_A(PG8_SA(1, 0), k3, 0, last);
;             PG8_BAR; PG8_WAIT_L(0); PG8_MMA(1, 0, At, B0); PG8_BAR; PG8_SCHED;
;             PG8_STAGE(PG8_SB(1, 1), b3 + hstep, voffA);
;             PG8_WAIT_V(6); PG8_BAR; PG8_MMA(1, 1, At, B1); PG8_BAR;
;         }
	s_waitcnt lgkmcnt(0)
	s_setprio 1
	v_mfma_f32_16x16x32_bf16 v[120:123], v[220:223], v[188:191], v[120:123]
	v_mfma_f32_16x16x32_bf16 v[116:119], v[228:231], v[188:191], v[116:119]
	v_mfma_f32_16x16x32_bf16 v[100:103], v[220:223], v[196:199], v[100:103]
	v_mfma_f32_16x16x32_bf16 v[96:99], v[228:231], v[196:199], v[96:99]
	v_mfma_f32_16x16x32_bf16 v[84:87], v[220:223], v[204:207], v[84:87]
	v_mfma_f32_16x16x32_bf16 v[80:83], v[228:231], v[204:207], v[80:83]
	v_mfma_f32_16x16x32_bf16 v[68:71], v[220:223], v[212:215], v[68:71]
	v_mfma_f32_16x16x32_bf16 v[64:67], v[228:231], v[212:215], v[64:67]
	v_mfma_f32_16x16x32_bf16 v[120:123], v[224:227], v[192:195], v[120:123]
	v_mfma_f32_16x16x32_bf16 v[116:119], v[232:235], v[192:195], v[116:119]
	v_mfma_f32_16x16x32_bf16 v[100:103], v[224:227], v[200:203], v[100:103]
	v_mfma_f32_16x16x32_bf16 v[96:99], v[232:235], v[200:203], v[96:99]
	v_mfma_f32_16x16x32_bf16 v[84:87], v[224:227], v[208:211], v[84:87]
	v_mfma_f32_16x16x32_bf16 v[80:83], v[232:235], v[208:211], v[80:83]
	v_mfma_f32_16x16x32_bf16 v[68:71], v[224:227], v[216:219], v[68:71]
	v_mfma_f32_16x16x32_bf16 v[64:67], v[232:235], v[216:219], v[64:67]
	s_setprio 0
	s_mov_b32 m0, s39
	v_lshl_add_u64 v[146:147], v[236:237], 0, s[2:3]
	s_barrier
	ds_read_b128 v[188:191], v163 offset:49152
	ds_read_b128 v[192:195], v163 offset:50176
	ds_read_b128 v[196:199], v163 offset:51200
	ds_read_b128 v[200:203], v163 offset:52224
	ds_read_b128 v[204:207], v163 offset:53248
	ds_read_b128 v[208:211], v163 offset:54272
	ds_read_b128 v[212:215], v163 offset:55296
	ds_read_b128 v[216:219], v163 offset:56320
	global_load_lds_dwordx4 v[146:147], off
	v_lshl_add_u64 v[146:147], v[238:239], 0, s[2:3]
	s_mov_b32 m0, s46
	s_nop 0
	global_load_lds_dwordx4 v[146:147], off
	s_barrier
	s_waitcnt lgkmcnt(0)
	s_setprio 1
	v_mfma_f32_16x16x32_bf16 v[60:63], v[134:137], v[188:191], v[60:63]
	v_mfma_f32_16x16x32_bf16 v[56:59], v[142:145], v[188:191], v[56:59]
	v_mfma_f32_16x16x32_bf16 v[44:47], v[134:137], v[196:199], v[44:47]
	v_mfma_f32_16x16x32_bf16 v[40:43], v[142:145], v[196:199], v[40:43]
	v_mfma_f32_16x16x32_bf16 v[28:31], v[134:137], v[204:207], v[28:31]
	v_mfma_f32_16x16x32_bf16 v[24:27], v[142:145], v[204:207], v[24:27]
	v_mfma_f32_16x16x32_bf16 v[12:15], v[134:137], v[212:215], v[12:15]
	v_mfma_f32_16x16x32_bf16 v[8:11], v[142:145], v[212:215], v[8:11]
	v_mfma_f32_16x16x32_bf16 v[60:63], v[138:141], v[192:195], v[60:63]
	v_mfma_f32_16x16x32_bf16 v[56:59], v[164:167], v[192:195], v[56:59]
	v_mfma_f32_16x16x32_bf16 v[44:47], v[138:141], v[200:203], v[44:47]
	v_mfma_f32_16x16x32_bf16 v[40:43], v[164:167], v[200:203], v[40:43]
	v_mfma_f32_16x16x32_bf16 v[28:31], v[138:141], v[208:211], v[28:31]
	v_mfma_f32_16x16x32_bf16 v[24:27], v[164:167], v[208:211], v[24:27]
	v_mfma_f32_16x16x32_bf16 v[12:15], v[138:141], v[216:219], v[12:15]
	v_mfma_f32_16x16x32_bf16 v[8:11], v[164:167], v[216:219], v[8:11]
	s_setprio 0
	s_barrier
	s_add_i32 s16, s16, s23
	v_lshl_add_u64 v[134:135], v[240:241], 0, s[2:3]
	s_mov_b32 m0, s16
	s_nop 0
	global_load_lds_dwordx4 v[134:135], off
	v_lshl_add_u64 v[134:135], v[242:243], 0, s[2:3]
	s_add_i32 m0, s16, 0x2000
	s_nop 0
	global_load_lds_dwordx4 v[134:135], off
	s_waitcnt vmcnt(6)
	s_barrier
	s_setprio 1
	v_mfma_f32_16x16x32_bf16 v[52:55], v[220:223], v[188:191], v[52:55]
	v_mfma_f32_16x16x32_bf16 v[48:51], v[228:231], v[188:191], v[48:51]
	v_mfma_f32_16x16x32_bf16 v[36:39], v[220:223], v[196:199], v[36:39]
	v_mfma_f32_16x16x32_bf16 v[32:35], v[228:231], v[196:199], v[32:35]
	v_mfma_f32_16x16x32_bf16 v[20:23], v[220:223], v[204:207], v[20:23]
	v_mfma_f32_16x16x32_bf16 v[16:19], v[228:231], v[204:207], v[16:19]
	v_mfma_f32_16x16x32_bf16 v[4:7], v[220:223], v[212:215], v[4:7]
	v_mfma_f32_16x16x32_bf16 v[0:3], v[228:231], v[212:215], v[0:3]
	v_mfma_f32_16x16x32_bf16 v[52:55], v[224:227], v[192:195], v[52:55]
	v_mfma_f32_16x16x32_bf16 v[48:51], v[232:235], v[192:195], v[48:51]
	v_mfma_f32_16x16x32_bf16 v[36:39], v[224:227], v[200:203], v[36:39]
	v_mfma_f32_16x16x32_bf16 v[32:35], v[232:235], v[200:203], v[32:35]
	v_mfma_f32_16x16x32_bf16 v[20:23], v[224:227], v[208:211], v[20:23]
	v_mfma_f32_16x16x32_bf16 v[16:19], v[232:235], v[208:211], v[16:19]
	v_mfma_f32_16x16x32_bf16 v[4:7], v[224:227], v[216:219], v[4:7]
	v_mfma_f32_16x16x32_bf16 v[0:3], v[232:235], v[216:219], v[0:3]
	s_setprio 0
	s_cmp_ge_i32 s31, s48
	s_mov_b64 s[16:17], s[18:19]
	s_mov_b32 s20, s31
	s_barrier
	s_cbranch_scc0 .LBB0_857

; #define PG8_STAGE(bufoff, gbase, voff) do { _Pragma("unroll") for (int _i = 0; _i < 2; ++_i) \
;         __builtin_amdgcn_global_load_lds((const unsigned*)((const char*)(gbase) + (voff)[_i]), (LAS unsigned*)(lds + (bufoff) + ldsw + _i * 8192), 16, 0, 0); } while (0)
; #define STG_A(bufoff, kb, h, usen) do { if constexpr (GATHER) { unsigned o_[2] = {(usen) ? noff[h][0] : coff[h][0], (usen) ? noff[h][1] : coff[h][1]}; PG8_STAGE(bufoff, (const char*)A + (kb), o_); } \
;         else { PG8_STAGE(bufoff, ((usen) ? nA : cA) + (kb) + (size_t)(h) * hstep, voffA); } } while (0)
; #define PG8_LDA(dst, b, h) do { _Pragma("unroll") for (int m = 0; m < 4; ++m) _Pragma("unroll") for (int k = 0; k < 2; ++k) dst[m][k] = *(const LAS bf16x8*)(lds + PG8_SA(b, h) + aoff + m * 2048 + k * 1024); } while (0)
; #define PG8_LDB(dst, b, h) do { _Pragma("unroll") for (int n = 0; n < 2; ++n) _Pragma("unroll") for (int k = 0; k < 2; ++k) dst[n][k] = *(const LAS bf16x8*)(lds + PG8_SB(b, h) + boff + n * 2048 + k * 1024); } while (0)
; #define PG8_MMA(ai, bj, At, Bt_) do { __builtin_amdgcn_s_setprio(1); _Pragma("unroll") for (int m = 0; m < 4; ++m) _Pragma("unroll") for (int n = 0; n < 2; ++n) _Pragma("unroll") for (int k = 0; k < 2; ++k) \
;         acc[ai][bj][m][n] = __builtin_amdgcn_mfma_f32_16x16x32_bf16(Bt_[n][k], At[m][k], acc[ai][bj][m][n], 0, 0, 0); __builtin_amdgcn_s_setprio(0); } while (0)
; #define PG8_WAIT_L(n) asm volatile("s_waitcnt lgkmcnt(" #n ")" ::: "memory")
; #define PG8_BAR __builtin_amdgcn_s_barrier()
; #define PG8_SCHED __builtin_amdgcn_sched_barrier(0)
; template <class Epi, bool GATHER = false>
; __device__ __forceinline__ void gemm_phase(LAS unsigned char* lds, const bf16_t* A, const bf16_t* Bt, const int K_, const Sched& S, const Epi& E, const int* gidx = nullptr) {
;     ...
;             PG8_LDB(B0, 0, 0); PG8_SCHED; PG8_LDA(At, 0, 0); STG_A(PG8_SA(1, 1), k1, 1, false);
;             PG8_WAIT_L(8); PG8_BAR; PG8_WAIT_L(0); PG8_MMA(0, 0, At, B0); PG8_BAR; PG8_SCHED;
;             PG8_LDB(B1, 0, 1); PG8_STAGE(PG8_SB(0, 0), b2, voffA);
;             PG8_BAR; PG8_WAIT_L(0); PG8_MMA(0, 1, At, B1); PG8_BAR;
;             PG8_LDA(At, 0, 1); STG_A(PG8_SA(0, 0), k2, 0, last);
;             PG8_BAR; PG8_WAIT_L(0); PG8_MMA(1, 0, At, B0); PG8_BAR; PG8_SCHED;
.LBB0_994:
	s_add_i32 s31, s20, 2
	s_add_u32 s18, s16, 0x100
	s_addc_u32 s19, s17, 0
	s_add_u32 s33, s49, s16
	s_addc_u32 s21, s50, s17
	s_add_i32 s51, 0, 0x10000
	v_add_u32_e32 v145, s51, v143
	ds_read_b128 v[146:149], v145
	ds_read_b128 v[150:153], v145 offset:1024
	ds_read_b128 v[154:157], v145 offset:2048
	ds_read_b128 v[158:161], v145 offset:3072
	s_add_i32 s54, s51, s23
	s_add_i32 m0, s34, 0xc000
	s_add_i32 s52, s34, 0xe000
	s_add_i32 s53, 0, 0x14000
	s_add_i32 s55, s54, 0x2000
	s_cmp_eq_u32 s42, s20
	s_cselect_b32 s20, s4, s33
	s_cselect_b32 s21, s5, s21
	s_cselect_b32 s33, 0, s19
	s_cselect_b32 s51, 0, s18
	v_lshl_add_u64 v[212:213], v[138:139], 0, s[16:17]
	ds_read_b128 v[162:165], v144
	ds_read_b128 v[166:169], v144 offset:1024
	ds_read_b128 v[188:191], v144 offset:2048
	ds_read_b128 v[192:195], v144 offset:3072
	ds_read_b128 v[196:199], v144 offset:4096
	ds_read_b128 v[200:203], v144 offset:5120
	ds_read_b128 v[204:207], v144 offset:6144
	ds_read_b128 v[208:211], v144 offset:7168
	global_load_lds_dwordx4 v[212:213], off
	v_lshl_add_u64 v[212:213], v[140:141], 0, s[16:17]
	s_mov_b32 m0, s52
	s_nop 0
	global_load_lds_dwordx4 v[212:213], off
	s_waitcnt lgkmcnt(8)
	s_barrier
	s_waitcnt lgkmcnt(0)
	s_setprio 1
	v_mfma_f32_16x16x32_bf16 v[122:125], v[146:149], v[162:165], v[122:125]
	v_mfma_f32_16x16x32_bf16 v[126:129], v[154:157], v[162:165], v[126:129]
	v_mfma_f32_16x16x32_bf16 v[108:111], v[146:149], v[188:191], v[108:111]
	v_mfma_f32_16x16x32_bf16 v[104:107], v[154:157], v[188:191], v[104:107]
	v_mfma_f32_16x16x32_bf16 v[92:95], v[146:149], v[196:199], v[92:95]
	v_mfma_f32_16x16x32_bf16 v[88:91], v[154:157], v[196:199], v[88:91]
	v_mfma_f32_16x16x32_bf16 v[76:79], v[146:149], v[204:207], v[76:79]
	v_mfma_f32_16x16x32_bf16 v[72:75], v[154:157], v[204:207], v[72:75]
	v_mfma_f32_16x16x32_bf16 v[122:125], v[150:153], v[166:169], v[122:125]
	v_mfma_f32_16x16x32_bf16 v[126:129], v[158:161], v[166:169], v[126:129]
	v_mfma_f32_16x16x32_bf16 v[108:111], v[150:153], v[192:195], v[108:111]
	v_mfma_f32_16x16x32_bf16 v[104:107], v[158:161], v[192:195], v[104:107]
	v_mfma_f32_16x16x32_bf16 v[92:95], v[150:153], v[200:203], v[92:95]
	v_mfma_f32_16x16x32_bf16 v[88:91], v[158:161], v[200:203], v[88:91]
	v_mfma_f32_16x16x32_bf16 v[76:79], v[150:153], v[208:211], v[76:79]
	v_mfma_f32_16x16x32_bf16 v[72:75], v[158:161], v[208:211], v[72:75]
	s_setprio 0
	s_barrier
	s_mov_b32 m0, s54
	v_add_u32_e32 v145, s53, v143
	v_lshl_add_u64 v[228:229], s[20:21], 0, v[132:133]
	ds_read_b128 v[212:215], v145
	ds_read_b128 v[216:219], v145 offset:1024
	ds_read_b128 v[220:223], v145 offset:2048
	ds_read_b128 v[224:227], v145 offset:3072
	global_load_lds_dwordx4 v[228:229], off
	v_lshl_add_u64 v[230:231], s[20:21], 0, v[130:131]
	s_mov_b32 m0, s55
	s_nop 0
	global_load_lds_dwordx4 v[230:231], off
	s_barrier
	s_waitcnt lgkmcnt(0)
	s_setprio 1
	v_mfma_f32_16x16x32_bf16 v[118:121], v[212:215], v[162:165], v[118:121]
	v_mfma_f32_16x16x32_bf16 v[114:117], v[220:223], v[162:165], v[114:117]
	v_mfma_f32_16x16x32_bf16 v[100:103], v[212:215], v[188:191], v[100:103]
	v_mfma_f32_16x16x32_bf16 v[96:99], v[220:223], v[188:191], v[96:99]
	v_mfma_f32_16x16x32_bf16 v[84:87], v[212:215], v[196:199], v[84:87]
	v_mfma_f32_16x16x32_bf16 v[80:83], v[220:223], v[196:199], v[80:83]
	v_mfma_f32_16x16x32_bf16 v[68:71], v[212:215], v[204:207], v[68:71]
	v_mfma_f32_16x16x32_bf16 v[64:67], v[220:223], v[204:207], v[64:67]
	v_mfma_f32_16x16x32_bf16 v[118:121], v[216:219], v[166:169], v[118:121]
	v_mfma_f32_16x16x32_bf16 v[114:117], v[224:227], v[166:169], v[114:117]
	v_mfma_f32_16x16x32_bf16 v[100:103], v[216:219], v[192:195], v[100:103]
	v_mfma_f32_16x16x32_bf16 v[96:99], v[224:227], v[192:195], v[96:99]
	v_mfma_f32_16x16x32_bf16 v[84:87], v[216:219], v[200:203], v[84:87]
	v_mfma_f32_16x16x32_bf16 v[80:83], v[224:227], v[200:203], v[80:83]
	v_mfma_f32_16x16x32_bf16 v[68:71], v[216:219], v[208:211], v[68:71]
	v_mfma_f32_16x16x32_bf16 v[64:67], v[224:227], v[208:211], v[64:67]
	s_setprio 0
	s_cselect_b32 s16, s12, s14
	s_cselect_b32 s17, s13, s15
	s_add_u32 s16, s16, s51
	s_addc_u32 s17, s17, s33
	s_mov_b32 m0, s34
	v_lshl_add_u64 v[232:233], s[16:17], 0, v[132:133]
	s_barrier
	ds_read_b128 v[162:165], v144 offset:16384
	ds_read_b128 v[166:169], v144 offset:17408
	ds_read_b128 v[188:191], v144 offset:18432
	ds_read_b128 v[192:195], v144 offset:19456
	ds_read_b128 v[196:199], v144 offset:20480
	ds_read_b128 v[200:203], v144 offset:21504
	ds_read_b128 v[204:207], v144 offset:22528
	ds_read_b128 v[208:211], v144 offset:23552
	global_load_lds_dwordx4 v[232:233], off
	v_lshl_add_u64 v[234:235], s[16:17], 0, v[130:131]
	s_mov_b32 m0, s35
	s_nop 0
	global_load_lds_dwordx4 v[234:235], off
	s_barrier
	s_waitcnt lgkmcnt(0)
	s_setprio 1
	v_mfma_f32_16x16x32_bf16 v[60:63], v[146:149], v[162:165], v[60:63]
	v_mfma_f32_16x16x32_bf16 v[56:59], v[154:157], v[162:165], v[56:59]
	v_mfma_f32_16x16x32_bf16 v[44:47], v[146:149], v[188:191], v[44:47]
	v_mfma_f32_16x16x32_bf16 v[40:43], v[154:157], v[188:191], v[40:43]
	v_mfma_f32_16x16x32_bf16 v[28:31], v[146:149], v[196:199], v[28:31]
	v_mfma_f32_16x16x32_bf16 v[24:27], v[154:157], v[196:199], v[24:27]
	v_mfma_f32_16x16x32_bf16 v[12:15], v[146:149], v[204:207], v[12:15]
	v_mfma_f32_16x16x32_bf16 v[8:11], v[154:157], v[204:207], v[8:11]
	v_mfma_f32_16x16x32_bf16 v[60:63], v[150:153], v[166:169], v[60:63]
	v_mfma_f32_16x16x32_bf16 v[56:59], v[158:161], v[166:169], v[56:59]
	v_mfma_f32_16x16x32_bf16 v[44:47], v[150:153], v[192:195], v[44:47]
	v_mfma_f32_16x16x32_bf16 v[40:43], v[158:161], v[192:195], v[40:43]
	v_mfma_f32_16x16x32_bf16 v[28:31], v[150:153], v[200:203], v[28:31]
	v_mfma_f32_16x16x32_bf16 v[24:27], v[158:161], v[200:203], v[24:27]
	v_mfma_f32_16x16x32_bf16 v[12:15], v[150:153], v[208:211], v[12:15]
	v_mfma_f32_16x16x32_bf16 v[8:11], v[158:161], v[208:211], v[8:11]
	s_setprio 0
	s_barrier
; #define PG8_STAGE(bufoff, gbase, voff) do { _Pragma("unroll") for (int _i = 0; _i < 2; ++_i) \
;         __builtin_amdgcn_global_load_lds((const unsigned*)((const char*)(gbase) + (voff)[_i]), (LAS unsigned*)(lds + (bufoff) + ldsw + _i * 8192), 16, 0, 0); } while (0)
; #define STG_A(bufoff, kb, h, usen) do { if constexpr (GATHER) { unsigned o_[2] = {(usen) ? noff[h][0] : coff[h][0], (usen) ? noff[h][1] : coff[h][1]}; PG8_STAGE(bufoff, (const char*)A + (kb), o_); } \
;         else { PG8_STAGE(bufoff, ((usen) ? nA : cA) + (kb) + (size_t)(h) * hstep, voffA); } } while (0)
; #define PG8_LDA(dst, b, h) do { _Pragma("unroll") for (int m = 0; m < 4; ++m) _Pragma("unroll") for (int k = 0; k < 2; ++k) dst[m][k] = *(const LAS bf16x8*)(lds + PG8_SA(b, h) + aoff + m * 2048 + k * 1024); } while (0)
; #define PG8_LDB(dst, b, h) do { _Pragma("unroll") for (int n = 0; n < 2; ++n) _Pragma("unroll") for (int k = 0; k < 2; ++k) dst[n][k] = *(const LAS bf16x8*)(lds + PG8_SB(b, h) + boff + n * 2048 + k * 1024); } while (0)
; #define PG8_MMA(ai, bj, At, Bt_) do { __builtin_amdgcn_s_setprio(1); _Pragma("unroll") for (int m = 0; m < 4; ++m) _Pragma("unroll") for (int n = 0; n < 2; ++n) _Pragma("unroll") for (int k = 0; k < 2; ++k) \
;         acc[ai][bj][m][n] = __builtin_amdgcn_mfma_f32_16x16x32_bf16(Bt_[n][k], At[m][k], acc[ai][bj][m][n], 0, 0, 0); __builtin_amdgcn_s_setprio(0); } while (0)
; #define PG8_WAIT_V(n) asm volatile("s_waitcnt vmcnt(" #n ")" ::: "memory")
; #define PG8_WAIT_L(n) asm volatile("s_waitcnt lgkmcnt(" #n ")" ::: "memory")
; #define PG8_BAR __builtin_amdgcn_s_barrier()
; #define PG8_SCHED __builtin_amdgcn_sched_barrier(0)
; template <class Epi, bool GATHER = false>
; __device__ __forceinline__ void gemm_phase(LAS unsigned char* lds, const bf16_t* A, const bf16_t* Bt, const int K_, const Sched& S, const Epi& E, const int* gidx = nullptr) {
;     ...
;             PG8_STAGE(PG8_SB(0, 1), b2 + hstep, voffA);
;             PG8_WAIT_V(6); PG8_BAR; PG8_MMA(1, 1, At, B1); PG8_BAR;
;             PG8_LDB(B0, 1, 0); PG8_SCHED; PG8_LDA(At, 1, 0); STG_A(PG8_SA(0, 1), k2, 1, last);
;             PG8_WAIT_L(8); PG8_BAR; PG8_WAIT_L(0); PG8_MMA(0, 0, At, B0); PG8_BAR; PG8_SCHED;
;             PG8_LDB(B1, 1, 1); PG8_STAGE(PG8_SB(1, 0), b3, voffA);
	s_add_u32 s20, s20, s0
	s_addc_u32 s21, s21, s1
	s_add_i32 s33, s53, s23
	v_lshl_add_u64 v[236:237], s[20:21], 0, v[132:133]
	s_mov_b32 m0, s33
	v_lshl_add_u64 v[238:239], s[20:21], 0, v[130:131]
	global_load_lds_dwordx4 v[236:237], off
	s_add_i32 m0, s33, 0x2000
	s_nop 0
	global_load_lds_dwordx4 v[238:239], off
	s_waitcnt vmcnt(6)
	s_barrier
	s_setprio 1
	v_mfma_f32_16x16x32_bf16 v[52:55], v[212:215], v[162:165], v[52:55]
	v_mfma_f32_16x16x32_bf16 v[48:51], v[220:223], v[162:165], v[48:51]
	v_mfma_f32_16x16x32_bf16 v[36:39], v[212:215], v[188:191], v[36:39]
	v_mfma_f32_16x16x32_bf16 v[32:35], v[220:223], v[188:191], v[32:35]
	v_mfma_f32_16x16x32_bf16 v[20:23], v[212:215], v[196:199], v[20:23]
	v_mfma_f32_16x16x32_bf16 v[16:19], v[220:223], v[196:199], v[16:19]
	v_mfma_f32_16x16x32_bf16 v[4:7], v[212:215], v[204:207], v[4:7]
	v_mfma_f32_16x16x32_bf16 v[0:3], v[220:223], v[204:207], v[0:3]
	v_mfma_f32_16x16x32_bf16 v[52:55], v[216:219], v[166:169], v[52:55]
	v_mfma_f32_16x16x32_bf16 v[48:51], v[224:227], v[166:169], v[48:51]
	v_mfma_f32_16x16x32_bf16 v[36:39], v[216:219], v[192:195], v[36:39]
	v_mfma_f32_16x16x32_bf16 v[32:35], v[224:227], v[192:195], v[32:35]
	v_mfma_f32_16x16x32_bf16 v[20:23], v[216:219], v[200:203], v[20:23]
	v_mfma_f32_16x16x32_bf16 v[16:19], v[224:227], v[200:203], v[16:19]
	v_mfma_f32_16x16x32_bf16 v[4:7], v[216:219], v[208:211], v[4:7]
	v_mfma_f32_16x16x32_bf16 v[0:3], v[224:227], v[208:211], v[0:3]
	s_setprio 0
	s_add_i32 s20, 0, 0x18000
	v_add_u32_e32 v145, s20, v143
	s_barrier
	ds_read_b128 v[146:149], v145
	ds_read_b128 v[150:153], v145 offset:1024
	ds_read_b128 v[154:157], v145 offset:2048
	ds_read_b128 v[158:161], v145 offset:3072
	s_add_u32 s16, s16, s0
	s_addc_u32 s17, s17, s1
	s_mov_b32 m0, s37
	v_lshl_add_u64 v[212:213], s[16:17], 0, v[132:133]
	ds_read_b128 v[162:165], v144 offset:32768
	ds_read_b128 v[166:169], v144 offset:33792
	ds_read_b128 v[188:191], v144 offset:34816
	ds_read_b128 v[192:195], v144 offset:35840
	ds_read_b128 v[196:199], v144 offset:36864
	ds_read_b128 v[200:203], v144 offset:37888
	ds_read_b128 v[204:207], v144 offset:38912
	ds_read_b128 v[208:211], v144 offset:39936
	global_load_lds_dwordx4 v[212:213], off
	v_lshl_add_u64 v[212:213], s[16:17], 0, v[130:131]
	s_mov_b32 m0, s38
	s_nop 0
	global_load_lds_dwordx4 v[212:213], off
	s_waitcnt lgkmcnt(8)
	s_barrier
	s_waitcnt lgkmcnt(0)
	s_setprio 1
	v_mfma_f32_16x16x32_bf16 v[122:125], v[146:149], v[162:165], v[122:125]
	v_mfma_f32_16x16x32_bf16 v[126:129], v[154:157], v[162:165], v[126:129]
	v_mfma_f32_16x16x32_bf16 v[108:111], v[146:149], v[188:191], v[108:111]
	v_mfma_f32_16x16x32_bf16 v[104:107], v[154:157], v[188:191], v[104:107]
	v_mfma_f32_16x16x32_bf16 v[92:95], v[146:149], v[196:199], v[92:95]
	v_mfma_f32_16x16x32_bf16 v[88:91], v[154:157], v[196:199], v[88:91]
	v_mfma_f32_16x16x32_bf16 v[76:79], v[146:149], v[204:207], v[76:79]
	v_mfma_f32_16x16x32_bf16 v[72:75], v[154:157], v[204:207], v[72:75]
	v_mfma_f32_16x16x32_bf16 v[122:125], v[150:153], v[166:169], v[122:125]
	v_mfma_f32_16x16x32_bf16 v[126:129], v[158:161], v[166:169], v[126:129]
	v_mfma_f32_16x16x32_bf16 v[108:111], v[150:153], v[192:195], v[108:111]
	v_mfma_f32_16x16x32_bf16 v[104:107], v[158:161], v[192:195], v[104:107]
	v_mfma_f32_16x16x32_bf16 v[92:95], v[150:153], v[200:203], v[92:95]
	v_mfma_f32_16x16x32_bf16 v[88:91], v[158:161], v[200:203], v[88:91]
	v_mfma_f32_16x16x32_bf16 v[76:79], v[150:153], v[208:211], v[76:79]
	v_mfma_f32_16x16x32_bf16 v[72:75], v[158:161], v[208:211], v[72:75]
	s_setprio 0
	s_barrier
	s_add_i32 s16, 0, 0x1c000
	s_add_i32 s17, s20, s23
	v_add_u32_e32 v145, s16, v143
	v_lshl_add_u64 v[228:229], v[228:229], 0, s[2:3]
	s_mov_b32 m0, s17
	ds_read_b128 v[212:215], v145
	ds_read_b128 v[216:219], v145 offset:1024
	ds_read_b128 v[220:223], v145 offset:2048
	ds_read_b128 v[224:227], v145 offset:3072
	global_load_lds_dwordx4 v[228:229], off
	v_lshl_add_u64 v[228:229], v[230:231], 0, s[2:3]
	s_add_i32 m0, s17, 0x2000
	s_nop 0
	global_load_lds_dwordx4 v[228:229], off
	s_barrier
; #define PG8_STAGE(bufoff, gbase, voff) do { _Pragma("unroll") for (int _i = 0; _i < 2; ++_i) \
;         __builtin_amdgcn_global_load_lds((const unsigned*)((const char*)(gbase) + (voff)[_i]), (LAS unsigned*)(lds + (bufoff) + ldsw + _i * 8192), 16, 0, 0); } while (0)
; #define STG_A(bufoff, kb, h, usen) do { if constexpr (GATHER) { unsigned o_[2] = {(usen) ? noff[h][0] : coff[h][0], (usen) ? noff[h][1] : coff[h][1]}; PG8_STAGE(bufoff, (const char*)A + (kb), o_); } \
;         else { PG8_STAGE(bufoff, ((usen) ? nA : cA) + (kb) + (size_t)(h) * hstep, voffA); } } while (0)
; #define PG8_LDA(dst, b, h) do { _Pragma("unroll") for (int m = 0; m < 4; ++m) _Pragma("unroll") for (int k = 0; k < 2; ++k) dst[m][k] = *(const LAS bf16x8*)(lds + PG8_SA(b, h) + aoff + m * 2048 + k * 1024); } while (0)
; #define PG8_MMA(ai, bj, At, Bt_) do { __builtin_amdgcn_s_setprio(1); _Pragma("unroll") for (int m = 0; m < 4; ++m) _Pragma("unroll") for (int n = 0; n < 2; ++n) _Pragma("unroll") for (int k = 0; k < 2; ++k) \
;         acc[ai][bj][m][n] = __builtin_amdgcn_mfma_f32_16x16x32_bf16(Bt_[n][k], At[m][k], acc[ai][bj][m][n], 0, 0, 0); __builtin_amdgcn_s_setprio(0); } while (0)
; #define PG8_WAIT_V(n) asm volatile("s_waitcnt vmcnt(" #n ")" ::: "memory")
; #define PG8_WAIT_L(n) asm volatile("s_waitcnt lgkmcnt(" #n ")" ::: "memory")
; #define PG8_BAR __builtin_amdgcn_s_barrier()
; #define PG8_SCHED __builtin_amdgcn_sched_barrier(0)
; template <class Epi, bool GATHER = false>
; __device__ __forceinline__ void gemm_phase(LAS unsigned char* lds, const bf16_t* A, const bf16_t* Bt, const int K_, const Sched& S, const Epi& E, const int* gidx = nullptr) {
;     ...
;             PG8_BAR; PG8_WAIT_L(0); PG8_MMA(0, 1, At, B1); PG8_BAR;
;             PG8_LDA(At, 1, 1); STG_A(PG8_SA(1, 0), k3, 0, last);
;             PG8_BAR; PG8_WAIT_L(0); PG8_MMA(1, 0, At, B0); PG8_BAR; PG8_SCHED;
;             PG8_STAGE(PG8_SB(1, 1), b3 + hstep, voffA);
;             PG8_WAIT_V(6); PG8_BAR; PG8_MMA(1, 1, At, B1); PG8_BAR;
;         }
	s_waitcnt lgkmcnt(0)
	s_setprio 1
	v_mfma_f32_16x16x32_bf16 v[118:121], v[212:215], v[162:165], v[118:121]
	v_mfma_f32_16x16x32_bf16 v[114:117], v[220:223], v[162:165], v[114:117]
	v_mfma_f32_16x16x32_bf16 v[100:103], v[212:215], v[188:191], v[100:103]
	v_mfma_f32_16x16x32_bf16 v[96:99], v[220:223], v[188:191], v[96:99]
	v_mfma_f32_16x16x32_bf16 v[84:87], v[212:215], v[196:199], v[84:87]
	v_mfma_f32_16x16x32_bf16 v[80:83], v[220:223], v[196:199], v[80:83]
	v_mfma_f32_16x16x32_bf16 v[68:71], v[212:215], v[204:207], v[68:71]
	v_mfma_f32_16x16x32_bf16 v[64:67], v[220:223], v[204:207], v[64:67]
	v_mfma_f32_16x16x32_bf16 v[118:121], v[216:219], v[166:169], v[118:121]
	v_mfma_f32_16x16x32_bf16 v[114:117], v[224:227], v[166:169], v[114:117]
	v_mfma_f32_16x16x32_bf16 v[100:103], v[216:219], v[192:195], v[100:103]
	v_mfma_f32_16x16x32_bf16 v[96:99], v[224:227], v[192:195], v[96:99]
	v_mfma_f32_16x16x32_bf16 v[84:87], v[216:219], v[200:203], v[84:87]
	v_mfma_f32_16x16x32_bf16 v[80:83], v[224:227], v[200:203], v[80:83]
	v_mfma_f32_16x16x32_bf16 v[68:71], v[216:219], v[208:211], v[68:71]
	v_mfma_f32_16x16x32_bf16 v[64:67], v[224:227], v[208:211], v[64:67]
	s_setprio 0
	s_mov_b32 m0, s39
	v_lshl_add_u64 v[228:229], v[232:233], 0, s[2:3]
	s_barrier
	ds_read_b128 v[162:165], v144 offset:49152
	ds_read_b128 v[166:169], v144 offset:50176
	ds_read_b128 v[188:191], v144 offset:51200
	ds_read_b128 v[192:195], v144 offset:52224
	ds_read_b128 v[196:199], v144 offset:53248
	ds_read_b128 v[200:203], v144 offset:54272
	ds_read_b128 v[204:207], v144 offset:55296
	ds_read_b128 v[208:211], v144 offset:56320
	global_load_lds_dwordx4 v[228:229], off
	v_lshl_add_u64 v[228:229], v[234:235], 0, s[2:3]
	s_mov_b32 m0, s40
	s_nop 0
	global_load_lds_dwordx4 v[228:229], off
	s_barrier
	s_waitcnt lgkmcnt(0)
	s_setprio 1
	v_mfma_f32_16x16x32_bf16 v[60:63], v[146:149], v[162:165], v[60:63]
	v_mfma_f32_16x16x32_bf16 v[56:59], v[154:157], v[162:165], v[56:59]
	v_mfma_f32_16x16x32_bf16 v[44:47], v[146:149], v[188:191], v[44:47]
	v_mfma_f32_16x16x32_bf16 v[40:43], v[154:157], v[188:191], v[40:43]
	v_mfma_f32_16x16x32_bf16 v[28:31], v[146:149], v[196:199], v[28:31]
	v_mfma_f32_16x16x32_bf16 v[24:27], v[154:157], v[196:199], v[24:27]
	v_mfma_f32_16x16x32_bf16 v[12:15], v[146:149], v[204:207], v[12:15]
	v_mfma_f32_16x16x32_bf16 v[8:11], v[154:157], v[204:207], v[8:11]
	v_mfma_f32_16x16x32_bf16 v[60:63], v[150:153], v[166:169], v[60:63]
	v_mfma_f32_16x16x32_bf16 v[56:59], v[158:161], v[166:169], v[56:59]
	v_mfma_f32_16x16x32_bf16 v[44:47], v[150:153], v[192:195], v[44:47]
	v_mfma_f32_16x16x32_bf16 v[40:43], v[158:161], v[192:195], v[40:43]
	v_mfma_f32_16x16x32_bf16 v[28:31], v[150:153], v[200:203], v[28:31]
	v_mfma_f32_16x16x32_bf16 v[24:27], v[158:161], v[200:203], v[24:27]
	v_mfma_f32_16x16x32_bf16 v[12:15], v[150:153], v[208:211], v[12:15]
	v_mfma_f32_16x16x32_bf16 v[8:11], v[158:161], v[208:211], v[8:11]
	s_setprio 0
	s_barrier
	s_add_i32 s16, s16, s23
	v_lshl_add_u64 v[146:147], v[236:237], 0, s[2:3]
	s_mov_b32 m0, s16
	s_nop 0
	global_load_lds_dwordx4 v[146:147], off
	v_lshl_add_u64 v[146:147], v[238:239], 0, s[2:3]
	s_add_i32 m0, s16, 0x2000
	s_nop 0
	global_load_lds_dwordx4 v[146:147], off
	s_waitcnt vmcnt(6)
	s_barrier
	s_setprio 1
	v_mfma_f32_16x16x32_bf16 v[52:55], v[212:215], v[162:165], v[52:55]
	v_mfma_f32_16x16x32_bf16 v[48:51], v[220:223], v[162:165], v[48:51]
	v_mfma_f32_16x16x32_bf16 v[36:39], v[212:215], v[188:191], v[36:39]
	v_mfma_f32_16x16x32_bf16 v[32:35], v[220:223], v[188:191], v[32:35]
	v_mfma_f32_16x16x32_bf16 v[20:23], v[212:215], v[196:199], v[20:23]
	v_mfma_f32_16x16x32_bf16 v[16:19], v[220:223], v[196:199], v[16:19]
	v_mfma_f32_16x16x32_bf16 v[4:7], v[212:215], v[204:207], v[4:7]
	v_mfma_f32_16x16x32_bf16 v[0:3], v[220:223], v[204:207], v[0:3]
	v_mfma_f32_16x16x32_bf16 v[52:55], v[216:219], v[166:169], v[52:55]
	v_mfma_f32_16x16x32_bf16 v[48:51], v[224:227], v[166:169], v[48:51]
	v_mfma_f32_16x16x32_bf16 v[36:39], v[216:219], v[192:195], v[36:39]
	v_mfma_f32_16x16x32_bf16 v[32:35], v[224:227], v[192:195], v[32:35]
	v_mfma_f32_16x16x32_bf16 v[20:23], v[216:219], v[200:203], v[20:23]
	v_mfma_f32_16x16x32_bf16 v[16:19], v[224:227], v[200:203], v[16:19]
	v_mfma_f32_16x16x32_bf16 v[4:7], v[216:219], v[208:211], v[4:7]
	v_mfma_f32_16x16x32_bf16 v[0:3], v[224:227], v[208:211], v[0:3]
	s_setprio 0
	s_cmp_ge_i32 s31, s41
	s_mov_b64 s[16:17], s[18:19]
	s_mov_b32 s20, s31
	s_barrier
	s_cbranch_scc0 .LBB0_994
	v_readlane_b32 s50, v255, 32
	s_mov_b64 s[18:19], s[58:59]
	v_readlane_b32 s51, v255, 33
	v_readlane_b32 s52, v255, 34
	v_readlane_b32 s53, v255, 35
	s_branch .LBB0_981

; #define PG8_STAGE(bufoff, gbase, voff) do { _Pragma("unroll") for (int _i = 0; _i < 2; ++_i) \
;         __builtin_amdgcn_global_load_lds((const unsigned*)((const char*)(gbase) + (voff)[_i]), (LAS unsigned*)(lds + (bufoff) + ldsw + _i * 8192), 16, 0, 0); } while (0)
; #define STG_A(bufoff, kb, h, usen) do { if constexpr (GATHER) { unsigned o_[2] = {(usen) ? noff[h][0] : coff[h][0], (usen) ? noff[h][1] : coff[h][1]}; PG8_STAGE(bufoff, (const char*)A + (kb), o_); } \
;         else { PG8_STAGE(bufoff, ((usen) ? nA : cA) + (kb) + (size_t)(h) * hstep, voffA); } } while (0)
; #define PG8_LDA(dst, b, h) do { _Pragma("unroll") for (int m = 0; m < 4; ++m) _Pragma("unroll") for (int k = 0; k < 2; ++k) dst[m][k] = *(const LAS bf16x8*)(lds + PG8_SA(b, h) + aoff + m * 2048 + k * 1024); } while (0)
; #define PG8_LDB(dst, b, h) do { _Pragma("unroll") for (int n = 0; n < 2; ++n) _Pragma("unroll") for (int k = 0; k < 2; ++k) dst[n][k] = *(const LAS bf16x8*)(lds + PG8_SB(b, h) + boff + n * 2048 + k * 1024); } while (0)
; #define PG8_MMA(ai, bj, At, Bt_) do { __builtin_amdgcn_s_setprio(1); _Pragma("unroll") for (int m = 0; m < 4; ++m) _Pragma("unroll") for (int n = 0; n < 2; ++n) _Pragma("unroll") for (int k = 0; k < 2; ++k) \
;         acc[ai][bj][m][n] = __builtin_amdgcn_mfma_f32_16x16x32_bf16(Bt_[n][k], At[m][k], acc[ai][bj][m][n], 0, 0, 0); __builtin_amdgcn_s_setprio(0); } while (0)
; #define PG8_WAIT_L(n) asm volatile("s_waitcnt lgkmcnt(" #n ")" ::: "memory")
; #define PG8_BAR __builtin_amdgcn_s_barrier()
; #define PG8_SCHED __builtin_amdgcn_sched_barrier(0)
; template <class Epi, bool GATHER = false>
; __device__ __forceinline__ void gemm_phase(LAS unsigned char* lds, const bf16_t* A, const bf16_t* Bt, const int K_, const Sched& S, const Epi& E, const int* gidx = nullptr) {
;     ...
;             PG8_LDB(B0, 0, 0); PG8_SCHED; PG8_LDA(At, 0, 0); STG_A(PG8_SA(1, 1), k1, 1, false);
;             PG8_WAIT_L(8); PG8_BAR; PG8_WAIT_L(0); PG8_MMA(0, 0, At, B0); PG8_BAR; PG8_SCHED;
;             PG8_LDB(B1, 0, 1); PG8_STAGE(PG8_SB(0, 0), b2, voffA);
;             PG8_BAR; PG8_WAIT_L(0); PG8_MMA(0, 1, At, B1); PG8_BAR;
;             PG8_LDA(At, 0, 1); STG_A(PG8_SA(0, 0), k2, 0, last);
;             PG8_BAR; PG8_WAIT_L(0); PG8_MMA(1, 0, At, B0); PG8_BAR; PG8_SCHED;
.LBB0_1200:
	s_add_i32 s31, s20, 2
	s_add_u32 s18, s16, 0x100
	s_addc_u32 s19, s17, 0
	s_add_u32 s33, s49, s16
	s_addc_u32 s21, s50, s17
	s_add_i32 s51, 0, 0x10000
	v_add_u32_e32 v156, s51, v141
	ds_read_b128 v[144:147], v156
	ds_read_b128 v[148:151], v156 offset:1024
	ds_read_b128 v[152:155], v156 offset:2048
	ds_read_b128 v[156:159], v156 offset:3072
	s_add_i32 s54, s51, s23
	s_add_i32 m0, s34, 0xc000
	s_add_i32 s52, s34, 0xe000
	s_add_i32 s53, 0, 0x14000
	s_add_i32 s55, s54, 0x2000
	s_cmp_eq_u32 s42, s20
	s_cselect_b32 s20, s4, s33
	s_cselect_b32 s21, s5, s21
	s_cselect_b32 s33, 0, s19
	s_cselect_b32 s51, 0, s18
	v_lshl_add_u64 v[168:169], v[136:137], 0, s[16:17]
	ds_read_b128 v[160:163], v143
	ds_read_b128 v[164:167], v143 offset:1024
	ds_read_b128 v[188:191], v143 offset:2048
	ds_read_b128 v[192:195], v143 offset:3072
	ds_read_b128 v[196:199], v143 offset:4096
	ds_read_b128 v[200:203], v143 offset:5120
	ds_read_b128 v[204:207], v143 offset:6144
	ds_read_b128 v[208:211], v143 offset:7168
	global_load_lds_dwordx4 v[168:169], off
	v_lshl_add_u64 v[168:169], v[138:139], 0, s[16:17]
	s_mov_b32 m0, s52
	s_nop 0
	global_load_lds_dwordx4 v[168:169], off
	s_waitcnt lgkmcnt(8)
	s_barrier
	s_waitcnt lgkmcnt(0)
	s_setprio 1
	v_mfma_f32_16x16x32_bf16 v[122:125], v[144:147], v[160:163], v[122:125]
	v_mfma_f32_16x16x32_bf16 v[126:129], v[152:155], v[160:163], v[126:129]
	v_mfma_f32_16x16x32_bf16 v[108:111], v[144:147], v[188:191], v[108:111]
	v_mfma_f32_16x16x32_bf16 v[104:107], v[152:155], v[188:191], v[104:107]
	v_mfma_f32_16x16x32_bf16 v[92:95], v[144:147], v[196:199], v[92:95]
	v_mfma_f32_16x16x32_bf16 v[88:91], v[152:155], v[196:199], v[88:91]
	v_mfma_f32_16x16x32_bf16 v[76:79], v[144:147], v[204:207], v[76:79]
	v_mfma_f32_16x16x32_bf16 v[72:75], v[152:155], v[204:207], v[72:75]
	v_mfma_f32_16x16x32_bf16 v[122:125], v[148:151], v[164:167], v[122:125]
	v_mfma_f32_16x16x32_bf16 v[126:129], v[156:159], v[164:167], v[126:129]
	v_mfma_f32_16x16x32_bf16 v[108:111], v[148:151], v[192:195], v[108:111]
	v_mfma_f32_16x16x32_bf16 v[104:107], v[156:159], v[192:195], v[104:107]
	v_mfma_f32_16x16x32_bf16 v[92:95], v[148:151], v[200:203], v[92:95]
	v_mfma_f32_16x16x32_bf16 v[88:91], v[156:159], v[200:203], v[88:91]
	v_mfma_f32_16x16x32_bf16 v[76:79], v[148:151], v[208:211], v[76:79]
	v_mfma_f32_16x16x32_bf16 v[72:75], v[156:159], v[208:211], v[72:75]
	s_setprio 0
	s_barrier
	v_add_u32_e32 v168, s53, v141
	s_mov_b32 m0, s54
	ds_read_b128 v[212:215], v168
	ds_read_b128 v[216:219], v168 offset:1024
	ds_read_b128 v[220:223], v168 offset:2048
	ds_read_b128 v[224:227], v168 offset:3072
	v_lshl_add_u64 v[168:169], s[20:21], 0, v[112:113]
	global_load_lds_dwordx4 v[168:169], off
	v_lshl_add_u64 v[228:229], s[20:21], 0, v[130:131]
	s_mov_b32 m0, s55
	s_nop 0
	global_load_lds_dwordx4 v[228:229], off
	s_barrier
	s_waitcnt lgkmcnt(0)
	s_setprio 1
	v_mfma_f32_16x16x32_bf16 v[118:121], v[212:215], v[160:163], v[118:121]
	v_mfma_f32_16x16x32_bf16 v[114:117], v[220:223], v[160:163], v[114:117]
	v_mfma_f32_16x16x32_bf16 v[100:103], v[212:215], v[188:191], v[100:103]
	v_mfma_f32_16x16x32_bf16 v[96:99], v[220:223], v[188:191], v[96:99]
	v_mfma_f32_16x16x32_bf16 v[84:87], v[212:215], v[196:199], v[84:87]
	v_mfma_f32_16x16x32_bf16 v[80:83], v[220:223], v[196:199], v[80:83]
	v_mfma_f32_16x16x32_bf16 v[68:71], v[212:215], v[204:207], v[68:71]
	v_mfma_f32_16x16x32_bf16 v[64:67], v[220:223], v[204:207], v[64:67]
	v_mfma_f32_16x16x32_bf16 v[118:121], v[216:219], v[164:167], v[118:121]
	v_mfma_f32_16x16x32_bf16 v[114:117], v[224:227], v[164:167], v[114:117]
	v_mfma_f32_16x16x32_bf16 v[100:103], v[216:219], v[192:195], v[100:103]
	v_mfma_f32_16x16x32_bf16 v[96:99], v[224:227], v[192:195], v[96:99]
	v_mfma_f32_16x16x32_bf16 v[84:87], v[216:219], v[200:203], v[84:87]
	v_mfma_f32_16x16x32_bf16 v[80:83], v[224:227], v[200:203], v[80:83]
	v_mfma_f32_16x16x32_bf16 v[68:71], v[216:219], v[208:211], v[68:71]
	v_mfma_f32_16x16x32_bf16 v[64:67], v[224:227], v[208:211], v[64:67]
	s_setprio 0
	s_cselect_b32 s16, s12, s14
	s_cselect_b32 s17, s13, s15
	s_add_u32 s16, s16, s51
	s_addc_u32 s17, s17, s33
	s_mov_b32 m0, s34
	v_lshl_add_u64 v[230:231], s[16:17], 0, v[112:113]
	s_barrier
	ds_read_b128 v[160:163], v143 offset:16384
	ds_read_b128 v[164:167], v143 offset:17408
	ds_read_b128 v[188:191], v143 offset:18432
	ds_read_b128 v[192:195], v143 offset:19456
	ds_read_b128 v[196:199], v143 offset:20480
	ds_read_b128 v[200:203], v143 offset:21504
	ds_read_b128 v[204:207], v143 offset:22528
	ds_read_b128 v[208:211], v143 offset:23552
	global_load_lds_dwordx4 v[230:231], off
	v_lshl_add_u64 v[232:233], s[16:17], 0, v[130:131]
	s_mov_b32 m0, s35
	s_nop 0
	global_load_lds_dwordx4 v[232:233], off
	s_barrier
	s_waitcnt lgkmcnt(0)
	s_setprio 1
	v_mfma_f32_16x16x32_bf16 v[60:63], v[144:147], v[160:163], v[60:63]
	v_mfma_f32_16x16x32_bf16 v[56:59], v[152:155], v[160:163], v[56:59]
	v_mfma_f32_16x16x32_bf16 v[44:47], v[144:147], v[188:191], v[44:47]
	v_mfma_f32_16x16x32_bf16 v[40:43], v[152:155], v[188:191], v[40:43]
	v_mfma_f32_16x16x32_bf16 v[28:31], v[144:147], v[196:199], v[28:31]
	v_mfma_f32_16x16x32_bf16 v[24:27], v[152:155], v[196:199], v[24:27]
	v_mfma_f32_16x16x32_bf16 v[12:15], v[144:147], v[204:207], v[12:15]
	v_mfma_f32_16x16x32_bf16 v[8:11], v[152:155], v[204:207], v[8:11]
	v_mfma_f32_16x16x32_bf16 v[60:63], v[148:151], v[164:167], v[60:63]
	v_mfma_f32_16x16x32_bf16 v[56:59], v[156:159], v[164:167], v[56:59]
	v_mfma_f32_16x16x32_bf16 v[44:47], v[148:151], v[192:195], v[44:47]
	v_mfma_f32_16x16x32_bf16 v[40:43], v[156:159], v[192:195], v[40:43]
	v_mfma_f32_16x16x32_bf16 v[28:31], v[148:151], v[200:203], v[28:31]
	v_mfma_f32_16x16x32_bf16 v[24:27], v[156:159], v[200:203], v[24:27]
	v_mfma_f32_16x16x32_bf16 v[12:15], v[148:151], v[208:211], v[12:15]
	v_mfma_f32_16x16x32_bf16 v[8:11], v[156:159], v[208:211], v[8:11]
	s_setprio 0
	s_barrier
; #define PG8_STAGE(bufoff, gbase, voff) do { _Pragma("unroll") for (int _i = 0; _i < 2; ++_i) \
;         __builtin_amdgcn_global_load_lds((const unsigned*)((const char*)(gbase) + (voff)[_i]), (LAS unsigned*)(lds + (bufoff) + ldsw + _i * 8192), 16, 0, 0); } while (0)
; #define STG_A(bufoff, kb, h, usen) do { if constexpr (GATHER) { unsigned o_[2] = {(usen) ? noff[h][0] : coff[h][0], (usen) ? noff[h][1] : coff[h][1]}; PG8_STAGE(bufoff, (const char*)A + (kb), o_); } \
;         else { PG8_STAGE(bufoff, ((usen) ? nA : cA) + (kb) + (size_t)(h) * hstep, voffA); } } while (0)
; #define PG8_LDA(dst, b, h) do { _Pragma("unroll") for (int m = 0; m < 4; ++m) _Pragma("unroll") for (int k = 0; k < 2; ++k) dst[m][k] = *(const LAS bf16x8*)(lds + PG8_SA(b, h) + aoff + m * 2048 + k * 1024); } while (0)
; #define PG8_LDB(dst, b, h) do { _Pragma("unroll") for (int n = 0; n < 2; ++n) _Pragma("unroll") for (int k = 0; k < 2; ++k) dst[n][k] = *(const LAS bf16x8*)(lds + PG8_SB(b, h) + boff + n * 2048 + k * 1024); } while (0)
; #define PG8_MMA(ai, bj, At, Bt_) do { __builtin_amdgcn_s_setprio(1); _Pragma("unroll") for (int m = 0; m < 4; ++m) _Pragma("unroll") for (int n = 0; n < 2; ++n) _Pragma("unroll") for (int k = 0; k < 2; ++k) \
;         acc[ai][bj][m][n] = __builtin_amdgcn_mfma_f32_16x16x32_bf16(Bt_[n][k], At[m][k], acc[ai][bj][m][n], 0, 0, 0); __builtin_amdgcn_s_setprio(0); } while (0)
; #define PG8_WAIT_V(n) asm volatile("s_waitcnt vmcnt(" #n ")" ::: "memory")
; #define PG8_WAIT_L(n) asm volatile("s_waitcnt lgkmcnt(" #n ")" ::: "memory")
; #define PG8_BAR __builtin_amdgcn_s_barrier()
; #define PG8_SCHED __builtin_amdgcn_sched_barrier(0)
; template <class Epi, bool GATHER = false>
; __device__ __forceinline__ void gemm_phase(LAS unsigned char* lds, const bf16_t* A, const bf16_t* Bt, const int K_, const Sched& S, const Epi& E, const int* gidx = nullptr) {
;     ...
;             PG8_STAGE(PG8_SB(0, 1), b2 + hstep, voffA);
;             PG8_WAIT_V(6); PG8_BAR; PG8_MMA(1, 1, At, B1); PG8_BAR;
;             PG8_LDB(B0, 1, 0); PG8_SCHED; PG8_LDA(At, 1, 0); STG_A(PG8_SA(0, 1), k2, 1, last);
;             PG8_WAIT_L(8); PG8_BAR; PG8_WAIT_L(0); PG8_MMA(0, 0, At, B0); PG8_BAR; PG8_SCHED;
;             PG8_LDB(B1, 1, 1); PG8_STAGE(PG8_SB(1, 0), b3, voffA);
	s_add_u32 s20, s20, s0
	s_addc_u32 s21, s21, s1
	s_add_i32 s33, s53, s23
	v_lshl_add_u64 v[234:235], s[20:21], 0, v[112:113]
	s_mov_b32 m0, s33
	v_lshl_add_u64 v[236:237], s[20:21], 0, v[130:131]
	global_load_lds_dwordx4 v[234:235], off
	s_add_i32 m0, s33, 0x2000
	s_nop 0
	global_load_lds_dwordx4 v[236:237], off
	s_waitcnt vmcnt(6)
	s_barrier
	s_setprio 1
	v_mfma_f32_16x16x32_bf16 v[52:55], v[212:215], v[160:163], v[52:55]
	v_mfma_f32_16x16x32_bf16 v[48:51], v[220:223], v[160:163], v[48:51]
	v_mfma_f32_16x16x32_bf16 v[36:39], v[212:215], v[188:191], v[36:39]
	v_mfma_f32_16x16x32_bf16 v[32:35], v[220:223], v[188:191], v[32:35]
	v_mfma_f32_16x16x32_bf16 v[20:23], v[212:215], v[196:199], v[20:23]
	v_mfma_f32_16x16x32_bf16 v[16:19], v[220:223], v[196:199], v[16:19]
	v_mfma_f32_16x16x32_bf16 v[4:7], v[212:215], v[204:207], v[4:7]
	v_mfma_f32_16x16x32_bf16 v[0:3], v[220:223], v[204:207], v[0:3]
	v_mfma_f32_16x16x32_bf16 v[52:55], v[216:219], v[164:167], v[52:55]
	v_mfma_f32_16x16x32_bf16 v[48:51], v[224:227], v[164:167], v[48:51]
	v_mfma_f32_16x16x32_bf16 v[36:39], v[216:219], v[192:195], v[36:39]
	v_mfma_f32_16x16x32_bf16 v[32:35], v[224:227], v[192:195], v[32:35]
	v_mfma_f32_16x16x32_bf16 v[20:23], v[216:219], v[200:203], v[20:23]
	v_mfma_f32_16x16x32_bf16 v[16:19], v[224:227], v[200:203], v[16:19]
	v_mfma_f32_16x16x32_bf16 v[4:7], v[216:219], v[208:211], v[4:7]
	v_mfma_f32_16x16x32_bf16 v[0:3], v[224:227], v[208:211], v[0:3]
	s_setprio 0
	s_add_i32 s20, 0, 0x18000
	v_add_u32_e32 v156, s20, v141
	s_barrier
	ds_read_b128 v[144:147], v156
	ds_read_b128 v[148:151], v156 offset:1024
	ds_read_b128 v[152:155], v156 offset:2048
	ds_read_b128 v[156:159], v156 offset:3072
	s_add_u32 s16, s16, s0
	s_addc_u32 s17, s17, s1
	s_mov_b32 m0, s37
	v_lshl_add_u64 v[212:213], s[16:17], 0, v[112:113]
	ds_read_b128 v[160:163], v143 offset:32768
	ds_read_b128 v[164:167], v143 offset:33792
	ds_read_b128 v[188:191], v143 offset:34816
	ds_read_b128 v[192:195], v143 offset:35840
	ds_read_b128 v[196:199], v143 offset:36864
	ds_read_b128 v[200:203], v143 offset:37888
	ds_read_b128 v[204:207], v143 offset:38912
	ds_read_b128 v[208:211], v143 offset:39936
	global_load_lds_dwordx4 v[212:213], off
	v_lshl_add_u64 v[212:213], s[16:17], 0, v[130:131]
	s_mov_b32 m0, s38
	s_nop 0
	global_load_lds_dwordx4 v[212:213], off
	s_waitcnt lgkmcnt(8)
	s_barrier
	s_waitcnt lgkmcnt(0)
	s_setprio 1
	v_mfma_f32_16x16x32_bf16 v[122:125], v[144:147], v[160:163], v[122:125]
	v_mfma_f32_16x16x32_bf16 v[126:129], v[152:155], v[160:163], v[126:129]
	v_mfma_f32_16x16x32_bf16 v[108:111], v[144:147], v[188:191], v[108:111]
	v_mfma_f32_16x16x32_bf16 v[104:107], v[152:155], v[188:191], v[104:107]
	v_mfma_f32_16x16x32_bf16 v[92:95], v[144:147], v[196:199], v[92:95]
	v_mfma_f32_16x16x32_bf16 v[88:91], v[152:155], v[196:199], v[88:91]
	v_mfma_f32_16x16x32_bf16 v[76:79], v[144:147], v[204:207], v[76:79]
	v_mfma_f32_16x16x32_bf16 v[72:75], v[152:155], v[204:207], v[72:75]
	v_mfma_f32_16x16x32_bf16 v[122:125], v[148:151], v[164:167], v[122:125]
	v_mfma_f32_16x16x32_bf16 v[126:129], v[156:159], v[164:167], v[126:129]
	v_mfma_f32_16x16x32_bf16 v[108:111], v[148:151], v[192:195], v[108:111]
	v_mfma_f32_16x16x32_bf16 v[104:107], v[156:159], v[192:195], v[104:107]
	v_mfma_f32_16x16x32_bf16 v[92:95], v[148:151], v[200:203], v[92:95]
	v_mfma_f32_16x16x32_bf16 v[88:91], v[156:159], v[200:203], v[88:91]
	v_mfma_f32_16x16x32_bf16 v[76:79], v[148:151], v[208:211], v[76:79]
	v_mfma_f32_16x16x32_bf16 v[72:75], v[156:159], v[208:211], v[72:75]
	s_setprio 0
	s_barrier
	s_add_i32 s16, 0, 0x1c000
	s_add_i32 s17, s20, s23
	v_add_u32_e32 v187, s16, v141
	v_lshl_add_u64 v[168:169], v[168:169], 0, s[2:3]
	s_mov_b32 m0, s17
	ds_read_b128 v[212:215], v187
	ds_read_b128 v[216:219], v187 offset:1024
	ds_read_b128 v[220:223], v187 offset:2048
	ds_read_b128 v[224:227], v187 offset:3072
	global_load_lds_dwordx4 v[168:169], off
	v_lshl_add_u64 v[168:169], v[228:229], 0, s[2:3]
	s_add_i32 m0, s17, 0x2000
	s_nop 0
	global_load_lds_dwordx4 v[168:169], off
	s_barrier
; #define PG8_STAGE(bufoff, gbase, voff) do { _Pragma("unroll") for (int _i = 0; _i < 2; ++_i) \
;         __builtin_amdgcn_global_load_lds((const unsigned*)((const char*)(gbase) + (voff)[_i]), (LAS unsigned*)(lds + (bufoff) + ldsw + _i * 8192), 16, 0, 0); } while (0)
; #define STG_A(bufoff, kb, h, usen) do { if constexpr (GATHER) { unsigned o_[2] = {(usen) ? noff[h][0] : coff[h][0], (usen) ? noff[h][1] : coff[h][1]}; PG8_STAGE(bufoff, (const char*)A + (kb), o_); } \
;         else { PG8_STAGE(bufoff, ((usen) ? nA : cA) + (kb) + (size_t)(h) * hstep, voffA); } } while (0)
; #define PG8_LDA(dst, b, h) do { _Pragma("unroll") for (int m = 0; m < 4; ++m) _Pragma("unroll") for (int k = 0; k < 2; ++k) dst[m][k] = *(const LAS bf16x8*)(lds + PG8_SA(b, h) + aoff + m * 2048 + k * 1024); } while (0)
; #define PG8_MMA(ai, bj, At, Bt_) do { __builtin_amdgcn_s_setprio(1); _Pragma("unroll") for (int m = 0; m < 4; ++m) _Pragma("unroll") for (int n = 0; n < 2; ++n) _Pragma("unroll") for (int k = 0; k < 2; ++k) \
;         acc[ai][bj][m][n] = __builtin_amdgcn_mfma_f32_16x16x32_bf16(Bt_[n][k], At[m][k], acc[ai][bj][m][n], 0, 0, 0); __builtin_amdgcn_s_setprio(0); } while (0)
; #define PG8_WAIT_V(n) asm volatile("s_waitcnt vmcnt(" #n ")" ::: "memory")
; #define PG8_WAIT_L(n) asm volatile("s_waitcnt lgkmcnt(" #n ")" ::: "memory")
; #define PG8_BAR __builtin_amdgcn_s_barrier()
; #define PG8_SCHED __builtin_amdgcn_sched_barrier(0)
; template <class Epi, bool GATHER = false>
; __device__ __forceinline__ void gemm_phase(LAS unsigned char* lds, const bf16_t* A, const bf16_t* Bt, const int K_, const Sched& S, const Epi& E, const int* gidx = nullptr) {
;     ...
;             PG8_BAR; PG8_WAIT_L(0); PG8_MMA(0, 1, At, B1); PG8_BAR;
;             PG8_LDA(At, 1, 1); STG_A(PG8_SA(1, 0), k3, 0, last);
;             PG8_BAR; PG8_WAIT_L(0); PG8_MMA(1, 0, At, B0); PG8_BAR; PG8_SCHED;
;             PG8_STAGE(PG8_SB(1, 1), b3 + hstep, voffA);
;             PG8_WAIT_V(6); PG8_BAR; PG8_MMA(1, 1, At, B1); PG8_BAR;
;         }
	s_waitcnt lgkmcnt(0)
	s_setprio 1
	v_mfma_f32_16x16x32_bf16 v[118:121], v[212:215], v[160:163], v[118:121]
	v_mfma_f32_16x16x32_bf16 v[114:117], v[220:223], v[160:163], v[114:117]
	v_mfma_f32_16x16x32_bf16 v[100:103], v[212:215], v[188:191], v[100:103]
	v_mfma_f32_16x16x32_bf16 v[96:99], v[220:223], v[188:191], v[96:99]
	v_mfma_f32_16x16x32_bf16 v[84:87], v[212:215], v[196:199], v[84:87]
	v_mfma_f32_16x16x32_bf16 v[80:83], v[220:223], v[196:199], v[80:83]
	v_mfma_f32_16x16x32_bf16 v[68:71], v[212:215], v[204:207], v[68:71]
	v_mfma_f32_16x16x32_bf16 v[64:67], v[220:223], v[204:207], v[64:67]
	v_mfma_f32_16x16x32_bf16 v[118:121], v[216:219], v[164:167], v[118:121]
	v_mfma_f32_16x16x32_bf16 v[114:117], v[224:227], v[164:167], v[114:117]
	v_mfma_f32_16x16x32_bf16 v[100:103], v[216:219], v[192:195], v[100:103]
	v_mfma_f32_16x16x32_bf16 v[96:99], v[224:227], v[192:195], v[96:99]
	v_mfma_f32_16x16x32_bf16 v[84:87], v[216:219], v[200:203], v[84:87]
	v_mfma_f32_16x16x32_bf16 v[80:83], v[224:227], v[200:203], v[80:83]
	v_mfma_f32_16x16x32_bf16 v[68:71], v[216:219], v[208:211], v[68:71]
	v_mfma_f32_16x16x32_bf16 v[64:67], v[224:227], v[208:211], v[64:67]
	s_setprio 0
	s_mov_b32 m0, s40
	v_lshl_add_u64 v[168:169], v[230:231], 0, s[2:3]
	s_barrier
	ds_read_b128 v[160:163], v143 offset:49152
	ds_read_b128 v[164:167], v143 offset:50176
	ds_read_b128 v[188:191], v143 offset:51200
	ds_read_b128 v[192:195], v143 offset:52224
	ds_read_b128 v[196:199], v143 offset:53248
	ds_read_b128 v[200:203], v143 offset:54272
	ds_read_b128 v[204:207], v143 offset:55296
	ds_read_b128 v[208:211], v143 offset:56320
	global_load_lds_dwordx4 v[168:169], off
	v_lshl_add_u64 v[168:169], v[232:233], 0, s[2:3]
	s_mov_b32 m0, s41
	s_nop 0
	global_load_lds_dwordx4 v[168:169], off
	s_barrier
	s_waitcnt lgkmcnt(0)
	s_setprio 1
	v_mfma_f32_16x16x32_bf16 v[60:63], v[144:147], v[160:163], v[60:63]
	v_mfma_f32_16x16x32_bf16 v[56:59], v[152:155], v[160:163], v[56:59]
	v_mfma_f32_16x16x32_bf16 v[44:47], v[144:147], v[188:191], v[44:47]
	v_mfma_f32_16x16x32_bf16 v[40:43], v[152:155], v[188:191], v[40:43]
	v_mfma_f32_16x16x32_bf16 v[28:31], v[144:147], v[196:199], v[28:31]
	v_mfma_f32_16x16x32_bf16 v[24:27], v[152:155], v[196:199], v[24:27]
	v_mfma_f32_16x16x32_bf16 v[12:15], v[144:147], v[204:207], v[12:15]
	v_mfma_f32_16x16x32_bf16 v[8:11], v[152:155], v[204:207], v[8:11]
	v_mfma_f32_16x16x32_bf16 v[60:63], v[148:151], v[164:167], v[60:63]
	v_mfma_f32_16x16x32_bf16 v[56:59], v[156:159], v[164:167], v[56:59]
	v_mfma_f32_16x16x32_bf16 v[44:47], v[148:151], v[192:195], v[44:47]
	v_mfma_f32_16x16x32_bf16 v[40:43], v[156:159], v[192:195], v[40:43]
	v_mfma_f32_16x16x32_bf16 v[28:31], v[148:151], v[200:203], v[28:31]
	v_mfma_f32_16x16x32_bf16 v[24:27], v[156:159], v[200:203], v[24:27]
	v_mfma_f32_16x16x32_bf16 v[12:15], v[148:151], v[208:211], v[12:15]
	v_mfma_f32_16x16x32_bf16 v[8:11], v[156:159], v[208:211], v[8:11]
	s_setprio 0
	s_barrier
	s_add_i32 s16, s16, s23
	v_lshl_add_u64 v[144:145], v[234:235], 0, s[2:3]
	s_mov_b32 m0, s16
	s_nop 0
	global_load_lds_dwordx4 v[144:145], off
	v_lshl_add_u64 v[144:145], v[236:237], 0, s[2:3]
	s_add_i32 m0, s16, 0x2000
	s_nop 0
	global_load_lds_dwordx4 v[144:145], off
	s_waitcnt vmcnt(6)
	s_barrier
	s_setprio 1
	v_mfma_f32_16x16x32_bf16 v[52:55], v[212:215], v[160:163], v[52:55]
	v_mfma_f32_16x16x32_bf16 v[48:51], v[220:223], v[160:163], v[48:51]
	v_mfma_f32_16x16x32_bf16 v[36:39], v[212:215], v[188:191], v[36:39]
	v_mfma_f32_16x16x32_bf16 v[32:35], v[220:223], v[188:191], v[32:35]
	v_mfma_f32_16x16x32_bf16 v[20:23], v[212:215], v[196:199], v[20:23]
	v_mfma_f32_16x16x32_bf16 v[16:19], v[220:223], v[196:199], v[16:19]
	v_mfma_f32_16x16x32_bf16 v[4:7], v[212:215], v[204:207], v[4:7]
	v_mfma_f32_16x16x32_bf16 v[0:3], v[220:223], v[204:207], v[0:3]
	v_mfma_f32_16x16x32_bf16 v[52:55], v[216:219], v[164:167], v[52:55]
	v_mfma_f32_16x16x32_bf16 v[48:51], v[224:227], v[164:167], v[48:51]
	v_mfma_f32_16x16x32_bf16 v[36:39], v[216:219], v[192:195], v[36:39]
	v_mfma_f32_16x16x32_bf16 v[32:35], v[224:227], v[192:195], v[32:35]
	v_mfma_f32_16x16x32_bf16 v[20:23], v[216:219], v[200:203], v[20:23]
	v_mfma_f32_16x16x32_bf16 v[16:19], v[224:227], v[200:203], v[16:19]
	v_mfma_f32_16x16x32_bf16 v[4:7], v[216:219], v[208:211], v[4:7]
	v_mfma_f32_16x16x32_bf16 v[0:3], v[224:227], v[208:211], v[0:3]
	s_setprio 0
	s_cmp_ge_i32 s31, s39
	s_mov_b64 s[16:17], s[18:19]
	s_mov_b32 s20, s31
	s_barrier
	s_cbranch_scc0 .LBB0_1200
	v_readlane_b32 s50, v255, 32
	s_mov_b32 s21, s59
	v_readlane_b32 s51, v255, 33
	v_readlane_b32 s52, v255, 34
	v_readlane_b32 s53, v255, 35
	s_branch .LBB0_1187

; #define PG8_STAGE(bufoff, gbase, voff) do { _Pragma("unroll") for (int _i = 0; _i < 2; ++_i) \
;         __builtin_amdgcn_global_load_lds((const unsigned*)((const char*)(gbase) + (voff)[_i]), (LAS unsigned*)(lds + (bufoff) + ldsw + _i * 8192), 16, 0, 0); } while (0)
; #define STG_A(bufoff, kb, h, usen) do { if constexpr (GATHER) { unsigned o_[2] = {(usen) ? noff[h][0] : coff[h][0], (usen) ? noff[h][1] : coff[h][1]}; PG8_STAGE(bufoff, (const char*)A + (kb), o_); } \
;         else { PG8_STAGE(bufoff, ((usen) ? nA : cA) + (kb) + (size_t)(h) * hstep, voffA); } } while (0)
; #define PG8_LDA(dst, b, h) do { _Pragma("unroll") for (int m = 0; m < 4; ++m) _Pragma("unroll") for (int k = 0; k < 2; ++k) dst[m][k] = *(const LAS bf16x8*)(lds + PG8_SA(b, h) + aoff + m * 2048 + k * 1024); } while (0)
; #define PG8_LDB(dst, b, h) do { _Pragma("unroll") for (int n = 0; n < 2; ++n) _Pragma("unroll") for (int k = 0; k < 2; ++k) dst[n][k] = *(const LAS bf16x8*)(lds + PG8_SB(b, h) + boff + n * 2048 + k * 1024); } while (0)
; #define PG8_WAIT_L(n) asm volatile("s_waitcnt lgkmcnt(" #n ")" ::: "memory")
; #define PG8_BAR __builtin_amdgcn_s_barrier()
; #define PG8_SCHED __builtin_amdgcn_sched_barrier(0)
; template <class Epi, bool GATHER = false>
; __device__ __forceinline__ void gemm_phase(LAS unsigned char* lds, const bf16_t* A, const bf16_t* Bt, const int K_, const Sched& S, const Epi& E, const int* gidx = nullptr) {
;     ...
;         for (int t = 0; t < nt; t += 2) {
;             const bool last = (t == nt - 2);
;             const size_t k1 = (size_t)(t + 1) * kstep, k2 = last ? (size_t)0 : (size_t)(t + 2) * kstep, k3 = k2 + kstep;
;             const char* b2 = last ? nB : cB + (size_t)(t + 2) * kstep;
;             const char* b3 = b2 + kstep;
;             PG8_LDB(B0, 0, 0); PG8_SCHED; PG8_LDA(At, 0, 0); STG_A(PG8_SA(1, 1), k1, 1, false);
;             PG8_WAIT_L(8); PG8_BAR; PG8_WAIT_L(0); PG8_MMA(0, 0, At, B0); PG8_BAR; PG8_SCHED;
;             PG8_LDB(B1, 0, 1); PG8_STAGE(PG8_SB(0, 0), b2, voffA);
;             PG8_BAR; PG8_WAIT_L(0); PG8_MMA(0, 1, At, B1); PG8_BAR;
;             PG8_LDA(At, 0, 1); STG_A(PG8_SA(0, 0), k2, 0, last);
;             PG8_BAR; PG8_WAIT_L(0); PG8_MMA(1, 0, At, B0); PG8_BAR; PG8_SCHED;
.LBB0_1496:
	s_cmp_eq_u32 s43, s50
	s_cselect_b64 vcc, -1, 0
	s_add_i32 s50, s50, 2
	s_add_u32 s31, s16, s4
	s_addc_u32 s33, s17, s5
	s_and_b64 s[20:21], vcc, exec
	s_cselect_b32 s21, s15, s33
	s_cselect_b32 s20, s14, s31
	s_add_i32 s31, 0, 0x10000
	v_add_u32_e32 v112, s31, v156
	ds_read_b128 v[158:161], v112
	ds_read_b128 v[162:165], v112 offset:1024
	ds_read_b128 v[166:169], v112 offset:2048
	ds_read_b128 v[188:191], v112 offset:3072
	s_and_b64 s[52:53], vcc, exec
	s_cselect_b32 s33, 0, s5
	s_cselect_b32 s51, 0, s4
	v_lshl_add_u64 v[224:225], s[18:19], 0, v[152:153]
	s_add_i32 m0, s37, 0xc000
	ds_read_b128 v[192:195], v157
	ds_read_b128 v[196:199], v157 offset:1024
	ds_read_b128 v[200:203], v157 offset:2048
	ds_read_b128 v[204:207], v157 offset:3072
	ds_read_b128 v[208:211], v157 offset:4096
	ds_read_b128 v[212:215], v157 offset:5120
	ds_read_b128 v[216:219], v157 offset:6144
	ds_read_b128 v[220:223], v157 offset:7168
	global_load_lds_dwordx4 v[224:225], off
	v_lshl_add_u64 v[224:225], s[18:19], 0, v[154:155]
	s_add_i32 m0, s37, 0xe000
	s_nop 0
	global_load_lds_dwordx4 v[224:225], off
	s_waitcnt lgkmcnt(8)
	s_barrier
	s_waitcnt lgkmcnt(0)
	s_setprio 1
	v_mfma_f32_16x16x32_bf16 v[126:129], v[158:161], v[192:195], v[126:129]
	v_mfma_f32_16x16x32_bf16 v[118:121], v[166:169], v[192:195], v[118:121]
	v_mfma_f32_16x16x32_bf16 v[108:111], v[158:161], v[200:203], v[108:111]
	v_mfma_f32_16x16x32_bf16 v[100:103], v[166:169], v[200:203], v[100:103]
	v_mfma_f32_16x16x32_bf16 v[92:95], v[158:161], v[208:211], v[92:95]
	v_mfma_f32_16x16x32_bf16 v[84:87], v[166:169], v[208:211], v[84:87]
	v_mfma_f32_16x16x32_bf16 v[76:79], v[158:161], v[216:219], v[76:79]
	v_mfma_f32_16x16x32_bf16 v[68:71], v[166:169], v[216:219], v[68:71]
	v_mfma_f32_16x16x32_bf16 v[126:129], v[162:165], v[196:199], v[126:129]
	v_mfma_f32_16x16x32_bf16 v[118:121], v[188:191], v[196:199], v[118:121]
	v_mfma_f32_16x16x32_bf16 v[108:111], v[162:165], v[204:207], v[108:111]
	v_mfma_f32_16x16x32_bf16 v[100:103], v[188:191], v[204:207], v[100:103]
	v_mfma_f32_16x16x32_bf16 v[92:95], v[162:165], v[212:215], v[92:95]
	v_mfma_f32_16x16x32_bf16 v[84:87], v[188:191], v[212:215], v[84:87]
	v_mfma_f32_16x16x32_bf16 v[76:79], v[162:165], v[220:223], v[76:79]
	v_mfma_f32_16x16x32_bf16 v[68:71], v[188:191], v[220:223], v[68:71]
	s_setprio 0
	s_barrier
	s_add_i32 s54, 0, 0x14000
	s_add_i32 s31, s31, s35
	v_add_u32_e32 v112, s54, v156
	v_lshl_add_u64 v[240:241], s[20:21], 0, v[132:133]
	s_mov_b32 m0, s31
	ds_read_b128 v[224:227], v112
	ds_read_b128 v[228:231], v112 offset:1024
	ds_read_b128 v[232:235], v112 offset:2048
	ds_read_b128 v[236:239], v112 offset:3072
	global_load_lds_dwordx4 v[240:241], off
	v_lshl_add_u64 v[242:243], s[20:21], 0, v[136:137]
	s_add_i32 m0, s31, 0x2000
	s_nop 0
	global_load_lds_dwordx4 v[242:243], off
	s_barrier
	s_waitcnt lgkmcnt(0)
	s_setprio 1
	v_mfma_f32_16x16x32_bf16 v[122:125], v[224:227], v[192:195], v[122:125]
	v_mfma_f32_16x16x32_bf16 v[114:117], v[232:235], v[192:195], v[114:117]
	v_mfma_f32_16x16x32_bf16 v[104:107], v[224:227], v[200:203], v[104:107]
	v_mfma_f32_16x16x32_bf16 v[96:99], v[232:235], v[200:203], v[96:99]
	v_mfma_f32_16x16x32_bf16 v[88:91], v[224:227], v[208:211], v[88:91]
	v_mfma_f32_16x16x32_bf16 v[80:83], v[232:235], v[208:211], v[80:83]
	v_mfma_f32_16x16x32_bf16 v[72:75], v[224:227], v[216:219], v[72:75]
	v_mfma_f32_16x16x32_bf16 v[64:67], v[232:235], v[216:219], v[64:67]
	v_mfma_f32_16x16x32_bf16 v[122:125], v[228:231], v[196:199], v[122:125]
	v_mfma_f32_16x16x32_bf16 v[114:117], v[236:239], v[196:199], v[114:117]
	v_mfma_f32_16x16x32_bf16 v[104:107], v[228:231], v[204:207], v[104:107]
	v_mfma_f32_16x16x32_bf16 v[96:99], v[236:239], v[204:207], v[96:99]
	v_mfma_f32_16x16x32_bf16 v[88:91], v[228:231], v[212:215], v[88:91]
	v_mfma_f32_16x16x32_bf16 v[80:83], v[236:239], v[212:215], v[80:83]
	v_mfma_f32_16x16x32_bf16 v[72:75], v[228:231], v[220:223], v[72:75]
	v_mfma_f32_16x16x32_bf16 v[64:67], v[236:239], v[220:223], v[64:67]
	s_setprio 0
	s_add_u32 s52, s56, s51
	s_mov_b32 m0, s37
	v_cndmask_b32_e32 v112, v148, v140, vcc
	s_addc_u32 s53, s57, s33
	s_barrier
	ds_read_b128 v[192:195], v157 offset:16384
	ds_read_b128 v[196:199], v157 offset:17408
	ds_read_b128 v[200:203], v157 offset:18432
	ds_read_b128 v[204:207], v157 offset:19456
	ds_read_b128 v[208:211], v157 offset:20480
	ds_read_b128 v[212:215], v157 offset:21504
	ds_read_b128 v[216:219], v157 offset:22528
	ds_read_b128 v[220:223], v157 offset:23552
	v_cndmask_b32_e32 v244, v150, v142, vcc
	global_load_lds_dwordx4 v112, s[52:53]
	s_mov_b32 m0, s38
	v_mov_b32_e32 v245, v113
	global_load_lds_dwordx4 v244, s[52:53]
	s_barrier
	s_waitcnt lgkmcnt(0)
	v_lshl_add_u64 v[246:247], s[52:53], 0, v[112:113]
	v_lshl_add_u64 v[244:245], s[52:53], 0, v[244:245]
	s_setprio 1
	s_waitcnt lgkmcnt(0)
	v_mfma_f32_16x16x32_bf16 v[60:63], v[158:161], v[192:195], v[60:63]
	v_mfma_f32_16x16x32_bf16 v[52:55], v[166:169], v[192:195], v[52:55]
	v_mfma_f32_16x16x32_bf16 v[44:47], v[158:161], v[200:203], v[44:47]
	v_mfma_f32_16x16x32_bf16 v[36:39], v[166:169], v[200:203], v[36:39]
	v_mfma_f32_16x16x32_bf16 v[28:31], v[158:161], v[208:211], v[28:31]
	v_mfma_f32_16x16x32_bf16 v[20:23], v[166:169], v[208:211], v[20:23]
	v_mfma_f32_16x16x32_bf16 v[12:15], v[158:161], v[216:219], v[12:15]
	v_mfma_f32_16x16x32_bf16 v[4:7], v[166:169], v[216:219], v[4:7]
	v_mfma_f32_16x16x32_bf16 v[60:63], v[162:165], v[196:199], v[60:63]
	v_mfma_f32_16x16x32_bf16 v[52:55], v[188:191], v[196:199], v[52:55]
	v_mfma_f32_16x16x32_bf16 v[44:47], v[162:165], v[204:207], v[44:47]
	v_mfma_f32_16x16x32_bf16 v[36:39], v[188:191], v[204:207], v[36:39]
	v_mfma_f32_16x16x32_bf16 v[28:31], v[162:165], v[212:215], v[28:31]
	v_mfma_f32_16x16x32_bf16 v[20:23], v[188:191], v[212:215], v[20:23]
	v_mfma_f32_16x16x32_bf16 v[12:15], v[162:165], v[220:223], v[12:15]
	v_mfma_f32_16x16x32_bf16 v[4:7], v[188:191], v[220:223], v[4:7]
	s_setprio 0
	s_barrier
; #define PG8_STAGE(bufoff, gbase, voff) do { _Pragma("unroll") for (int _i = 0; _i < 2; ++_i) \
;         __builtin_amdgcn_global_load_lds((const unsigned*)((const char*)(gbase) + (voff)[_i]), (LAS unsigned*)(lds + (bufoff) + ldsw + _i * 8192), 16, 0, 0); } while (0)
; #define STG_A(bufoff, kb, h, usen) do { if constexpr (GATHER) { unsigned o_[2] = {(usen) ? noff[h][0] : coff[h][0], (usen) ? noff[h][1] : coff[h][1]}; PG8_STAGE(bufoff, (const char*)A + (kb), o_); } \
;         else { PG8_STAGE(bufoff, ((usen) ? nA : cA) + (kb) + (size_t)(h) * hstep, voffA); } } while (0)
; #define PG8_LDA(dst, b, h) do { _Pragma("unroll") for (int m = 0; m < 4; ++m) _Pragma("unroll") for (int k = 0; k < 2; ++k) dst[m][k] = *(const LAS bf16x8*)(lds + PG8_SA(b, h) + aoff + m * 2048 + k * 1024); } while (0)
; #define PG8_LDB(dst, b, h) do { _Pragma("unroll") for (int n = 0; n < 2; ++n) _Pragma("unroll") for (int k = 0; k < 2; ++k) dst[n][k] = *(const LAS bf16x8*)(lds + PG8_SB(b, h) + boff + n * 2048 + k * 1024); } while (0)
; #define PG8_MMA(ai, bj, At, Bt_) do { __builtin_amdgcn_s_setprio(1); _Pragma("unroll") for (int m = 0; m < 4; ++m) _Pragma("unroll") for (int n = 0; n < 2; ++n) _Pragma("unroll") for (int k = 0; k < 2; ++k) \
;         acc[ai][bj][m][n] = __builtin_amdgcn_mfma_f32_16x16x32_bf16(Bt_[n][k], At[m][k], acc[ai][bj][m][n], 0, 0, 0); __builtin_amdgcn_s_setprio(0); } while (0)
; #define PG8_WAIT_V(n) asm volatile("s_waitcnt vmcnt(" #n ")" ::: "memory")
; #define PG8_WAIT_L(n) asm volatile("s_waitcnt lgkmcnt(" #n ")" ::: "memory")
; #define PG8_BAR __builtin_amdgcn_s_barrier()
; #define PG8_SCHED __builtin_amdgcn_sched_barrier(0)
; template <class Epi, bool GATHER = false>
; __device__ __forceinline__ void gemm_phase(LAS unsigned char* lds, const bf16_t* A, const bf16_t* Bt, const int K_, const Sched& S, const Epi& E, const int* gidx = nullptr) {
;     ...
;             PG8_STAGE(PG8_SB(0, 1), b2 + hstep, voffA);
;             PG8_WAIT_V(6); PG8_BAR; PG8_MMA(1, 1, At, B1); PG8_BAR;
;             PG8_LDB(B0, 1, 0); PG8_SCHED; PG8_LDA(At, 1, 0); STG_A(PG8_SA(0, 1), k2, 1, last);
;             PG8_WAIT_L(8); PG8_BAR; PG8_WAIT_L(0); PG8_MMA(0, 0, At, B0); PG8_BAR; PG8_SCHED;
;             PG8_LDB(B1, 1, 1); PG8_STAGE(PG8_SB(1, 0), b3, voffA);
;             PG8_BAR; PG8_WAIT_L(0); PG8_MMA(0, 1, At, B1); PG8_BAR;
	s_add_u32 s20, s20, s6
	s_addc_u32 s21, s21, s7
	s_add_i32 s31, s54, s35
	v_lshl_add_u64 v[248:249], s[20:21], 0, v[132:133]
	s_mov_b32 m0, s31
	v_lshl_add_u64 v[250:251], s[20:21], 0, v[136:137]
	global_load_lds_dwordx4 v[248:249], off
	s_add_i32 m0, s31, 0x2000
	s_nop 0
	global_load_lds_dwordx4 v[250:251], off
	s_waitcnt vmcnt(6)
	s_barrier
	s_setprio 1
	v_mfma_f32_16x16x32_bf16 v[56:59], v[224:227], v[192:195], v[56:59]
	v_mfma_f32_16x16x32_bf16 v[48:51], v[232:235], v[192:195], v[48:51]
	v_mfma_f32_16x16x32_bf16 v[40:43], v[224:227], v[200:203], v[40:43]
	v_mfma_f32_16x16x32_bf16 v[32:35], v[232:235], v[200:203], v[32:35]
	v_mfma_f32_16x16x32_bf16 v[24:27], v[224:227], v[208:211], v[24:27]
	v_mfma_f32_16x16x32_bf16 v[16:19], v[232:235], v[208:211], v[16:19]
	v_mfma_f32_16x16x32_bf16 v[8:11], v[224:227], v[216:219], v[8:11]
	v_mfma_f32_16x16x32_bf16 v[0:3], v[232:235], v[216:219], v[0:3]
	v_mfma_f32_16x16x32_bf16 v[56:59], v[228:231], v[196:199], v[56:59]
	v_mfma_f32_16x16x32_bf16 v[48:51], v[236:239], v[196:199], v[48:51]
	v_mfma_f32_16x16x32_bf16 v[40:43], v[228:231], v[204:207], v[40:43]
	v_mfma_f32_16x16x32_bf16 v[32:35], v[236:239], v[204:207], v[32:35]
	v_mfma_f32_16x16x32_bf16 v[24:27], v[228:231], v[212:215], v[24:27]
	v_mfma_f32_16x16x32_bf16 v[16:19], v[236:239], v[212:215], v[16:19]
	v_mfma_f32_16x16x32_bf16 v[8:11], v[228:231], v[220:223], v[8:11]
	v_mfma_f32_16x16x32_bf16 v[0:3], v[236:239], v[220:223], v[0:3]
	s_setprio 0
	s_add_i32 s20, 0, 0x18000
	v_add_u32_e32 v112, s20, v156
	s_barrier
	ds_read_b128 v[158:161], v112
	ds_read_b128 v[162:165], v112 offset:1024
	ds_read_b128 v[166:169], v112 offset:2048
	ds_read_b128 v[188:191], v112 offset:3072
	s_mov_b32 m0, s39
	v_cndmask_b32_e32 v112, v152, v144, vcc
	ds_read_b128 v[192:195], v157 offset:32768
	ds_read_b128 v[196:199], v157 offset:33792
	ds_read_b128 v[200:203], v157 offset:34816
	ds_read_b128 v[204:207], v157 offset:35840
	ds_read_b128 v[208:211], v157 offset:36864
	ds_read_b128 v[212:215], v157 offset:37888
	ds_read_b128 v[216:219], v157 offset:38912
	ds_read_b128 v[220:223], v157 offset:39936
	v_cndmask_b32_e32 v139, v154, v146, vcc
	global_load_lds_dwordx4 v112, s[52:53]
	s_mov_b32 m0, s40
	s_nop 0
	global_load_lds_dwordx4 v139, s[52:53]
	s_waitcnt lgkmcnt(8)
	s_barrier
	s_waitcnt lgkmcnt(0)
	s_setprio 1
	v_mfma_f32_16x16x32_bf16 v[126:129], v[158:161], v[192:195], v[126:129]
	v_mfma_f32_16x16x32_bf16 v[118:121], v[166:169], v[192:195], v[118:121]
	v_mfma_f32_16x16x32_bf16 v[108:111], v[158:161], v[200:203], v[108:111]
	v_mfma_f32_16x16x32_bf16 v[100:103], v[166:169], v[200:203], v[100:103]
	v_mfma_f32_16x16x32_bf16 v[92:95], v[158:161], v[208:211], v[92:95]
	v_mfma_f32_16x16x32_bf16 v[84:87], v[166:169], v[208:211], v[84:87]
	v_mfma_f32_16x16x32_bf16 v[76:79], v[158:161], v[216:219], v[76:79]
	v_mfma_f32_16x16x32_bf16 v[68:71], v[166:169], v[216:219], v[68:71]
	v_mfma_f32_16x16x32_bf16 v[126:129], v[162:165], v[196:199], v[126:129]
	v_mfma_f32_16x16x32_bf16 v[118:121], v[188:191], v[196:199], v[118:121]
	v_mfma_f32_16x16x32_bf16 v[108:111], v[162:165], v[204:207], v[108:111]
	v_mfma_f32_16x16x32_bf16 v[100:103], v[188:191], v[204:207], v[100:103]
	v_mfma_f32_16x16x32_bf16 v[92:95], v[162:165], v[212:215], v[92:95]
	v_mfma_f32_16x16x32_bf16 v[84:87], v[188:191], v[212:215], v[84:87]
	v_mfma_f32_16x16x32_bf16 v[76:79], v[162:165], v[220:223], v[76:79]
	v_mfma_f32_16x16x32_bf16 v[68:71], v[188:191], v[220:223], v[68:71]
	s_setprio 0
	s_barrier
	s_add_i32 s21, 0, 0x1c000
	s_add_i32 s20, s20, s35
	v_add_u32_e32 v112, s21, v156
	v_lshl_add_u64 v[240:241], v[240:241], 0, s[2:3]
	s_mov_b32 m0, s20
	ds_read_b128 v[224:227], v112
	ds_read_b128 v[228:231], v112 offset:1024
	ds_read_b128 v[232:235], v112 offset:2048
	ds_read_b128 v[236:239], v112 offset:3072
	global_load_lds_dwordx4 v[240:241], off
	v_lshl_add_u64 v[240:241], v[242:243], 0, s[2:3]
	s_add_i32 m0, s20, 0x2000
	s_nop 0
	global_load_lds_dwordx4 v[240:241], off
	s_barrier
; #define PG8_STAGE(bufoff, gbase, voff) do { _Pragma("unroll") for (int _i = 0; _i < 2; ++_i) \
;         __builtin_amdgcn_global_load_lds((const unsigned*)((const char*)(gbase) + (voff)[_i]), (LAS unsigned*)(lds + (bufoff) + ldsw + _i * 8192), 16, 0, 0); } while (0)
; #define STG_A(bufoff, kb, h, usen) do { if constexpr (GATHER) { unsigned o_[2] = {(usen) ? noff[h][0] : coff[h][0], (usen) ? noff[h][1] : coff[h][1]}; PG8_STAGE(bufoff, (const char*)A + (kb), o_); } \
;         else { PG8_STAGE(bufoff, ((usen) ? nA : cA) + (kb) + (size_t)(h) * hstep, voffA); } } while (0)
; #define PG8_LDA(dst, b, h) do { _Pragma("unroll") for (int m = 0; m < 4; ++m) _Pragma("unroll") for (int k = 0; k < 2; ++k) dst[m][k] = *(const LAS bf16x8*)(lds + PG8_SA(b, h) + aoff + m * 2048 + k * 1024); } while (0)
; #define PG8_LDB(dst, b, h) do { _Pragma("unroll") for (int n = 0; n < 2; ++n) _Pragma("unroll") for (int k = 0; k < 2; ++k) dst[n][k] = *(const LAS bf16x8*)(lds + PG8_SB(b, h) + boff + n * 2048 + k * 1024); } while (0)
; #define PG8_MMA(ai, bj, At, Bt_) do { __builtin_amdgcn_s_setprio(1); _Pragma("unroll") for (int m = 0; m < 4; ++m) _Pragma("unroll") for (int n = 0; n < 2; ++n) _Pragma("unroll") for (int k = 0; k < 2; ++k) \
;         acc[ai][bj][m][n] = __builtin_amdgcn_mfma_f32_16x16x32_bf16(Bt_[n][k], At[m][k], acc[ai][bj][m][n], 0, 0, 0); __builtin_amdgcn_s_setprio(0); } while (0)
; #define PG8_WAIT_V(n) asm volatile("s_waitcnt vmcnt(" #n ")" ::: "memory")
; #define PG8_WAIT_L(n) asm volatile("s_waitcnt lgkmcnt(" #n ")" ::: "memory")
; template <class Epi, bool GATHER = false>
; __device__ __forceinline__ void gemm_phase(LAS unsigned char* lds, const bf16_t* A, const bf16_t* Bt, const int K_, const Sched& S, const Epi& E, const int* gidx = nullptr) {
;     ...
;             PG8_WAIT_L(8); PG8_BAR; PG8_WAIT_L(0); PG8_MMA(0, 0, At, B0); PG8_BAR; PG8_SCHED;
;             PG8_LDB(B1, 1, 1); PG8_STAGE(PG8_SB(1, 0), b3, voffA);
;             PG8_BAR; PG8_WAIT_L(0); PG8_MMA(0, 1, At, B1); PG8_BAR;
;             PG8_LDA(At, 1, 1); STG_A(PG8_SA(1, 0), k3, 0, last);
;             PG8_BAR; PG8_WAIT_L(0); PG8_MMA(1, 0, At, B0); PG8_BAR; PG8_SCHED;
;             PG8_STAGE(PG8_SB(1, 1), b3 + hstep, voffA);
;             PG8_WAIT_V(6); PG8_BAR; PG8_MMA(1, 1, At, B1); PG8_BAR;
;         }
;         E(acc, cur, wr, wc, fr, fq);
;         if (!has_next) break;
	s_waitcnt lgkmcnt(0)
	s_setprio 1
	v_mfma_f32_16x16x32_bf16 v[122:125], v[224:227], v[192:195], v[122:125]
	v_mfma_f32_16x16x32_bf16 v[114:117], v[232:235], v[192:195], v[114:117]
	v_mfma_f32_16x16x32_bf16 v[104:107], v[224:227], v[200:203], v[104:107]
	v_mfma_f32_16x16x32_bf16 v[96:99], v[232:235], v[200:203], v[96:99]
	v_mfma_f32_16x16x32_bf16 v[88:91], v[224:227], v[208:211], v[88:91]
	v_mfma_f32_16x16x32_bf16 v[80:83], v[232:235], v[208:211], v[80:83]
	v_mfma_f32_16x16x32_bf16 v[72:75], v[224:227], v[216:219], v[72:75]
	v_mfma_f32_16x16x32_bf16 v[64:67], v[232:235], v[216:219], v[64:67]
	v_mfma_f32_16x16x32_bf16 v[122:125], v[228:231], v[196:199], v[122:125]
	v_mfma_f32_16x16x32_bf16 v[114:117], v[236:239], v[196:199], v[114:117]
	v_mfma_f32_16x16x32_bf16 v[104:107], v[228:231], v[204:207], v[104:107]
	v_mfma_f32_16x16x32_bf16 v[96:99], v[236:239], v[204:207], v[96:99]
	v_mfma_f32_16x16x32_bf16 v[88:91], v[228:231], v[212:215], v[88:91]
	v_mfma_f32_16x16x32_bf16 v[80:83], v[236:239], v[212:215], v[80:83]
	v_mfma_f32_16x16x32_bf16 v[72:75], v[228:231], v[220:223], v[72:75]
	v_mfma_f32_16x16x32_bf16 v[64:67], v[236:239], v[220:223], v[64:67]
	s_setprio 0
	s_mov_b32 m0, s41
	v_lshl_add_u64 v[240:241], v[246:247], 0, s[2:3]
	s_barrier
	ds_read_b128 v[192:195], v157 offset:49152
	ds_read_b128 v[196:199], v157 offset:50176
	ds_read_b128 v[200:203], v157 offset:51200
	ds_read_b128 v[204:207], v157 offset:52224
	ds_read_b128 v[208:211], v157 offset:53248
	ds_read_b128 v[212:215], v157 offset:54272
	ds_read_b128 v[216:219], v157 offset:55296
	ds_read_b128 v[220:223], v157 offset:56320
	global_load_lds_dwordx4 v[240:241], off
	v_lshl_add_u64 v[240:241], v[244:245], 0, s[2:3]
	s_mov_b32 m0, s42
	s_nop 0
	global_load_lds_dwordx4 v[240:241], off
	s_barrier
	s_waitcnt lgkmcnt(0)
	s_setprio 1
	v_mfma_f32_16x16x32_bf16 v[60:63], v[158:161], v[192:195], v[60:63]
	v_mfma_f32_16x16x32_bf16 v[52:55], v[166:169], v[192:195], v[52:55]
	v_mfma_f32_16x16x32_bf16 v[44:47], v[158:161], v[200:203], v[44:47]
	v_mfma_f32_16x16x32_bf16 v[36:39], v[166:169], v[200:203], v[36:39]
	v_mfma_f32_16x16x32_bf16 v[28:31], v[158:161], v[208:211], v[28:31]
	v_mfma_f32_16x16x32_bf16 v[20:23], v[166:169], v[208:211], v[20:23]
	v_mfma_f32_16x16x32_bf16 v[12:15], v[158:161], v[216:219], v[12:15]
	v_mfma_f32_16x16x32_bf16 v[4:7], v[166:169], v[216:219], v[4:7]
	v_mfma_f32_16x16x32_bf16 v[60:63], v[162:165], v[196:199], v[60:63]
	v_mfma_f32_16x16x32_bf16 v[52:55], v[188:191], v[196:199], v[52:55]
	v_mfma_f32_16x16x32_bf16 v[44:47], v[162:165], v[204:207], v[44:47]
	v_mfma_f32_16x16x32_bf16 v[36:39], v[188:191], v[204:207], v[36:39]
	v_mfma_f32_16x16x32_bf16 v[28:31], v[162:165], v[212:215], v[28:31]
	v_mfma_f32_16x16x32_bf16 v[20:23], v[188:191], v[212:215], v[20:23]
	v_mfma_f32_16x16x32_bf16 v[12:15], v[162:165], v[220:223], v[12:15]
	v_mfma_f32_16x16x32_bf16 v[4:7], v[188:191], v[220:223], v[4:7]
	s_setprio 0
	s_barrier
	s_add_i32 s20, s21, s35
	v_lshl_add_u64 v[158:159], v[248:249], 0, s[2:3]
	s_mov_b32 m0, s20
	s_nop 0
	global_load_lds_dwordx4 v[158:159], off
	v_lshl_add_u64 v[158:159], v[250:251], 0, s[2:3]
	s_add_i32 m0, s20, 0x2000
	s_nop 0
	global_load_lds_dwordx4 v[158:159], off
	s_waitcnt vmcnt(6)
	s_barrier
	s_setprio 1
	v_mfma_f32_16x16x32_bf16 v[56:59], v[224:227], v[192:195], v[56:59]
	v_mfma_f32_16x16x32_bf16 v[48:51], v[232:235], v[192:195], v[48:51]
	v_mfma_f32_16x16x32_bf16 v[40:43], v[224:227], v[200:203], v[40:43]
	v_mfma_f32_16x16x32_bf16 v[32:35], v[232:235], v[200:203], v[32:35]
	v_mfma_f32_16x16x32_bf16 v[24:27], v[224:227], v[208:211], v[24:27]
	v_mfma_f32_16x16x32_bf16 v[16:19], v[232:235], v[208:211], v[16:19]
	v_mfma_f32_16x16x32_bf16 v[8:11], v[224:227], v[216:219], v[8:11]
	v_mfma_f32_16x16x32_bf16 v[0:3], v[232:235], v[216:219], v[0:3]
	v_mfma_f32_16x16x32_bf16 v[56:59], v[228:231], v[196:199], v[56:59]
	v_mfma_f32_16x16x32_bf16 v[48:51], v[236:239], v[196:199], v[48:51]
	v_mfma_f32_16x16x32_bf16 v[40:43], v[228:231], v[204:207], v[40:43]
	v_mfma_f32_16x16x32_bf16 v[32:35], v[236:239], v[204:207], v[32:35]
	v_mfma_f32_16x16x32_bf16 v[24:27], v[228:231], v[212:215], v[24:27]
	v_mfma_f32_16x16x32_bf16 v[16:19], v[236:239], v[212:215], v[16:19]
	v_mfma_f32_16x16x32_bf16 v[8:11], v[228:231], v[220:223], v[8:11]
	v_mfma_f32_16x16x32_bf16 v[0:3], v[236:239], v[220:223], v[0:3]
	s_setprio 0
	s_add_u32 s4, s4, 0x100
	s_addc_u32 s5, s5, 0
	s_add_u32 s18, s18, 0x100
	s_addc_u32 s19, s19, 0
	s_cmp_ge_i32 s50, s1
	s_barrier
	s_cbranch_scc0 .LBB0_1496
	v_readlane_b32 s50, v255, 32
	s_mov_b64 s[20:21], s[58:59]
	v_readlane_b32 s51, v255, 33
	v_readlane_b32 s52, v255, 34
	v_readlane_b32 s53, v255, 35
	s_branch .LBB0_1487

; #define PG8_STAGE(bufoff, gbase, voff) do { _Pragma("unroll") for (int _i = 0; _i < 2; ++_i) \
;         __builtin_amdgcn_global_load_lds((const unsigned*)((const char*)(gbase) + (voff)[_i]), (LAS unsigned*)(lds + (bufoff) + ldsw + _i * 8192), 16, 0, 0); } while (0)
; #define STG_A(bufoff, kb, h, usen) do { if constexpr (GATHER) { unsigned o_[2] = {(usen) ? noff[h][0] : coff[h][0], (usen) ? noff[h][1] : coff[h][1]}; PG8_STAGE(bufoff, (const char*)A + (kb), o_); } \
;         else { PG8_STAGE(bufoff, ((usen) ? nA : cA) + (kb) + (size_t)(h) * hstep, voffA); } } while (0)
; #define PG8_LDA(dst, b, h) do { _Pragma("unroll") for (int m = 0; m < 4; ++m) _Pragma("unroll") for (int k = 0; k < 2; ++k) dst[m][k] = *(const LAS bf16x8*)(lds + PG8_SA(b, h) + aoff + m * 2048 + k * 1024); } while (0)
; #define PG8_LDB(dst, b, h) do { _Pragma("unroll") for (int n = 0; n < 2; ++n) _Pragma("unroll") for (int k = 0; k < 2; ++k) dst[n][k] = *(const LAS bf16x8*)(lds + PG8_SB(b, h) + boff + n * 2048 + k * 1024); } while (0)
; #define PG8_WAIT_V(n) asm volatile("s_waitcnt vmcnt(" #n ")" ::: "memory")
; #define PG8_WAIT_L(n) asm volatile("s_waitcnt lgkmcnt(" #n ")" ::: "memory")
; #define PG8_BAR __builtin_amdgcn_s_barrier()
; template <class Epi, bool GATHER = false>
; __device__ __forceinline__ void gemm_phase(LAS unsigned char* lds, const bf16_t* A, const bf16_t* Bt, const int K_, const Sched& S, const Epi& E, const int* gidx = nullptr) {
;     ...
;         for (int t = 0; t < nt; t += 2) {
;             const bool last = (t == nt - 2);
;             const size_t k1 = (size_t)(t + 1) * kstep, k2 = last ? (size_t)0 : (size_t)(t + 2) * kstep, k3 = k2 + kstep;
;             const char* b2 = last ? nB : cB + (size_t)(t + 2) * kstep;
;             const char* b3 = b2 + kstep;
;             PG8_LDB(B0, 0, 0); PG8_SCHED; PG8_LDA(At, 0, 0); STG_A(PG8_SA(1, 1), k1, 1, false);
;             PG8_WAIT_L(8); PG8_BAR; PG8_WAIT_L(0); PG8_MMA(0, 0, At, B0); PG8_BAR; PG8_SCHED;
;             PG8_LDB(B1, 0, 1); PG8_STAGE(PG8_SB(0, 0), b2, voffA);
;             PG8_BAR; PG8_WAIT_L(0); PG8_MMA(0, 1, At, B1); PG8_BAR;
;             PG8_LDA(At, 0, 1); STG_A(PG8_SA(0, 0), k2, 0, last);
;             PG8_BAR; PG8_WAIT_L(0); PG8_MMA(1, 0, At, B0); PG8_BAR; PG8_SCHED;
;             PG8_STAGE(PG8_SB(0, 1), b2 + hstep, voffA);
;             PG8_WAIT_V(6); PG8_BAR; PG8_MMA(1, 1, At, B1); PG8_BAR;
.LBB0_1581:
	s_add_i32 s31, s20, 2
	s_add_u32 s18, s16, 0x100
	s_addc_u32 s19, s17, 0
	s_add_u32 s33, s51, s16
	s_addc_u32 s21, s52, s17
	s_add_i32 s53, 0, 0x10000
	v_add_u32_e32 v145, s53, v143
	ds_read_b128 v[146:149], v145
	ds_read_b128 v[150:153], v145 offset:1024
	ds_read_b128 v[154:157], v145 offset:2048
	ds_read_b128 v[158:161], v145 offset:3072
	s_add_i32 s56, s53, s35
	s_add_i32 m0, s37, 0xc000
	s_add_i32 s54, s37, 0xe000
	s_add_i32 s55, 0, 0x14000
	s_add_i32 s57, s56, 0x2000
	s_cmp_eq_u32 s44, s20
	s_cselect_b32 s20, s4, s33
	s_cselect_b32 s21, s5, s21
	s_cselect_b32 s33, 0, s19
	s_cselect_b32 s53, 0, s18
	v_lshl_add_u64 v[212:213], v[138:139], 0, s[16:17]
	ds_read_b128 v[162:165], v144
	ds_read_b128 v[166:169], v144 offset:1024
	ds_read_b128 v[188:191], v144 offset:2048
	ds_read_b128 v[192:195], v144 offset:3072
	ds_read_b128 v[196:199], v144 offset:4096
	ds_read_b128 v[200:203], v144 offset:5120
	ds_read_b128 v[204:207], v144 offset:6144
	ds_read_b128 v[208:211], v144 offset:7168
	global_load_lds_dwordx4 v[212:213], off
	v_lshl_add_u64 v[212:213], v[140:141], 0, s[16:17]
	s_mov_b32 m0, s54
	s_nop 0
	global_load_lds_dwordx4 v[212:213], off
	s_waitcnt lgkmcnt(8)
	s_barrier
	s_waitcnt lgkmcnt(0)
	s_setprio 1
	v_mfma_f32_16x16x32_bf16 v[126:129], v[146:149], v[162:165], v[126:129]
	v_mfma_f32_16x16x32_bf16 v[122:125], v[154:157], v[162:165], v[122:125]
	v_mfma_f32_16x16x32_bf16 v[108:111], v[146:149], v[188:191], v[108:111]
	v_mfma_f32_16x16x32_bf16 v[104:107], v[154:157], v[188:191], v[104:107]
	v_mfma_f32_16x16x32_bf16 v[92:95], v[146:149], v[196:199], v[92:95]
	v_mfma_f32_16x16x32_bf16 v[88:91], v[154:157], v[196:199], v[88:91]
	v_mfma_f32_16x16x32_bf16 v[76:79], v[146:149], v[204:207], v[76:79]
	v_mfma_f32_16x16x32_bf16 v[72:75], v[154:157], v[204:207], v[72:75]
	v_mfma_f32_16x16x32_bf16 v[126:129], v[150:153], v[166:169], v[126:129]
	v_mfma_f32_16x16x32_bf16 v[122:125], v[158:161], v[166:169], v[122:125]
	v_mfma_f32_16x16x32_bf16 v[108:111], v[150:153], v[192:195], v[108:111]
	v_mfma_f32_16x16x32_bf16 v[104:107], v[158:161], v[192:195], v[104:107]
	v_mfma_f32_16x16x32_bf16 v[92:95], v[150:153], v[200:203], v[92:95]
	v_mfma_f32_16x16x32_bf16 v[88:91], v[158:161], v[200:203], v[88:91]
	v_mfma_f32_16x16x32_bf16 v[76:79], v[150:153], v[208:211], v[76:79]
	v_mfma_f32_16x16x32_bf16 v[72:75], v[158:161], v[208:211], v[72:75]
	s_setprio 0
	s_barrier
	s_mov_b32 m0, s56
	v_add_u32_e32 v145, s55, v143
	v_lshl_add_u64 v[228:229], s[20:21], 0, v[132:133]
	ds_read_b128 v[212:215], v145
	ds_read_b128 v[216:219], v145 offset:1024
	ds_read_b128 v[220:223], v145 offset:2048
	ds_read_b128 v[224:227], v145 offset:3072
	global_load_lds_dwordx4 v[228:229], off
	v_lshl_add_u64 v[230:231], s[20:21], 0, v[130:131]
	s_mov_b32 m0, s57
	s_nop 0
	global_load_lds_dwordx4 v[230:231], off
	s_barrier
	s_waitcnt lgkmcnt(0)
	s_setprio 1
	v_mfma_f32_16x16x32_bf16 v[118:121], v[212:215], v[162:165], v[118:121]
	v_mfma_f32_16x16x32_bf16 v[114:117], v[220:223], v[162:165], v[114:117]
	v_mfma_f32_16x16x32_bf16 v[100:103], v[212:215], v[188:191], v[100:103]
	v_mfma_f32_16x16x32_bf16 v[96:99], v[220:223], v[188:191], v[96:99]
	v_mfma_f32_16x16x32_bf16 v[84:87], v[212:215], v[196:199], v[84:87]
	v_mfma_f32_16x16x32_bf16 v[80:83], v[220:223], v[196:199], v[80:83]
	v_mfma_f32_16x16x32_bf16 v[68:71], v[212:215], v[204:207], v[68:71]
	v_mfma_f32_16x16x32_bf16 v[64:67], v[220:223], v[204:207], v[64:67]
	v_mfma_f32_16x16x32_bf16 v[118:121], v[216:219], v[166:169], v[118:121]
	v_mfma_f32_16x16x32_bf16 v[114:117], v[224:227], v[166:169], v[114:117]
	v_mfma_f32_16x16x32_bf16 v[100:103], v[216:219], v[192:195], v[100:103]
	v_mfma_f32_16x16x32_bf16 v[96:99], v[224:227], v[192:195], v[96:99]
	v_mfma_f32_16x16x32_bf16 v[84:87], v[216:219], v[200:203], v[84:87]
	v_mfma_f32_16x16x32_bf16 v[80:83], v[224:227], v[200:203], v[80:83]
	v_mfma_f32_16x16x32_bf16 v[68:71], v[216:219], v[208:211], v[68:71]
	v_mfma_f32_16x16x32_bf16 v[64:67], v[224:227], v[208:211], v[64:67]
	s_setprio 0
	s_cselect_b32 s16, s12, s14
	s_cselect_b32 s17, s13, s15
	s_add_u32 s16, s16, s53
	s_addc_u32 s17, s17, s33
	s_mov_b32 m0, s37
	v_lshl_add_u64 v[232:233], s[16:17], 0, v[132:133]
	s_barrier
	ds_read_b128 v[162:165], v144 offset:16384
	ds_read_b128 v[166:169], v144 offset:17408
	ds_read_b128 v[188:191], v144 offset:18432
	ds_read_b128 v[192:195], v144 offset:19456
	ds_read_b128 v[196:199], v144 offset:20480
	ds_read_b128 v[200:203], v144 offset:21504
	ds_read_b128 v[204:207], v144 offset:22528
	ds_read_b128 v[208:211], v144 offset:23552
	global_load_lds_dwordx4 v[232:233], off
	v_lshl_add_u64 v[234:235], s[16:17], 0, v[130:131]
	s_mov_b32 m0, s38
	s_nop 0
	global_load_lds_dwordx4 v[234:235], off
	s_barrier
	s_waitcnt lgkmcnt(0)
	s_setprio 1
	v_mfma_f32_16x16x32_bf16 v[60:63], v[146:149], v[162:165], v[60:63]
	v_mfma_f32_16x16x32_bf16 v[56:59], v[154:157], v[162:165], v[56:59]
	v_mfma_f32_16x16x32_bf16 v[44:47], v[146:149], v[188:191], v[44:47]
	v_mfma_f32_16x16x32_bf16 v[40:43], v[154:157], v[188:191], v[40:43]
	v_mfma_f32_16x16x32_bf16 v[28:31], v[146:149], v[196:199], v[28:31]
	v_mfma_f32_16x16x32_bf16 v[24:27], v[154:157], v[196:199], v[24:27]
	v_mfma_f32_16x16x32_bf16 v[12:15], v[146:149], v[204:207], v[12:15]
	v_mfma_f32_16x16x32_bf16 v[8:11], v[154:157], v[204:207], v[8:11]
	v_mfma_f32_16x16x32_bf16 v[60:63], v[150:153], v[166:169], v[60:63]
	v_mfma_f32_16x16x32_bf16 v[56:59], v[158:161], v[166:169], v[56:59]
	v_mfma_f32_16x16x32_bf16 v[44:47], v[150:153], v[192:195], v[44:47]
	v_mfma_f32_16x16x32_bf16 v[40:43], v[158:161], v[192:195], v[40:43]
	v_mfma_f32_16x16x32_bf16 v[28:31], v[150:153], v[200:203], v[28:31]
	v_mfma_f32_16x16x32_bf16 v[24:27], v[158:161], v[200:203], v[24:27]
	v_mfma_f32_16x16x32_bf16 v[12:15], v[150:153], v[208:211], v[12:15]
	v_mfma_f32_16x16x32_bf16 v[8:11], v[158:161], v[208:211], v[8:11]
	s_setprio 0
	s_barrier
; #define PG8_STAGE(bufoff, gbase, voff) do { _Pragma("unroll") for (int _i = 0; _i < 2; ++_i) \
;         __builtin_amdgcn_global_load_lds((const unsigned*)((const char*)(gbase) + (voff)[_i]), (LAS unsigned*)(lds + (bufoff) + ldsw + _i * 8192), 16, 0, 0); } while (0)
; #define STG_A(bufoff, kb, h, usen) do { if constexpr (GATHER) { unsigned o_[2] = {(usen) ? noff[h][0] : coff[h][0], (usen) ? noff[h][1] : coff[h][1]}; PG8_STAGE(bufoff, (const char*)A + (kb), o_); } \
;         else { PG8_STAGE(bufoff, ((usen) ? nA : cA) + (kb) + (size_t)(h) * hstep, voffA); } } while (0)
; #define PG8_LDA(dst, b, h) do { _Pragma("unroll") for (int m = 0; m < 4; ++m) _Pragma("unroll") for (int k = 0; k < 2; ++k) dst[m][k] = *(const LAS bf16x8*)(lds + PG8_SA(b, h) + aoff + m * 2048 + k * 1024); } while (0)
; #define PG8_LDB(dst, b, h) do { _Pragma("unroll") for (int n = 0; n < 2; ++n) _Pragma("unroll") for (int k = 0; k < 2; ++k) dst[n][k] = *(const LAS bf16x8*)(lds + PG8_SB(b, h) + boff + n * 2048 + k * 1024); } while (0)
; #define PG8_MMA(ai, bj, At, Bt_) do { __builtin_amdgcn_s_setprio(1); _Pragma("unroll") for (int m = 0; m < 4; ++m) _Pragma("unroll") for (int n = 0; n < 2; ++n) _Pragma("unroll") for (int k = 0; k < 2; ++k) \
;         acc[ai][bj][m][n] = __builtin_amdgcn_mfma_f32_16x16x32_bf16(Bt_[n][k], At[m][k], acc[ai][bj][m][n], 0, 0, 0); __builtin_amdgcn_s_setprio(0); } while (0)
; #define PG8_WAIT_V(n) asm volatile("s_waitcnt vmcnt(" #n ")" ::: "memory")
; #define PG8_WAIT_L(n) asm volatile("s_waitcnt lgkmcnt(" #n ")" ::: "memory")
; template <class Epi, bool GATHER = false>
; __device__ __forceinline__ void gemm_phase(LAS unsigned char* lds, const bf16_t* A, const bf16_t* Bt, const int K_, const Sched& S, const Epi& E, const int* gidx = nullptr) {
;     ...
;             PG8_STAGE(PG8_SB(0, 1), b2 + hstep, voffA);
;             PG8_WAIT_V(6); PG8_BAR; PG8_MMA(1, 1, At, B1); PG8_BAR;
;             PG8_LDB(B0, 1, 0); PG8_SCHED; PG8_LDA(At, 1, 0); STG_A(PG8_SA(0, 1), k2, 1, last);
;             PG8_WAIT_L(8); PG8_BAR; PG8_WAIT_L(0); PG8_MMA(0, 0, At, B0); PG8_BAR; PG8_SCHED;
;             PG8_LDB(B1, 1, 1); PG8_STAGE(PG8_SB(1, 0), b3, voffA);
;             PG8_BAR; PG8_WAIT_L(0); PG8_MMA(0, 1, At, B1); PG8_BAR;
;             PG8_LDA(At, 1, 1); STG_A(PG8_SA(1, 0), k3, 0, last);
;             PG8_BAR; PG8_WAIT_L(0); PG8_MMA(1, 0, At, B0); PG8_BAR; PG8_SCHED;
	s_add_u32 s20, s20, s0
	s_addc_u32 s21, s21, s1
	s_add_i32 s33, s55, s35
	v_lshl_add_u64 v[236:237], s[20:21], 0, v[132:133]
	s_mov_b32 m0, s33
	v_lshl_add_u64 v[238:239], s[20:21], 0, v[130:131]
	global_load_lds_dwordx4 v[236:237], off
	s_add_i32 m0, s33, 0x2000
	s_nop 0
	global_load_lds_dwordx4 v[238:239], off
	s_waitcnt vmcnt(6)
	s_barrier
	s_setprio 1
	v_mfma_f32_16x16x32_bf16 v[52:55], v[212:215], v[162:165], v[52:55]
	v_mfma_f32_16x16x32_bf16 v[48:51], v[220:223], v[162:165], v[48:51]
	v_mfma_f32_16x16x32_bf16 v[36:39], v[212:215], v[188:191], v[36:39]
	v_mfma_f32_16x16x32_bf16 v[32:35], v[220:223], v[188:191], v[32:35]
	v_mfma_f32_16x16x32_bf16 v[20:23], v[212:215], v[196:199], v[20:23]
	v_mfma_f32_16x16x32_bf16 v[16:19], v[220:223], v[196:199], v[16:19]
	v_mfma_f32_16x16x32_bf16 v[4:7], v[212:215], v[204:207], v[4:7]
	v_mfma_f32_16x16x32_bf16 v[0:3], v[220:223], v[204:207], v[0:3]
	v_mfma_f32_16x16x32_bf16 v[52:55], v[216:219], v[166:169], v[52:55]
	v_mfma_f32_16x16x32_bf16 v[48:51], v[224:227], v[166:169], v[48:51]
	v_mfma_f32_16x16x32_bf16 v[36:39], v[216:219], v[192:195], v[36:39]
	v_mfma_f32_16x16x32_bf16 v[32:35], v[224:227], v[192:195], v[32:35]
	v_mfma_f32_16x16x32_bf16 v[20:23], v[216:219], v[200:203], v[20:23]
	v_mfma_f32_16x16x32_bf16 v[16:19], v[224:227], v[200:203], v[16:19]
	v_mfma_f32_16x16x32_bf16 v[4:7], v[216:219], v[208:211], v[4:7]
	v_mfma_f32_16x16x32_bf16 v[0:3], v[224:227], v[208:211], v[0:3]
	s_setprio 0
	s_add_i32 s20, 0, 0x18000
	v_add_u32_e32 v145, s20, v143
	s_barrier
	ds_read_b128 v[146:149], v145
	ds_read_b128 v[150:153], v145 offset:1024
	ds_read_b128 v[154:157], v145 offset:2048
	ds_read_b128 v[158:161], v145 offset:3072
	s_add_u32 s16, s16, s0
	s_addc_u32 s17, s17, s1
	s_mov_b32 m0, s39
	v_lshl_add_u64 v[212:213], s[16:17], 0, v[132:133]
	ds_read_b128 v[162:165], v144 offset:32768
	ds_read_b128 v[166:169], v144 offset:33792
	ds_read_b128 v[188:191], v144 offset:34816
	ds_read_b128 v[192:195], v144 offset:35840
	ds_read_b128 v[196:199], v144 offset:36864
	ds_read_b128 v[200:203], v144 offset:37888
	ds_read_b128 v[204:207], v144 offset:38912
	ds_read_b128 v[208:211], v144 offset:39936
	global_load_lds_dwordx4 v[212:213], off
	v_lshl_add_u64 v[212:213], s[16:17], 0, v[130:131]
	s_mov_b32 m0, s40
	s_nop 0
	global_load_lds_dwordx4 v[212:213], off
	s_waitcnt lgkmcnt(8)
	s_barrier
	s_waitcnt lgkmcnt(0)
	s_setprio 1
	v_mfma_f32_16x16x32_bf16 v[126:129], v[146:149], v[162:165], v[126:129]
	v_mfma_f32_16x16x32_bf16 v[122:125], v[154:157], v[162:165], v[122:125]
	v_mfma_f32_16x16x32_bf16 v[108:111], v[146:149], v[188:191], v[108:111]
	v_mfma_f32_16x16x32_bf16 v[104:107], v[154:157], v[188:191], v[104:107]
	v_mfma_f32_16x16x32_bf16 v[92:95], v[146:149], v[196:199], v[92:95]
	v_mfma_f32_16x16x32_bf16 v[88:91], v[154:157], v[196:199], v[88:91]
	v_mfma_f32_16x16x32_bf16 v[76:79], v[146:149], v[204:207], v[76:79]
	v_mfma_f32_16x16x32_bf16 v[72:75], v[154:157], v[204:207], v[72:75]
	v_mfma_f32_16x16x32_bf16 v[126:129], v[150:153], v[166:169], v[126:129]
	v_mfma_f32_16x16x32_bf16 v[122:125], v[158:161], v[166:169], v[122:125]
	v_mfma_f32_16x16x32_bf16 v[108:111], v[150:153], v[192:195], v[108:111]
	v_mfma_f32_16x16x32_bf16 v[104:107], v[158:161], v[192:195], v[104:107]
	v_mfma_f32_16x16x32_bf16 v[92:95], v[150:153], v[200:203], v[92:95]
	v_mfma_f32_16x16x32_bf16 v[88:91], v[158:161], v[200:203], v[88:91]
	v_mfma_f32_16x16x32_bf16 v[76:79], v[150:153], v[208:211], v[76:79]
	v_mfma_f32_16x16x32_bf16 v[72:75], v[158:161], v[208:211], v[72:75]
	s_setprio 0
	s_barrier
	s_add_i32 s16, 0, 0x1c000
	s_add_i32 s17, s20, s35
	v_add_u32_e32 v145, s16, v143
	v_lshl_add_u64 v[228:229], v[228:229], 0, s[2:3]
	s_mov_b32 m0, s17
	ds_read_b128 v[212:215], v145
	ds_read_b128 v[216:219], v145 offset:1024
	ds_read_b128 v[220:223], v145 offset:2048
	ds_read_b128 v[224:227], v145 offset:3072
	global_load_lds_dwordx4 v[228:229], off
	v_lshl_add_u64 v[228:229], v[230:231], 0, s[2:3]
	s_add_i32 m0, s17, 0x2000
	s_nop 0
	global_load_lds_dwordx4 v[228:229], off
	s_barrier
; #define PG8_STAGE(bufoff, gbase, voff) do { _Pragma("unroll") for (int _i = 0; _i < 2; ++_i) \
;         __builtin_amdgcn_global_load_lds((const unsigned*)((const char*)(gbase) + (voff)[_i]), (LAS unsigned*)(lds + (bufoff) + ldsw + _i * 8192), 16, 0, 0); } while (0)
; #define STG_A(bufoff, kb, h, usen) do { if constexpr (GATHER) { unsigned o_[2] = {(usen) ? noff[h][0] : coff[h][0], (usen) ? noff[h][1] : coff[h][1]}; PG8_STAGE(bufoff, (const char*)A + (kb), o_); } \
;         else { PG8_STAGE(bufoff, ((usen) ? nA : cA) + (kb) + (size_t)(h) * hstep, voffA); } } while (0)
; #define PG8_LDA(dst, b, h) do { _Pragma("unroll") for (int m = 0; m < 4; ++m) _Pragma("unroll") for (int k = 0; k < 2; ++k) dst[m][k] = *(const LAS bf16x8*)(lds + PG8_SA(b, h) + aoff + m * 2048 + k * 1024); } while (0)
; #define PG8_MMA(ai, bj, At, Bt_) do { __builtin_amdgcn_s_setprio(1); _Pragma("unroll") for (int m = 0; m < 4; ++m) _Pragma("unroll") for (int n = 0; n < 2; ++n) _Pragma("unroll") for (int k = 0; k < 2; ++k) \
;         acc[ai][bj][m][n] = __builtin_amdgcn_mfma_f32_16x16x32_bf16(Bt_[n][k], At[m][k], acc[ai][bj][m][n], 0, 0, 0); __builtin_amdgcn_s_setprio(0); } while (0)
; #define PG8_WAIT_V(n) asm volatile("s_waitcnt vmcnt(" #n ")" ::: "memory")
; #define PG8_WAIT_L(n) asm volatile("s_waitcnt lgkmcnt(" #n ")" ::: "memory")
; #define PG8_BAR __builtin_amdgcn_s_barrier()
; #define PG8_SCHED __builtin_amdgcn_sched_barrier(0)
; template <class Epi, bool GATHER = false>
; __device__ __forceinline__ void gemm_phase(LAS unsigned char* lds, const bf16_t* A, const bf16_t* Bt, const int K_, const Sched& S, const Epi& E, const int* gidx = nullptr) {
;     ...
;             PG8_LDA(At, 1, 1); STG_A(PG8_SA(1, 0), k3, 0, last);
;             PG8_BAR; PG8_WAIT_L(0); PG8_MMA(1, 0, At, B0); PG8_BAR; PG8_SCHED;
;             PG8_STAGE(PG8_SB(1, 1), b3 + hstep, voffA);
;             PG8_WAIT_V(6); PG8_BAR; PG8_MMA(1, 1, At, B1); PG8_BAR;
;         }
;         E(acc, cur, wr, wc, fr, fq);
;         if (!has_next) break;
	s_waitcnt lgkmcnt(0)
	s_setprio 1
	v_mfma_f32_16x16x32_bf16 v[118:121], v[212:215], v[162:165], v[118:121]
	v_mfma_f32_16x16x32_bf16 v[114:117], v[220:223], v[162:165], v[114:117]
	v_mfma_f32_16x16x32_bf16 v[100:103], v[212:215], v[188:191], v[100:103]
	v_mfma_f32_16x16x32_bf16 v[96:99], v[220:223], v[188:191], v[96:99]
	v_mfma_f32_16x16x32_bf16 v[84:87], v[212:215], v[196:199], v[84:87]
	v_mfma_f32_16x16x32_bf16 v[80:83], v[220:223], v[196:199], v[80:83]
	v_mfma_f32_16x16x32_bf16 v[68:71], v[212:215], v[204:207], v[68:71]
	v_mfma_f32_16x16x32_bf16 v[64:67], v[220:223], v[204:207], v[64:67]
	v_mfma_f32_16x16x32_bf16 v[118:121], v[216:219], v[166:169], v[118:121]
	v_mfma_f32_16x16x32_bf16 v[114:117], v[224:227], v[166:169], v[114:117]
	v_mfma_f32_16x16x32_bf16 v[100:103], v[216:219], v[192:195], v[100:103]
	v_mfma_f32_16x16x32_bf16 v[96:99], v[224:227], v[192:195], v[96:99]
	v_mfma_f32_16x16x32_bf16 v[84:87], v[216:219], v[200:203], v[84:87]
	v_mfma_f32_16x16x32_bf16 v[80:83], v[224:227], v[200:203], v[80:83]
	v_mfma_f32_16x16x32_bf16 v[68:71], v[216:219], v[208:211], v[68:71]
	v_mfma_f32_16x16x32_bf16 v[64:67], v[224:227], v[208:211], v[64:67]
	s_setprio 0
	s_mov_b32 m0, s41
	v_lshl_add_u64 v[228:229], v[232:233], 0, s[2:3]
	s_barrier
	ds_read_b128 v[162:165], v144 offset:49152
	ds_read_b128 v[166:169], v144 offset:50176
	ds_read_b128 v[188:191], v144 offset:51200
	ds_read_b128 v[192:195], v144 offset:52224
	ds_read_b128 v[196:199], v144 offset:53248
	ds_read_b128 v[200:203], v144 offset:54272
	ds_read_b128 v[204:207], v144 offset:55296
	ds_read_b128 v[208:211], v144 offset:56320
	global_load_lds_dwordx4 v[228:229], off
	v_lshl_add_u64 v[228:229], v[234:235], 0, s[2:3]
	s_mov_b32 m0, s42
	s_nop 0
	global_load_lds_dwordx4 v[228:229], off
	s_barrier
	s_waitcnt lgkmcnt(0)
	s_setprio 1
	v_mfma_f32_16x16x32_bf16 v[60:63], v[146:149], v[162:165], v[60:63]
	v_mfma_f32_16x16x32_bf16 v[56:59], v[154:157], v[162:165], v[56:59]
	v_mfma_f32_16x16x32_bf16 v[44:47], v[146:149], v[188:191], v[44:47]
	v_mfma_f32_16x16x32_bf16 v[40:43], v[154:157], v[188:191], v[40:43]
	v_mfma_f32_16x16x32_bf16 v[28:31], v[146:149], v[196:199], v[28:31]
	v_mfma_f32_16x16x32_bf16 v[24:27], v[154:157], v[196:199], v[24:27]
	v_mfma_f32_16x16x32_bf16 v[12:15], v[146:149], v[204:207], v[12:15]
	v_mfma_f32_16x16x32_bf16 v[8:11], v[154:157], v[204:207], v[8:11]
	v_mfma_f32_16x16x32_bf16 v[60:63], v[150:153], v[166:169], v[60:63]
	v_mfma_f32_16x16x32_bf16 v[56:59], v[158:161], v[166:169], v[56:59]
	v_mfma_f32_16x16x32_bf16 v[44:47], v[150:153], v[192:195], v[44:47]
	v_mfma_f32_16x16x32_bf16 v[40:43], v[158:161], v[192:195], v[40:43]
	v_mfma_f32_16x16x32_bf16 v[28:31], v[150:153], v[200:203], v[28:31]
	v_mfma_f32_16x16x32_bf16 v[24:27], v[158:161], v[200:203], v[24:27]
	v_mfma_f32_16x16x32_bf16 v[12:15], v[150:153], v[208:211], v[12:15]
	v_mfma_f32_16x16x32_bf16 v[8:11], v[158:161], v[208:211], v[8:11]
	s_setprio 0
	s_barrier
	s_add_i32 s16, s16, s35
	v_lshl_add_u64 v[146:147], v[236:237], 0, s[2:3]
	s_mov_b32 m0, s16
	s_nop 0
	global_load_lds_dwordx4 v[146:147], off
	v_lshl_add_u64 v[146:147], v[238:239], 0, s[2:3]
	s_add_i32 m0, s16, 0x2000
	s_nop 0
	global_load_lds_dwordx4 v[146:147], off
	s_waitcnt vmcnt(6)
	s_barrier
	s_setprio 1
	v_mfma_f32_16x16x32_bf16 v[52:55], v[212:215], v[162:165], v[52:55]
	v_mfma_f32_16x16x32_bf16 v[48:51], v[220:223], v[162:165], v[48:51]
	v_mfma_f32_16x16x32_bf16 v[36:39], v[212:215], v[188:191], v[36:39]
	v_mfma_f32_16x16x32_bf16 v[32:35], v[220:223], v[188:191], v[32:35]
	v_mfma_f32_16x16x32_bf16 v[20:23], v[212:215], v[196:199], v[20:23]
	v_mfma_f32_16x16x32_bf16 v[16:19], v[220:223], v[196:199], v[16:19]
	v_mfma_f32_16x16x32_bf16 v[4:7], v[212:215], v[204:207], v[4:7]
	v_mfma_f32_16x16x32_bf16 v[0:3], v[220:223], v[204:207], v[0:3]
	v_mfma_f32_16x16x32_bf16 v[52:55], v[216:219], v[166:169], v[52:55]
	v_mfma_f32_16x16x32_bf16 v[48:51], v[224:227], v[166:169], v[48:51]
	v_mfma_f32_16x16x32_bf16 v[36:39], v[216:219], v[192:195], v[36:39]
	v_mfma_f32_16x16x32_bf16 v[32:35], v[224:227], v[192:195], v[32:35]
	v_mfma_f32_16x16x32_bf16 v[20:23], v[216:219], v[200:203], v[20:23]
	v_mfma_f32_16x16x32_bf16 v[16:19], v[224:227], v[200:203], v[16:19]
	v_mfma_f32_16x16x32_bf16 v[4:7], v[216:219], v[208:211], v[4:7]
	v_mfma_f32_16x16x32_bf16 v[0:3], v[224:227], v[208:211], v[0:3]
	s_setprio 0
	s_cmp_ge_i32 s31, s43
	s_mov_b64 s[16:17], s[18:19]
	s_mov_b32 s20, s31
	s_barrier
	s_cbranch_scc0 .LBB0_1581
	s_mov_b64 s[20:21], s[58:59]
	v_readlane_b32 s52, v255, 34
	v_readlane_b32 s53, v255, 35
	s_branch .LBB0_1572
